# GEMM K-loops: drop the duplicate s_waitcnt lgkmcnt(0) after s_setprio 1 (the one inside the asm block right before already drains LDS)
# baseline (speedup 1.0000x reference)
; #define PG8_LDA(dst, b, h) do { _Pragma("unroll") for (int m = 0; m < 4; ++m) _Pragma("unroll") for (int k = 0; k < 2; ++k) dst[m][k] = *(const LAS bf16x8*)(lds + PG8_SA(b, h) + aoff + m * 2048 + k * 1024); } while (0)
; #define PG8_LDB(dst, b, h) do { _Pragma("unroll") for (int n = 0; n < 2; ++n) _Pragma("unroll") for (int k = 0; k < 2; ++k) dst[n][k] = *(const LAS bf16x8*)(lds + PG8_SB(b, h) + boff + n * 2048 + k * 1024); } while (0)
; #define PG8_MMA(ai, bj, At, Bt_) do { __builtin_amdgcn_s_setprio(1); _Pragma("unroll") for (int m = 0; m < 4; ++m) _Pragma("unroll") for (int n = 0; n < 2; ++n) _Pragma("unroll") for (int k = 0; k < 2; ++k) \
;     acc[ai][bj][m][n] = __builtin_amdgcn_mfma_f32_16x16x32_bf16(Bt_[n][k], At[m][k], acc[ai][bj][m][n], 0, 0, 0); __builtin_amdgcn_s_setprio(0); } while (0)
; #define PG8_WAIT_V(n) asm volatile("s_waitcnt vmcnt(" #n ")" ::: "memory")
; #define PG8_WAIT_L(n) asm volatile("s_waitcnt lgkmcnt(" #n ")" ::: "memory")
; #define PG8_BAR __builtin_amdgcn_s_barrier()
; #define PG8_SCHED __builtin_amdgcn_sched_barrier(0)
; #define PG8_STA(bufoff, gbase, ld2) PG8_STAGE3(bufoff, gbase, ld2, R0, R1)
; #define PG8_STB(bufoff, gbase, ld2) PG8_STAGE3(bufoff, gbase, ld2, Rb0, Rb1)
; #define PG8_LDA(dst, b, h) do { _Pragma("unroll") for (int m = 0; m < 4; ++m) _Pragma("unroll") for (int k = 0; k < 2; ++k) dst[m][k] = *(const LAS bf16x8*)(lds + PG8_SA(b, h) + aoff + m * 2048 + k * 1024); } while (0)
; #define PG8_LDB(dst, b, h) do { _Pragma("unroll") for (int n = 0; n < 2; ++n) _Pragma("unroll") for (int k = 0; k < 2; ++k) dst[n][k] = *(const LAS bf16x8*)(lds + PG8_SB(b, h) + boff + n * 2048 + k * 1024); } while (0)
; #define PG8_WAIT_V(n) asm volatile("s_waitcnt vmcnt(" #n ")" ::: "memory")
; template <class Sched, class Epi>
; DI void gemm_stream(char* smem, const Sched& S_, const Epi& E) {
;     ...
;       PG8_LDB(B0, 0, 0); PG8_SCHED; PG8_LDA(At, 0, 0); PG8_STA(PG8_SA(1, 1), a1 + hA, la2);
;       PG8_WAIT_L(8); PG8_BAR; PG8_WAIT_L(0); PG8_MMA(0, 0, At, B0); PG8_BAR; PG8_SCHED;
;       PG8_LDB(B1, 0, 1); PG8_STB(PG8_SB(0, 0), b2, xb2);
;       PG8_BAR; PG8_WAIT_L(0); PG8_MMA(0, 1, At, B1); PG8_BAR;
;       PG8_LDA(At, 0, 1); PG8_STA(PG8_SA(0, 0), a2, xa2);
;       PG8_BAR; PG8_WAIT_L(0); PG8_MMA(1, 0, At, B0); PG8_BAR; PG8_SCHED;
;       PG8_STB(PG8_SB(0, 1), b2 + xhB, xb2);
;       PG8_WAIT_V(6); PG8_BAR; PG8_MMA(1, 1, At, B1); PG8_BAR;
.LBB0_466:
	s_add_u32 s46, s44, 0xfffc0080
	s_addc_u32 s47, s45, -1
	s_add_i32 s52, 0, 0x10000
	v_add_u32_e32 v138, s52, v141
	ds_read_b128 v[144:147], v138
	ds_read_b128 v[148:151], v138 offset:1024
	ds_read_b128 v[152:155], v138 offset:2048
	ds_read_b128 v[156:159], v138 offset:3072
	s_cmp_eq_u32 s49, 12
	s_cselect_b32 s51, s37, s47
	s_cselect_b32 s50, s36, s46
	s_cselect_b32 s47, s41, s27
	s_cselect_b32 s46, s40, s1
	v_lshl_add_u64 v[138:139], s[44:45], 0, v[134:135]
	s_add_i32 m0, s5, 0xc000
	ds_read_b128 v[160:163], v143
	ds_read_b128 v[164:167], v143 offset:1024
	ds_read_b128 v[168:171], v143 offset:2048
	ds_read_b128 v[172:175], v143 offset:3072
	ds_read_b128 v[176:179], v143 offset:4096
	ds_read_b128 v[180:183], v143 offset:5120
	ds_read_b128 v[184:187], v143 offset:6144
	ds_read_b128 v[188:191], v143 offset:7168
	global_load_lds_dwordx4 v[138:139], off
	v_lshl_add_u64 v[138:139], s[44:45], 0, v[136:137]
	s_add_i32 m0, s5, 0xe000
	s_nop 0
	global_load_lds_dwordx4 v[138:139], off
	s_waitcnt lgkmcnt(8)
	s_barrier
	s_waitcnt lgkmcnt(0)
	s_setprio 1
	v_mfma_f32_16x16x32_bf16 v[124:127], v[144:147], v[160:163], v[124:127]
	v_mfma_f32_16x16x32_bf16 v[120:123], v[152:155], v[160:163], v[120:123]
	v_mfma_f32_16x16x32_bf16 v[116:119], v[144:147], v[168:171], v[116:119]
	v_mfma_f32_16x16x32_bf16 v[112:115], v[152:155], v[168:171], v[112:115]
	v_mfma_f32_16x16x32_bf16 v[108:111], v[144:147], v[176:179], v[108:111]
	v_mfma_f32_16x16x32_bf16 v[100:103], v[152:155], v[176:179], v[100:103]
	v_mfma_f32_16x16x32_bf16 v[92:95], v[144:147], v[184:187], v[92:95]
	v_mfma_f32_16x16x32_bf16 v[84:87], v[152:155], v[184:187], v[84:87]
	v_mfma_f32_16x16x32_bf16 v[124:127], v[148:151], v[164:167], v[124:127]
	v_mfma_f32_16x16x32_bf16 v[120:123], v[156:159], v[164:167], v[120:123]
	v_mfma_f32_16x16x32_bf16 v[116:119], v[148:151], v[172:175], v[116:119]
	v_mfma_f32_16x16x32_bf16 v[112:115], v[156:159], v[172:175], v[112:115]
	v_mfma_f32_16x16x32_bf16 v[108:111], v[148:151], v[180:183], v[108:111]
	v_mfma_f32_16x16x32_bf16 v[100:103], v[156:159], v[180:183], v[100:103]
	v_mfma_f32_16x16x32_bf16 v[92:95], v[148:151], v[188:191], v[92:95]
	v_mfma_f32_16x16x32_bf16 v[84:87], v[156:159], v[188:191], v[84:87]
	s_setprio 0
	s_barrier
	s_add_i32 s56, 0, 0x14000
	v_add_u32_e32 v138, s56, v141
	s_add_i32 s52, s52, s4
	ds_read_b128 v[210:213], v138
	ds_read_b128 v[214:217], v138 offset:1024
	ds_read_b128 v[234:237], v138 offset:2048
	ds_read_b128 v[238:241], v138 offset:3072
	v_lshl_add_u64 v[138:139], s[46:47], 0, v[220:221]
	s_mov_b32 m0, s52
	v_lshl_add_u64 v[218:219], s[46:47], 0, v[128:129]
	global_load_lds_dwordx4 v[138:139], off
	s_add_i32 m0, s52, 0x2000
	s_nop 0
	global_load_lds_dwordx4 v[218:219], off
	s_barrier
	s_waitcnt lgkmcnt(0)
	s_setprio 1
	v_mfma_f32_16x16x32_bf16 v[104:107], v[210:213], v[160:163], v[104:107]
	v_mfma_f32_16x16x32_bf16 v[96:99], v[234:237], v[160:163], v[96:99]
	v_mfma_f32_16x16x32_bf16 v[88:91], v[210:213], v[168:171], v[88:91]
	v_mfma_f32_16x16x32_bf16 v[80:83], v[234:237], v[168:171], v[80:83]
	v_mfma_f32_16x16x32_bf16 v[76:79], v[210:213], v[176:179], v[76:79]
	v_mfma_f32_16x16x32_bf16 v[72:75], v[234:237], v[176:179], v[72:75]
	v_mfma_f32_16x16x32_bf16 v[68:71], v[210:213], v[184:187], v[68:71]
	v_mfma_f32_16x16x32_bf16 v[64:67], v[234:237], v[184:187], v[64:67]
	v_mfma_f32_16x16x32_bf16 v[104:107], v[214:217], v[164:167], v[104:107]
	v_mfma_f32_16x16x32_bf16 v[96:99], v[238:241], v[164:167], v[96:99]
	v_mfma_f32_16x16x32_bf16 v[88:91], v[214:217], v[172:175], v[88:91]
	v_mfma_f32_16x16x32_bf16 v[80:83], v[238:241], v[172:175], v[80:83]
	v_mfma_f32_16x16x32_bf16 v[76:79], v[214:217], v[180:183], v[76:79]
	v_mfma_f32_16x16x32_bf16 v[72:75], v[238:241], v[180:183], v[72:75]
	v_mfma_f32_16x16x32_bf16 v[68:71], v[214:217], v[188:191], v[68:71]
	v_mfma_f32_16x16x32_bf16 v[64:67], v[238:241], v[188:191], v[64:67]
	s_setprio 0
	s_mov_b32 m0, s5
	v_lshl_add_u64 v[242:243], s[50:51], 0, v[130:131]
	s_barrier
	ds_read_b128 v[160:163], v143 offset:16384
	ds_read_b128 v[164:167], v143 offset:17408
	ds_read_b128 v[168:171], v143 offset:18432
	ds_read_b128 v[172:175], v143 offset:19456
	ds_read_b128 v[176:179], v143 offset:20480
	ds_read_b128 v[180:183], v143 offset:21504
	ds_read_b128 v[184:187], v143 offset:22528
	ds_read_b128 v[188:191], v143 offset:23552
	global_load_lds_dwordx4 v[242:243], off
	v_lshl_add_u64 v[244:245], s[50:51], 0, v[132:133]
	s_mov_b32 m0, s9
	s_nop 0
	global_load_lds_dwordx4 v[244:245], off
	s_barrier
	s_waitcnt lgkmcnt(0)
	s_setprio 1
	v_mfma_f32_16x16x32_bf16 v[60:63], v[144:147], v[160:163], v[60:63]
	v_mfma_f32_16x16x32_bf16 v[56:59], v[152:155], v[160:163], v[56:59]
	v_mfma_f32_16x16x32_bf16 v[52:55], v[144:147], v[168:171], v[52:55]
	v_mfma_f32_16x16x32_bf16 v[48:51], v[152:155], v[168:171], v[48:51]
	v_mfma_f32_16x16x32_bf16 v[44:47], v[144:147], v[176:179], v[44:47]
	v_mfma_f32_16x16x32_bf16 v[36:39], v[152:155], v[176:179], v[36:39]
	v_mfma_f32_16x16x32_bf16 v[28:31], v[144:147], v[184:187], v[28:31]
	v_mfma_f32_16x16x32_bf16 v[20:23], v[152:155], v[184:187], v[20:23]
	v_mfma_f32_16x16x32_bf16 v[60:63], v[148:151], v[164:167], v[60:63]
	v_mfma_f32_16x16x32_bf16 v[56:59], v[156:159], v[164:167], v[56:59]
	v_mfma_f32_16x16x32_bf16 v[52:55], v[148:151], v[172:175], v[52:55]
	v_mfma_f32_16x16x32_bf16 v[48:51], v[156:159], v[172:175], v[48:51]
	v_mfma_f32_16x16x32_bf16 v[44:47], v[148:151], v[180:183], v[44:47]
	v_mfma_f32_16x16x32_bf16 v[36:39], v[156:159], v[180:183], v[36:39]
	v_mfma_f32_16x16x32_bf16 v[28:31], v[148:151], v[188:191], v[28:31]
	v_mfma_f32_16x16x32_bf16 v[20:23], v[156:159], v[188:191], v[20:23]
	s_setprio 0
	s_barrier
; #define PG8_LDA(dst, b, h) do { _Pragma("unroll") for (int m = 0; m < 4; ++m) _Pragma("unroll") for (int k = 0; k < 2; ++k) dst[m][k] = *(const LAS bf16x8*)(lds + PG8_SA(b, h) + aoff + m * 2048 + k * 1024); } while (0)
; #define PG8_LDB(dst, b, h) do { _Pragma("unroll") for (int n = 0; n < 2; ++n) _Pragma("unroll") for (int k = 0; k < 2; ++k) dst[n][k] = *(const LAS bf16x8*)(lds + PG8_SB(b, h) + boff + n * 2048 + k * 1024); } while (0)
; #define PG8_MMA(ai, bj, At, Bt_) do { __builtin_amdgcn_s_setprio(1); _Pragma("unroll") for (int m = 0; m < 4; ++m) _Pragma("unroll") for (int n = 0; n < 2; ++n) _Pragma("unroll") for (int k = 0; k < 2; ++k) \
;     acc[ai][bj][m][n] = __builtin_amdgcn_mfma_f32_16x16x32_bf16(Bt_[n][k], At[m][k], acc[ai][bj][m][n], 0, 0, 0); __builtin_amdgcn_s_setprio(0); } while (0)
; #define PG8_WAIT_V(n) asm volatile("s_waitcnt vmcnt(" #n ")" ::: "memory")
; #define PG8_WAIT_L(n) asm volatile("s_waitcnt lgkmcnt(" #n ")" ::: "memory")
; #define PG8_BAR __builtin_amdgcn_s_barrier()
; #define PG8_SCHED __builtin_amdgcn_sched_barrier(0)
; #define PG8_STA(bufoff, gbase, ld2) PG8_STAGE3(bufoff, gbase, ld2, R0, R1)
; #define PG8_STB(bufoff, gbase, ld2) PG8_STAGE3(bufoff, gbase, ld2, Rb0, Rb1)
; #define PG8_LDA(dst, b, h) do { _Pragma("unroll") for (int m = 0; m < 4; ++m) _Pragma("unroll") for (int k = 0; k < 2; ++k) dst[m][k] = *(const LAS bf16x8*)(lds + PG8_SA(b, h) + aoff + m * 2048 + k * 1024); } while (0)
; #define PG8_LDB(dst, b, h) do { _Pragma("unroll") for (int n = 0; n < 2; ++n) _Pragma("unroll") for (int k = 0; k < 2; ++k) dst[n][k] = *(const LAS bf16x8*)(lds + PG8_SB(b, h) + boff + n * 2048 + k * 1024); } while (0)
; #define PG8_WAIT_V(n) asm volatile("s_waitcnt vmcnt(" #n ")" ::: "memory")
; #define PG8_BAR __builtin_amdgcn_s_barrier()
; template <class Sched, class Epi>
; DI void gemm_stream(char* smem, const Sched& S_, const Epi& E) {
;     ...
;       PG8_STB(PG8_SB(0, 1), b2 + xhB, xb2);
;       PG8_WAIT_V(6); PG8_BAR; PG8_MMA(1, 1, At, B1); PG8_BAR;
;       PG8_LDB(B0, 1, 0); PG8_SCHED; PG8_LDA(At, 1, 0); PG8_STA(PG8_SA(0, 1), a2 + xhA, xa2);
;       PG8_WAIT_L(8); PG8_BAR; PG8_WAIT_L(0); PG8_MMA(0, 0, At, B0); PG8_BAR; PG8_SCHED;
;       PG8_LDB(B1, 1, 1); PG8_STB(PG8_SB(1, 0), b3, xb2);
;       PG8_BAR; PG8_WAIT_L(0); PG8_MMA(0, 1, At, B1); PG8_BAR;
;       PG8_LDA(At, 1, 1); PG8_STA(PG8_SA(1, 0), a3, xa2);
	s_add_u32 s52, s46, 0x40000
	s_addc_u32 s53, s47, 0
	s_add_i32 s56, s56, s4
	v_lshl_add_u64 v[144:145], s[52:53], 0, v[220:221]
	s_mov_b32 m0, s56
	s_nop 0
	global_load_lds_dwordx4 v[144:145], off
	v_lshl_add_u64 v[144:145], s[52:53], 0, v[128:129]
	s_add_i32 m0, s56, 0x2000
	s_nop 0
	global_load_lds_dwordx4 v[144:145], off
	s_waitcnt vmcnt(6)
	s_barrier
	s_setprio 1
	v_mfma_f32_16x16x32_bf16 v[40:43], v[210:213], v[160:163], v[40:43]
	v_mfma_f32_16x16x32_bf16 v[32:35], v[234:237], v[160:163], v[32:35]
	v_mfma_f32_16x16x32_bf16 v[24:27], v[210:213], v[168:171], v[24:27]
	v_mfma_f32_16x16x32_bf16 v[16:19], v[234:237], v[168:171], v[16:19]
	v_mfma_f32_16x16x32_bf16 v[12:15], v[210:213], v[176:179], v[12:15]
	v_mfma_f32_16x16x32_bf16 v[8:11], v[234:237], v[176:179], v[8:11]
	v_mfma_f32_16x16x32_bf16 v[4:7], v[210:213], v[184:187], v[4:7]
	v_mfma_f32_16x16x32_bf16 v[0:3], v[234:237], v[184:187], v[0:3]
	v_mfma_f32_16x16x32_bf16 v[40:43], v[214:217], v[164:167], v[40:43]
	v_mfma_f32_16x16x32_bf16 v[32:35], v[238:241], v[164:167], v[32:35]
	v_mfma_f32_16x16x32_bf16 v[24:27], v[214:217], v[172:175], v[24:27]
	v_mfma_f32_16x16x32_bf16 v[16:19], v[238:241], v[172:175], v[16:19]
	v_mfma_f32_16x16x32_bf16 v[12:15], v[214:217], v[180:183], v[12:15]
	v_mfma_f32_16x16x32_bf16 v[8:11], v[238:241], v[180:183], v[8:11]
	v_mfma_f32_16x16x32_bf16 v[4:7], v[214:217], v[188:191], v[4:7]
	v_mfma_f32_16x16x32_bf16 v[0:3], v[238:241], v[188:191], v[0:3]
	s_setprio 0
	s_add_i32 s52, 0, 0x18000
	v_add_u32_e32 v156, s52, v141
	s_barrier
	ds_read_b128 v[144:147], v156
	ds_read_b128 v[148:151], v156 offset:1024
	ds_read_b128 v[152:155], v156 offset:2048
	ds_read_b128 v[156:159], v156 offset:3072
	s_add_u32 s50, s50, 0x40000
	s_addc_u32 s51, s51, 0
	s_mov_b32 m0, s13
	v_lshl_add_u64 v[210:211], s[50:51], 0, v[130:131]
	ds_read_b128 v[160:163], v143 offset:32768
	ds_read_b128 v[164:167], v143 offset:33792
	ds_read_b128 v[168:171], v143 offset:34816
	ds_read_b128 v[172:175], v143 offset:35840
	ds_read_b128 v[176:179], v143 offset:36864
	ds_read_b128 v[180:183], v143 offset:37888
	ds_read_b128 v[184:187], v143 offset:38912
	ds_read_b128 v[188:191], v143 offset:39936
	global_load_lds_dwordx4 v[210:211], off
	v_lshl_add_u64 v[210:211], s[50:51], 0, v[132:133]
	s_mov_b32 m0, s15
	s_nop 0
	global_load_lds_dwordx4 v[210:211], off
	s_waitcnt lgkmcnt(8)
	s_barrier
	s_waitcnt lgkmcnt(0)
	s_setprio 1
	v_mfma_f32_16x16x32_bf16 v[124:127], v[144:147], v[160:163], v[124:127]
	v_mfma_f32_16x16x32_bf16 v[120:123], v[152:155], v[160:163], v[120:123]
	v_mfma_f32_16x16x32_bf16 v[116:119], v[144:147], v[168:171], v[116:119]
	v_mfma_f32_16x16x32_bf16 v[112:115], v[152:155], v[168:171], v[112:115]
	v_mfma_f32_16x16x32_bf16 v[108:111], v[144:147], v[176:179], v[108:111]
	v_mfma_f32_16x16x32_bf16 v[100:103], v[152:155], v[176:179], v[100:103]
	v_mfma_f32_16x16x32_bf16 v[92:95], v[144:147], v[184:187], v[92:95]
	v_mfma_f32_16x16x32_bf16 v[84:87], v[152:155], v[184:187], v[84:87]
	v_mfma_f32_16x16x32_bf16 v[124:127], v[148:151], v[164:167], v[124:127]
	v_mfma_f32_16x16x32_bf16 v[120:123], v[156:159], v[164:167], v[120:123]
	v_mfma_f32_16x16x32_bf16 v[116:119], v[148:151], v[172:175], v[116:119]
	v_mfma_f32_16x16x32_bf16 v[112:115], v[156:159], v[172:175], v[112:115]
	v_mfma_f32_16x16x32_bf16 v[108:111], v[148:151], v[180:183], v[108:111]
	v_mfma_f32_16x16x32_bf16 v[100:103], v[156:159], v[180:183], v[100:103]
	v_mfma_f32_16x16x32_bf16 v[92:95], v[148:151], v[188:191], v[92:95]
	v_mfma_f32_16x16x32_bf16 v[84:87], v[156:159], v[188:191], v[84:87]
	s_setprio 0
	s_barrier
	s_add_i32 s50, 0, 0x1c000
	s_add_i32 s51, s52, s4
	v_add_u32_e32 v194, s50, v141
	v_lshl_add_u64 v[138:139], v[138:139], 0, s[58:59]
	s_mov_b32 m0, s51
	ds_read_b128 v[210:213], v194
	ds_read_b128 v[214:217], v194 offset:1024
	ds_read_b128 v[234:237], v194 offset:2048
	ds_read_b128 v[238:241], v194 offset:3072
	global_load_lds_dwordx4 v[138:139], off
	v_lshl_add_u64 v[138:139], v[218:219], 0, s[58:59]
	s_add_i32 m0, s51, 0x2000
	s_nop 0
	global_load_lds_dwordx4 v[138:139], off
	s_barrier
	s_waitcnt lgkmcnt(0)
	s_setprio 1
	v_mfma_f32_16x16x32_bf16 v[104:107], v[210:213], v[160:163], v[104:107]
	v_mfma_f32_16x16x32_bf16 v[96:99], v[234:237], v[160:163], v[96:99]
	v_mfma_f32_16x16x32_bf16 v[88:91], v[210:213], v[168:171], v[88:91]
	v_mfma_f32_16x16x32_bf16 v[80:83], v[234:237], v[168:171], v[80:83]
	v_mfma_f32_16x16x32_bf16 v[76:79], v[210:213], v[176:179], v[76:79]
	v_mfma_f32_16x16x32_bf16 v[72:75], v[234:237], v[176:179], v[72:75]
	v_mfma_f32_16x16x32_bf16 v[68:71], v[210:213], v[184:187], v[68:71]
	v_mfma_f32_16x16x32_bf16 v[64:67], v[234:237], v[184:187], v[64:67]
	v_mfma_f32_16x16x32_bf16 v[104:107], v[214:217], v[164:167], v[104:107]
	v_mfma_f32_16x16x32_bf16 v[96:99], v[238:241], v[164:167], v[96:99]
	v_mfma_f32_16x16x32_bf16 v[88:91], v[214:217], v[172:175], v[88:91]
	v_mfma_f32_16x16x32_bf16 v[80:83], v[238:241], v[172:175], v[80:83]
	v_mfma_f32_16x16x32_bf16 v[76:79], v[214:217], v[180:183], v[76:79]
	v_mfma_f32_16x16x32_bf16 v[72:75], v[238:241], v[180:183], v[72:75]
	v_mfma_f32_16x16x32_bf16 v[68:71], v[214:217], v[188:191], v[68:71]
	v_mfma_f32_16x16x32_bf16 v[64:67], v[238:241], v[188:191], v[64:67]
	s_setprio 0
	s_mov_b32 m0, s16
	v_lshl_add_u64 v[138:139], v[242:243], 0, s[58:59]
	s_barrier
	ds_read_b128 v[160:163], v143 offset:49152
	ds_read_b128 v[164:167], v143 offset:50176
	ds_read_b128 v[168:171], v143 offset:51200
	ds_read_b128 v[172:175], v143 offset:52224
	ds_read_b128 v[176:179], v143 offset:53248
	ds_read_b128 v[180:183], v143 offset:54272
	ds_read_b128 v[184:187], v143 offset:55296
	ds_read_b128 v[188:191], v143 offset:56320
	global_load_lds_dwordx4 v[138:139], off
	v_lshl_add_u64 v[138:139], v[244:245], 0, s[58:59]
	s_mov_b32 m0, s20
	s_nop 0
	global_load_lds_dwordx4 v[138:139], off
	s_barrier
; #define PG8_LDA(dst, b, h) do { _Pragma("unroll") for (int m = 0; m < 4; ++m) _Pragma("unroll") for (int k = 0; k < 2; ++k) dst[m][k] = *(const LAS bf16x8*)(lds + PG8_SA(b, h) + aoff + m * 2048 + k * 1024); } while (0)
; #define PG8_MMA(ai, bj, At, Bt_) do { __builtin_amdgcn_s_setprio(1); _Pragma("unroll") for (int m = 0; m < 4; ++m) _Pragma("unroll") for (int n = 0; n < 2; ++n) _Pragma("unroll") for (int k = 0; k < 2; ++k) \
;     acc[ai][bj][m][n] = __builtin_amdgcn_mfma_f32_16x16x32_bf16(Bt_[n][k], At[m][k], acc[ai][bj][m][n], 0, 0, 0); __builtin_amdgcn_s_setprio(0); } while (0)
; #define PG8_WAIT_V(n) asm volatile("s_waitcnt vmcnt(" #n ")" ::: "memory")
; #define PG8_WAIT_L(n) asm volatile("s_waitcnt lgkmcnt(" #n ")" ::: "memory")
; #define PG8_BAR __builtin_amdgcn_s_barrier()
; #define PG8_SCHED __builtin_amdgcn_sched_barrier(0)
; #define PG8_STA(bufoff, gbase, ld2) PG8_STAGE3(bufoff, gbase, ld2, R0, R1)
; #define PG8_STB(bufoff, gbase, ld2) PG8_STAGE3(bufoff, gbase, ld2, Rb0, Rb1)
; #define PG8_LDA(dst, b, h) do { _Pragma("unroll") for (int m = 0; m < 4; ++m) _Pragma("unroll") for (int k = 0; k < 2; ++k) dst[m][k] = *(const LAS bf16x8*)(lds + PG8_SA(b, h) + aoff + m * 2048 + k * 1024); } while (0)
; #define PG8_MMA(ai, bj, At, Bt_) do { __builtin_amdgcn_s_setprio(1); _Pragma("unroll") for (int m = 0; m < 4; ++m) _Pragma("unroll") for (int n = 0; n < 2; ++n) _Pragma("unroll") for (int k = 0; k < 2; ++k) \
;     acc[ai][bj][m][n] = __builtin_amdgcn_mfma_f32_16x16x32_bf16(Bt_[n][k], At[m][k], acc[ai][bj][m][n], 0, 0, 0); __builtin_amdgcn_s_setprio(0); } while (0)
; #define PG8_WAIT_V(n) asm volatile("s_waitcnt vmcnt(" #n ")" ::: "memory")
; #define PG8_WAIT_L(n) asm volatile("s_waitcnt lgkmcnt(" #n ")" ::: "memory")
; #define PG8_BAR __builtin_amdgcn_s_barrier()
; #define PG8_SCHED __builtin_amdgcn_sched_barrier(0)
; template <class Sched, class Epi>
; DI void gemm_stream(char* smem, const Sched& S_, const Epi& E) {
;     ...
;       PG8_LDA(At, 1, 1); PG8_STA(PG8_SA(1, 0), a3, xa2);
;       PG8_BAR; PG8_WAIT_L(0); PG8_MMA(1, 0, At, B0); PG8_BAR; PG8_SCHED;
;       PG8_STB(PG8_SB(1, 1), b3 + xhB, xb2);
;       PG8_WAIT_V(6); PG8_BAR; PG8_MMA(1, 1, At, B1); PG8_BAR;
;     }
	s_waitcnt lgkmcnt(0)
	s_setprio 1
	v_mfma_f32_16x16x32_bf16 v[60:63], v[144:147], v[160:163], v[60:63]
	v_mfma_f32_16x16x32_bf16 v[56:59], v[152:155], v[160:163], v[56:59]
	v_mfma_f32_16x16x32_bf16 v[52:55], v[144:147], v[168:171], v[52:55]
	v_mfma_f32_16x16x32_bf16 v[48:51], v[152:155], v[168:171], v[48:51]
	v_mfma_f32_16x16x32_bf16 v[44:47], v[144:147], v[176:179], v[44:47]
	v_mfma_f32_16x16x32_bf16 v[36:39], v[152:155], v[176:179], v[36:39]
	v_mfma_f32_16x16x32_bf16 v[28:31], v[144:147], v[184:187], v[28:31]
	v_mfma_f32_16x16x32_bf16 v[20:23], v[152:155], v[184:187], v[20:23]
	v_mfma_f32_16x16x32_bf16 v[60:63], v[148:151], v[164:167], v[60:63]
	v_mfma_f32_16x16x32_bf16 v[56:59], v[156:159], v[164:167], v[56:59]
	v_mfma_f32_16x16x32_bf16 v[52:55], v[148:151], v[172:175], v[52:55]
	v_mfma_f32_16x16x32_bf16 v[48:51], v[156:159], v[172:175], v[48:51]
	v_mfma_f32_16x16x32_bf16 v[44:47], v[148:151], v[180:183], v[44:47]
	v_mfma_f32_16x16x32_bf16 v[36:39], v[156:159], v[180:183], v[36:39]
	v_mfma_f32_16x16x32_bf16 v[28:31], v[148:151], v[188:191], v[28:31]
	v_mfma_f32_16x16x32_bf16 v[20:23], v[156:159], v[188:191], v[20:23]
	s_setprio 0
	s_barrier
	s_add_u32 s46, s46, 0x40080
	s_addc_u32 s47, s47, 0
	s_add_i32 s50, s50, s4
	v_lshl_add_u64 v[138:139], s[46:47], 0, v[220:221]
	s_mov_b32 m0, s50
	s_nop 0
	global_load_lds_dwordx4 v[138:139], off
	v_lshl_add_u64 v[138:139], s[46:47], 0, v[128:129]
	s_add_i32 m0, s50, 0x2000
	s_nop 0
	global_load_lds_dwordx4 v[138:139], off
	s_waitcnt vmcnt(6)
	s_barrier
	s_setprio 1
	v_mfma_f32_16x16x32_bf16 v[40:43], v[210:213], v[160:163], v[40:43]
	v_mfma_f32_16x16x32_bf16 v[32:35], v[234:237], v[160:163], v[32:35]
	v_mfma_f32_16x16x32_bf16 v[24:27], v[210:213], v[168:171], v[24:27]
	v_mfma_f32_16x16x32_bf16 v[16:19], v[234:237], v[168:171], v[16:19]
	v_mfma_f32_16x16x32_bf16 v[12:15], v[210:213], v[176:179], v[12:15]
	v_mfma_f32_16x16x32_bf16 v[8:11], v[234:237], v[176:179], v[8:11]
	v_mfma_f32_16x16x32_bf16 v[4:7], v[210:213], v[184:187], v[4:7]
	v_mfma_f32_16x16x32_bf16 v[0:3], v[234:237], v[184:187], v[0:3]
	v_mfma_f32_16x16x32_bf16 v[40:43], v[214:217], v[164:167], v[40:43]
	v_mfma_f32_16x16x32_bf16 v[32:35], v[238:241], v[164:167], v[32:35]
	v_mfma_f32_16x16x32_bf16 v[24:27], v[214:217], v[172:175], v[24:27]
	v_mfma_f32_16x16x32_bf16 v[16:19], v[238:241], v[172:175], v[16:19]
	v_mfma_f32_16x16x32_bf16 v[12:15], v[214:217], v[180:183], v[12:15]
	v_mfma_f32_16x16x32_bf16 v[8:11], v[238:241], v[180:183], v[8:11]
	v_mfma_f32_16x16x32_bf16 v[4:7], v[214:217], v[188:191], v[4:7]
	v_mfma_f32_16x16x32_bf16 v[0:3], v[238:241], v[188:191], v[0:3]
	s_setprio 0
	s_add_i32 s49, s49, 2
	s_add_u32 s44, s44, 0x100
	s_addc_u32 s45, s45, 0
	s_add_u32 s1, s1, 0x100
	s_addc_u32 s27, s27, 0
	s_cmp_gt_u32 s49, 13
	s_barrier
	s_cbranch_scc0 .LBB0_466
; DI u32x4 pack8v(const f32x4& a, const f32x4& b) { u32x4 w; w.x = pk2(a[0], a[1]); w.y = pk2(a[2], a[3]); w.z = pk2(b[0], b[1]); w.w = pk2(b[2], b[3]); return w; }
;   DI void operator()(const acc_t& acc, const Desc& u, int wr, int wc, int fr, int fq) const {
;     ...
;       const int t0 = u.pn * BM, b = t0 / S, s0 = t0 - b * S + wc * 32 + 8 * fq;
; #pragma unroll
;       for (int ai = 0; ai < 2; ++ai)
; #pragma unroll
;         for (int m = 0; m < 4; ++m) { bf16_t* rowp = RVT + ((size_t)b * 512 + row0 + ai * HALF + m * 16) * S + s0;
; #pragma unroll
;           for (int bj = 0; bj < 2; ++bj) *(u32x4*)(rowp + bj * HALF) = pack8v(acc[ai][bj][m][0], acc[ai][bj][m][1]); }
	s_lshl_b32 s1, s33, 8
	v_lshl_add_u32 v138, s43, 8, v140
	s_cmp_lg_u32 s42, 0
	v_cvt_pk_bf16_f32 v124, v124, v125
	v_cvt_pk_bf16_f32 v125, v126, v127
	v_cvt_pk_bf16_f32 v126, v120, v121
	v_cvt_pk_bf16_f32 v127, v122, v123
	v_cvt_pk_bf16_f32 v104, v104, v105
	v_cvt_pk_bf16_f32 v105, v106, v107
	v_cvt_pk_bf16_f32 v106, v96, v97
	v_cvt_pk_bf16_f32 v107, v98, v99
	v_cvt_pk_bf16_f32 v96, v116, v117
	v_cvt_pk_bf16_f32 v97, v118, v119
	v_cvt_pk_bf16_f32 v98, v112, v113
	v_cvt_pk_bf16_f32 v99, v114, v115
	v_cvt_pk_bf16_f32 v88, v88, v89
	v_cvt_pk_bf16_f32 v89, v90, v91
	v_cvt_pk_bf16_f32 v90, v80, v81
	v_cvt_pk_bf16_f32 v91, v82, v83
	v_cvt_pk_bf16_f32 v80, v108, v109
	v_cvt_pk_bf16_f32 v81, v110, v111
	v_cvt_pk_bf16_f32 v82, v100, v101
	v_cvt_pk_bf16_f32 v83, v102, v103
	v_cvt_pk_bf16_f32 v76, v76, v77
	v_cvt_pk_bf16_f32 v77, v78, v79
	v_cvt_pk_bf16_f32 v78, v72, v73
	v_cvt_pk_bf16_f32 v79, v74, v75
	v_cvt_pk_bf16_f32 v72, v92, v93
	v_cvt_pk_bf16_f32 v73, v94, v95
	v_cvt_pk_bf16_f32 v74, v84, v85
	v_cvt_pk_bf16_f32 v75, v86, v87
	v_cvt_pk_bf16_f32 v68, v68, v69
	v_cvt_pk_bf16_f32 v69, v70, v71
	v_cvt_pk_bf16_f32 v70, v64, v65
	v_cvt_pk_bf16_f32 v71, v66, v67
	v_cvt_pk_bf16_f32 v60, v60, v61
	v_cvt_pk_bf16_f32 v61, v62, v63
	v_cvt_pk_bf16_f32 v62, v56, v57
	v_cvt_pk_bf16_f32 v63, v58, v59
	v_cvt_pk_bf16_f32 v40, v40, v41
	v_cvt_pk_bf16_f32 v41, v42, v43
	v_cvt_pk_bf16_f32 v42, v32, v33
	v_cvt_pk_bf16_f32 v43, v34, v35
	v_cvt_pk_bf16_f32 v32, v52, v53
	v_cvt_pk_bf16_f32 v33, v54, v55
	v_cvt_pk_bf16_f32 v34, v48, v49
	v_cvt_pk_bf16_f32 v35, v50, v51
	v_cvt_pk_bf16_f32 v24, v24, v25
	v_cvt_pk_bf16_f32 v25, v26, v27
	v_cvt_pk_bf16_f32 v26, v16, v17
	v_cvt_pk_bf16_f32 v27, v18, v19
	v_cvt_pk_bf16_f32 v16, v44, v45
	v_cvt_pk_bf16_f32 v17, v46, v47
	v_cvt_pk_bf16_f32 v18, v36, v37
	v_cvt_pk_bf16_f32 v19, v38, v39
	v_cvt_pk_bf16_f32 v12, v12, v13
	v_cvt_pk_bf16_f32 v13, v14, v15
	v_cvt_pk_bf16_f32 v14, v8, v9
	v_cvt_pk_bf16_f32 v15, v10, v11
	v_cvt_pk_bf16_f32 v8, v28, v29
	v_cvt_pk_bf16_f32 v9, v30, v31
	v_cvt_pk_bf16_f32 v10, v20, v21
	v_cvt_pk_bf16_f32 v11, v22, v23
	v_readlane_b32 s49, v254, 50
	s_cbranch_scc0 .LBB0_469
	s_mul_hi_i32 s27, s33, 0x78787879
	s_lshr_b32 s33, s27, 31
	s_ashr_i32 s27, s27, 3
	s_add_i32 s42, s27, s33
	s_ashr_i32 s43, s42, 31
	s_mul_i32 s27, s42, 0xffffef00
	s_lshl_b64 s[42:43], s[42:43], 9
	v_ashrrev_i32_e32 v139, 31, v138
	v_lshl_add_u64 v[22:23], s[42:43], 0, v[138:139]
	v_readlane_b32 s42, v251, 41
	s_add_i32 s27, s27, s1
	v_readlane_b32 s43, v251, 42
	v_or_b32_e32 v20, s27, v142
	s_movk_i32 s27, 0x2200
	v_mov_b64_e32 v[28:29], s[42:43]
	v_mad_u64_u32 v[28:29], s[42:43], v22, s27, v[28:29]
	v_ashrrev_i32_e32 v21, 31, v20
	v_mad_i32_i24 v29, v23, s27, v29
	v_lshl_add_u64 v[22:23], v[20:21], 1, v[28:29]
	s_mov_b32 s27, 0x22000
	v_add_co_u32_e32 v28, vcc, s27, v22
	s_mov_b64 s[42:43], 0x22000
	s_nop 0
	v_addc_co_u32_e32 v29, vcc, 0, v23, vcc
	s_mov_b32 s27, 0x44000
	global_store_dwordx4 v[22:23], v[124:127], off
	global_store_dwordx4 v[22:23], v[104:107], off offset:256
	v_lshl_add_u64 v[20:21], v[22:23], 0, s[42:43]
	global_store_dwordx4 v[28:29], v[96:99], off
	global_store_dwordx4 v[20:21], v[88:91], off offset:256
	v_add_co_u32_e32 v28, vcc, s27, v22
	s_mov_b64 s[42:43], 0x44000
	s_nop 0
	v_addc_co_u32_e32 v29, vcc, 0, v23, vcc
	s_mov_b32 s27, 0x66000
	v_lshl_add_u64 v[20:21], v[22:23], 0, s[42:43]
	global_store_dwordx4 v[28:29], v[80:83], off
	global_store_dwordx4 v[20:21], v[76:79], off offset:256
	v_add_co_u32_e32 v28, vcc, s27, v22
	s_mov_b64 s[42:43], 0x66000
	s_nop 0
	v_addc_co_u32_e32 v29, vcc, 0, v23, vcc
	s_mov_b32 s27, 0x110000
	v_lshl_add_u64 v[20:21], v[22:23], 0, s[42:43]
	global_store_dwordx4 v[28:29], v[72:75], off
	global_store_dwordx4 v[20:21], v[68:71], off offset:256
	v_add_co_u32_e32 v28, vcc, s27, v22
	s_mov_b64 s[42:43], 0x110000
	s_nop 0
	v_addc_co_u32_e32 v29, vcc, 0, v23, vcc
	s_mov_b32 s27, 0x132000
	v_lshl_add_u64 v[20:21], v[22:23], 0, s[42:43]
	global_store_dwordx4 v[28:29], v[60:63], off
	global_store_dwordx4 v[20:21], v[40:43], off offset:256
	v_add_co_u32_e32 v28, vcc, s27, v22
	s_mov_b64 s[42:43], 0x132000
	s_nop 0
	v_addc_co_u32_e32 v29, vcc, 0, v23, vcc
	s_mov_b32 s27, 0x154000
	v_lshl_add_u64 v[20:21], v[22:23], 0, s[42:43]
	global_store_dwordx4 v[28:29], v[32:35], off
	global_store_dwordx4 v[20:21], v[24:27], off offset:256
	s_mov_b64 s[42:43], 0x154000
	v_add_co_u32_e32 v28, vcc, s27, v22
	v_lshl_add_u64 v[20:21], v[22:23], 0, s[42:43]
	s_nop 0
	v_addc_co_u32_e32 v29, vcc, 0, v23, vcc
	s_mov_b64 s[42:43], 0x176000
	global_store_dwordx4 v[28:29], v[16:19], off
	global_store_dwordx4 v[20:21], v[12:15], off offset:256
	v_lshl_add_u64 v[20:21], v[22:23], 0, s[42:43]
	v_add_co_u32_e32 v22, vcc, 0x176000, v22
	s_nop 1
	v_addc_co_u32_e32 v23, vcc, 0, v23, vcc
	global_store_dwordx4 v[22:23], v[8:11], off
	s_movk_i32 s50, 0x100
	s_mov_b32 s51, 0x78787879
	s_cbranch_execnz .LBB0_456
	s_branch .LBB0_470

; #define PG8_LDA(dst, b, h) do { _Pragma("unroll") for (int m = 0; m < 4; ++m) _Pragma("unroll") for (int k = 0; k < 2; ++k) dst[m][k] = *(const LAS bf16x8*)(lds + PG8_SA(b, h) + aoff + m * 2048 + k * 1024); } while (0)
; #define PG8_LDB(dst, b, h) do { _Pragma("unroll") for (int n = 0; n < 2; ++n) _Pragma("unroll") for (int k = 0; k < 2; ++k) dst[n][k] = *(const LAS bf16x8*)(lds + PG8_SB(b, h) + boff + n * 2048 + k * 1024); } while (0)
; #define PG8_MMA(ai, bj, At, Bt_) do { __builtin_amdgcn_s_setprio(1); _Pragma("unroll") for (int m = 0; m < 4; ++m) _Pragma("unroll") for (int n = 0; n < 2; ++n) _Pragma("unroll") for (int k = 0; k < 2; ++k) \
;     acc[ai][bj][m][n] = __builtin_amdgcn_mfma_f32_16x16x32_bf16(Bt_[n][k], At[m][k], acc[ai][bj][m][n], 0, 0, 0); __builtin_amdgcn_s_setprio(0); } while (0)
; #define PG8_WAIT_V(n) asm volatile("s_waitcnt vmcnt(" #n ")" ::: "memory")
; #define PG8_WAIT_L(n) asm volatile("s_waitcnt lgkmcnt(" #n ")" ::: "memory")
; #define PG8_BAR __builtin_amdgcn_s_barrier()
; #define PG8_SCHED __builtin_amdgcn_sched_barrier(0)
; #define PG8_STA(bufoff, gbase, ld2) PG8_STAGE3(bufoff, gbase, ld2, R0, R1)
; #define PG8_STB(bufoff, gbase, ld2) PG8_STAGE3(bufoff, gbase, ld2, Rb0, Rb1)
; #define PG8_LDA(dst, b, h) do { _Pragma("unroll") for (int m = 0; m < 4; ++m) _Pragma("unroll") for (int k = 0; k < 2; ++k) dst[m][k] = *(const LAS bf16x8*)(lds + PG8_SA(b, h) + aoff + m * 2048 + k * 1024); } while (0)
; #define PG8_WAIT_V(n) asm volatile("s_waitcnt vmcnt(" #n ")" ::: "memory")
; #define PG8_BAR __builtin_amdgcn_s_barrier()
; template <class Sched, class Epi>
; DI void gemm_stream(char* smem, const Sched& S_, const Epi& E) {
;     ...
;       const int xa2 = (last ? nxt.lda : cur.lda) * 2, xb2 = (last ? nxt.ldb : cur.ldb) * 2;
;       const size_t xhA = (size_t)HALF * xa2, xhB = (size_t)HALF * xb2;
;       PG8_LDB(B0, 0, 0); PG8_SCHED; PG8_LDA(At, 0, 0); PG8_STA(PG8_SA(1, 1), a1 + hA, la2);
;       PG8_WAIT_L(8); PG8_BAR; PG8_WAIT_L(0); PG8_MMA(0, 0, At, B0); PG8_BAR; PG8_SCHED;
;       PG8_LDB(B1, 0, 1); PG8_STB(PG8_SB(0, 0), b2, xb2);
;       PG8_BAR; PG8_WAIT_L(0); PG8_MMA(0, 1, At, B1); PG8_BAR;
;       PG8_LDA(At, 0, 1); PG8_STA(PG8_SA(0, 0), a2, xa2);
;       PG8_BAR; PG8_WAIT_L(0); PG8_MMA(1, 0, At, B0); PG8_BAR; PG8_SCHED;
;       PG8_STB(PG8_SB(0, 1), b2 + xhB, xb2);
;       PG8_WAIT_V(6); PG8_BAR; PG8_MMA(1, 1, At, B1); PG8_BAR;
.LBB0_654:
	s_add_i32 s52, s40, 2
	s_add_u32 s44, s36, 0x80
	s_addc_u32 s41, s37, 0
	s_cmp_eq_u32 s63, s40
	s_cselect_b32 s41, s1, s41
	s_cselect_b32 s40, s0, s44
	s_cselect_b32 s44, s87, s62
	s_cselect_b32 s45, s86, s20
	s_cselect_b32 s47, s27, vcc_hi
	s_cselect_b32 s46, s26, vcc_lo
	s_add_i32 s53, 0, 0x10000
	v_add_u32_e32 v158, s53, v143
	ds_read_b128 v[146:149], v158
	ds_read_b128 v[150:153], v158 offset:1024
	ds_read_b128 v[154:157], v158 offset:2048
	ds_read_b128 v[158:161], v158 offset:3072
	s_lshl_b32 s88, s44, 1
	s_lshl_b32 s50, s45, 1
	s_ashr_i32 s89, s88, 31
	s_ashr_i32 s51, s50, 31
	s_lshl_b64 s[44:45], s[88:89], 7
	v_lshl_add_u64 v[190:191], s[36:37], 0, v[138:139]
	s_add_i32 m0, s33, 0xc000
	ds_read_b128 v[162:165], v145
	ds_read_b128 v[166:169], v145 offset:1024
	ds_read_b128 v[170:173], v145 offset:2048
	ds_read_b128 v[174:177], v145 offset:3072
	ds_read_b128 v[178:181], v145 offset:4096
	ds_read_b128 v[182:185], v145 offset:5120
	ds_read_b128 v[186:189], v145 offset:6144
	ds_read_b128 v[210:213], v145 offset:7168
	global_load_lds_dwordx4 v[190:191], off
	v_lshl_add_u64 v[190:191], s[36:37], 0, v[140:141]
	s_add_i32 m0, s33, 0xe000
	s_nop 0
	global_load_lds_dwordx4 v[190:191], off
	s_waitcnt lgkmcnt(8)
	s_barrier
	s_waitcnt lgkmcnt(0)
	s_setprio 1
	v_mfma_f32_16x16x32_bf16 v[124:127], v[146:149], v[162:165], v[124:127]
	v_mfma_f32_16x16x32_bf16 v[120:123], v[154:157], v[162:165], v[120:123]
	v_mfma_f32_16x16x32_bf16 v[116:119], v[146:149], v[170:173], v[116:119]
	v_mfma_f32_16x16x32_bf16 v[112:115], v[154:157], v[170:173], v[112:115]
	v_mfma_f32_16x16x32_bf16 v[108:111], v[146:149], v[178:181], v[108:111]
	v_mfma_f32_16x16x32_bf16 v[104:107], v[154:157], v[178:181], v[104:107]
	v_mfma_f32_16x16x32_bf16 v[100:103], v[146:149], v[186:189], v[100:103]
	v_mfma_f32_16x16x32_bf16 v[92:95], v[154:157], v[186:189], v[92:95]
	v_mfma_f32_16x16x32_bf16 v[124:127], v[150:153], v[166:169], v[124:127]
	v_mfma_f32_16x16x32_bf16 v[120:123], v[158:161], v[166:169], v[120:123]
	v_mfma_f32_16x16x32_bf16 v[116:119], v[150:153], v[174:177], v[116:119]
	v_mfma_f32_16x16x32_bf16 v[112:115], v[158:161], v[174:177], v[112:115]
	v_mfma_f32_16x16x32_bf16 v[108:111], v[150:153], v[182:185], v[108:111]
	v_mfma_f32_16x16x32_bf16 v[104:107], v[158:161], v[182:185], v[104:107]
	v_mfma_f32_16x16x32_bf16 v[100:103], v[150:153], v[210:213], v[100:103]
	v_mfma_f32_16x16x32_bf16 v[92:95], v[158:161], v[210:213], v[92:95]
	s_setprio 0
	s_barrier
	s_add_i32 s64, 0, 0x14000
	v_add_u32_e32 v190, s64, v143
	s_add_i32 s53, s53, s13
	ds_read_b128 v[214:217], v190
	ds_read_b128 v[234:237], v190 offset:1024
	ds_read_b128 v[238:241], v190 offset:2048
	ds_read_b128 v[242:245], v190 offset:3072
	v_mad_u64_u32 v[190:191], s[56:57], s50, v135, v[128:129]
	s_mov_b32 m0, s53
	v_mad_u64_u32 v[218:219], s[56:57], s50, v137, v[130:131]
	global_load_lds_dwordx4 v190, s[46:47]
	s_add_i32 m0, s53, 0x2000
	v_mov_b32_e32 v191, v221
	global_load_lds_dwordx4 v218, s[46:47]
	s_barrier
	s_waitcnt lgkmcnt(0)
	v_mov_b32_e32 v219, v221
	v_lshl_add_u64 v[246:247], s[46:47], 0, v[190:191]
	v_lshl_add_u64 v[202:203], s[46:47], 0, v[218:219]
	s_setprio 1
	s_waitcnt lgkmcnt(0)
	v_mfma_f32_16x16x32_bf16 v[96:99], v[214:217], v[162:165], v[96:99]
	v_mfma_f32_16x16x32_bf16 v[88:91], v[238:241], v[162:165], v[88:91]
	v_mfma_f32_16x16x32_bf16 v[84:87], v[214:217], v[170:173], v[84:87]
	v_mfma_f32_16x16x32_bf16 v[80:83], v[238:241], v[170:173], v[80:83]
	v_mfma_f32_16x16x32_bf16 v[76:79], v[214:217], v[178:181], v[76:79]
	v_mfma_f32_16x16x32_bf16 v[72:75], v[238:241], v[178:181], v[72:75]
	v_mfma_f32_16x16x32_bf16 v[68:71], v[214:217], v[186:189], v[68:71]
	v_mfma_f32_16x16x32_bf16 v[64:67], v[238:241], v[186:189], v[64:67]
	v_mfma_f32_16x16x32_bf16 v[96:99], v[234:237], v[166:169], v[96:99]
	v_mfma_f32_16x16x32_bf16 v[88:91], v[242:245], v[166:169], v[88:91]
	v_mfma_f32_16x16x32_bf16 v[84:87], v[234:237], v[174:177], v[84:87]
	v_mfma_f32_16x16x32_bf16 v[80:83], v[242:245], v[174:177], v[80:83]
	v_mfma_f32_16x16x32_bf16 v[76:79], v[234:237], v[182:185], v[76:79]
	v_mfma_f32_16x16x32_bf16 v[72:75], v[242:245], v[182:185], v[72:75]
	v_mfma_f32_16x16x32_bf16 v[68:71], v[234:237], v[210:213], v[68:71]
	v_mfma_f32_16x16x32_bf16 v[64:67], v[242:245], v[210:213], v[64:67]
	s_setprio 0
	s_mov_b32 m0, s33
	v_mad_u64_u32 v[194:195], s[56:57], s88, v129, v[128:129]
	s_barrier
	ds_read_b128 v[162:165], v145 offset:16384
	ds_read_b128 v[166:169], v145 offset:17408
	ds_read_b128 v[170:173], v145 offset:18432
	ds_read_b128 v[174:177], v145 offset:19456
	ds_read_b128 v[178:181], v145 offset:20480
	ds_read_b128 v[182:185], v145 offset:21504
	ds_read_b128 v[186:189], v145 offset:22528
	ds_read_b128 v[210:213], v145 offset:23552
	global_load_lds_dwordx4 v194, s[40:41]
	v_mad_u64_u32 v[200:201], s[56:57], s88, v131, v[130:131]
	s_mov_b32 m0, s34
	v_mov_b32_e32 v195, v221
	global_load_lds_dwordx4 v200, s[40:41]
	s_barrier
	s_waitcnt lgkmcnt(0)
	v_mov_b32_e32 v201, v221
	v_lshl_add_u64 v[208:209], s[40:41], 0, v[194:195]
	v_lshl_add_u64 v[222:223], s[40:41], 0, v[200:201]
	s_setprio 1
	s_waitcnt lgkmcnt(0)
	v_mfma_f32_16x16x32_bf16 v[60:63], v[146:149], v[162:165], v[60:63]
	s_lshl_b64 s[50:51], s[50:51], 7
	v_mfma_f32_16x16x32_bf16 v[56:59], v[154:157], v[162:165], v[56:59]
	v_mfma_f32_16x16x32_bf16 v[52:55], v[146:149], v[170:173], v[52:55]
	v_mfma_f32_16x16x32_bf16 v[48:51], v[154:157], v[170:173], v[48:51]
	v_mfma_f32_16x16x32_bf16 v[44:47], v[146:149], v[178:181], v[44:47]
	v_mfma_f32_16x16x32_bf16 v[40:43], v[154:157], v[178:181], v[40:43]
	v_mfma_f32_16x16x32_bf16 v[32:35], v[146:149], v[186:189], v[32:35]
	v_mfma_f32_16x16x32_bf16 v[24:27], v[154:157], v[186:189], v[24:27]
	v_mfma_f32_16x16x32_bf16 v[60:63], v[150:153], v[166:169], v[60:63]
	v_mfma_f32_16x16x32_bf16 v[56:59], v[158:161], v[166:169], v[56:59]
	v_mfma_f32_16x16x32_bf16 v[52:55], v[150:153], v[174:177], v[52:55]
	v_mfma_f32_16x16x32_bf16 v[48:51], v[158:161], v[174:177], v[48:51]
	v_mfma_f32_16x16x32_bf16 v[44:47], v[150:153], v[182:185], v[44:47]
	v_mfma_f32_16x16x32_bf16 v[40:43], v[158:161], v[182:185], v[40:43]
	v_mfma_f32_16x16x32_bf16 v[32:35], v[150:153], v[210:213], v[32:35]
	v_mfma_f32_16x16x32_bf16 v[24:27], v[158:161], v[210:213], v[24:27]
	s_setprio 0
	s_barrier
; #define PG8_LDA(dst, b, h) do { _Pragma("unroll") for (int m = 0; m < 4; ++m) _Pragma("unroll") for (int k = 0; k < 2; ++k) dst[m][k] = *(const LAS bf16x8*)(lds + PG8_SA(b, h) + aoff + m * 2048 + k * 1024); } while (0)
; #define PG8_LDB(dst, b, h) do { _Pragma("unroll") for (int n = 0; n < 2; ++n) _Pragma("unroll") for (int k = 0; k < 2; ++k) dst[n][k] = *(const LAS bf16x8*)(lds + PG8_SB(b, h) + boff + n * 2048 + k * 1024); } while (0)
; #define PG8_MMA(ai, bj, At, Bt_) do { __builtin_amdgcn_s_setprio(1); _Pragma("unroll") for (int m = 0; m < 4; ++m) _Pragma("unroll") for (int n = 0; n < 2; ++n) _Pragma("unroll") for (int k = 0; k < 2; ++k) \
;     acc[ai][bj][m][n] = __builtin_amdgcn_mfma_f32_16x16x32_bf16(Bt_[n][k], At[m][k], acc[ai][bj][m][n], 0, 0, 0); __builtin_amdgcn_s_setprio(0); } while (0)
; #define PG8_WAIT_V(n) asm volatile("s_waitcnt vmcnt(" #n ")" ::: "memory")
; #define PG8_WAIT_L(n) asm volatile("s_waitcnt lgkmcnt(" #n ")" ::: "memory")
; #define PG8_BAR __builtin_amdgcn_s_barrier()
; #define PG8_SCHED __builtin_amdgcn_sched_barrier(0)
; #define PG8_STA(bufoff, gbase, ld2) PG8_STAGE3(bufoff, gbase, ld2, R0, R1)
; #define PG8_STB(bufoff, gbase, ld2) PG8_STAGE3(bufoff, gbase, ld2, Rb0, Rb1)
; #define PG8_LDA(dst, b, h) do { _Pragma("unroll") for (int m = 0; m < 4; ++m) _Pragma("unroll") for (int k = 0; k < 2; ++k) dst[m][k] = *(const LAS bf16x8*)(lds + PG8_SA(b, h) + aoff + m * 2048 + k * 1024); } while (0)
; #define PG8_LDB(dst, b, h) do { _Pragma("unroll") for (int n = 0; n < 2; ++n) _Pragma("unroll") for (int k = 0; k < 2; ++k) dst[n][k] = *(const LAS bf16x8*)(lds + PG8_SB(b, h) + boff + n * 2048 + k * 1024); } while (0)
; #define PG8_WAIT_V(n) asm volatile("s_waitcnt vmcnt(" #n ")" ::: "memory")
; #define PG8_BAR __builtin_amdgcn_s_barrier()
; template <class Sched, class Epi>
; DI void gemm_stream(char* smem, const Sched& S_, const Epi& E) {
;     ...
;       PG8_STB(PG8_SB(0, 1), b2 + xhB, xb2);
;       PG8_WAIT_V(6); PG8_BAR; PG8_MMA(1, 1, At, B1); PG8_BAR;
;       PG8_LDB(B0, 1, 0); PG8_SCHED; PG8_LDA(At, 1, 0); PG8_STA(PG8_SA(0, 1), a2 + xhA, xa2);
;       PG8_WAIT_L(8); PG8_BAR; PG8_WAIT_L(0); PG8_MMA(0, 0, At, B0); PG8_BAR; PG8_SCHED;
;       PG8_LDB(B1, 1, 1); PG8_STB(PG8_SB(1, 0), b3, xb2);
;       PG8_BAR; PG8_WAIT_L(0); PG8_MMA(0, 1, At, B1); PG8_BAR;
;       PG8_LDA(At, 1, 1); PG8_STA(PG8_SA(1, 0), a3, xa2);
	s_add_u32 s46, s46, s50
	s_addc_u32 s47, s47, s51
	s_add_i32 s50, s64, s13
	s_mov_b32 m0, s50
	s_nop 0
	global_load_lds_dwordx4 v190, s[46:47]
	s_add_i32 m0, s50, 0x2000
	v_lshl_add_u64 v[190:191], s[46:47], 0, v[190:191]
	global_load_lds_dwordx4 v218, s[46:47]
	s_waitcnt vmcnt(6)
	v_lshl_add_u64 v[218:219], s[46:47], 0, v[218:219]
	s_barrier
	s_setprio 1
	v_mfma_f32_16x16x32_bf16 v[36:39], v[214:217], v[162:165], v[36:39]
	v_mfma_f32_16x16x32_bf16 v[28:31], v[238:241], v[162:165], v[28:31]
	v_mfma_f32_16x16x32_bf16 v[20:23], v[214:217], v[170:173], v[20:23]
	v_mfma_f32_16x16x32_bf16 v[16:19], v[238:241], v[170:173], v[16:19]
	v_mfma_f32_16x16x32_bf16 v[12:15], v[214:217], v[178:181], v[12:15]
	v_mfma_f32_16x16x32_bf16 v[8:11], v[238:241], v[178:181], v[8:11]
	v_mfma_f32_16x16x32_bf16 v[4:7], v[214:217], v[186:189], v[4:7]
	v_mfma_f32_16x16x32_bf16 v[0:3], v[238:241], v[186:189], v[0:3]
	v_mfma_f32_16x16x32_bf16 v[36:39], v[234:237], v[166:169], v[36:39]
	v_mfma_f32_16x16x32_bf16 v[28:31], v[242:245], v[166:169], v[28:31]
	v_mfma_f32_16x16x32_bf16 v[20:23], v[234:237], v[174:177], v[20:23]
	v_mfma_f32_16x16x32_bf16 v[16:19], v[242:245], v[174:177], v[16:19]
	v_mfma_f32_16x16x32_bf16 v[12:15], v[234:237], v[182:185], v[12:15]
	v_mfma_f32_16x16x32_bf16 v[8:11], v[242:245], v[182:185], v[8:11]
	v_mfma_f32_16x16x32_bf16 v[4:7], v[234:237], v[210:213], v[4:7]
	v_mfma_f32_16x16x32_bf16 v[0:3], v[242:245], v[210:213], v[0:3]
	s_setprio 0
	s_add_i32 s46, 0, 0x18000
	v_add_u32_e32 v158, s46, v143
	s_barrier
	ds_read_b128 v[146:149], v158
	ds_read_b128 v[150:153], v158 offset:1024
	ds_read_b128 v[154:157], v158 offset:2048
	ds_read_b128 v[158:161], v158 offset:3072
	s_add_u32 s40, s40, s44
	s_addc_u32 s41, s41, s45
	s_mov_b32 m0, s49
	ds_read_b128 v[162:165], v145 offset:32768
	ds_read_b128 v[166:169], v145 offset:33792
	ds_read_b128 v[170:173], v145 offset:34816
	ds_read_b128 v[174:177], v145 offset:35840
	ds_read_b128 v[178:181], v145 offset:36864
	ds_read_b128 v[182:185], v145 offset:37888
	ds_read_b128 v[186:189], v145 offset:38912
	ds_read_b128 v[210:213], v145 offset:39936
	global_load_lds_dwordx4 v194, s[40:41]
	s_mov_b32 m0, s60
	s_nop 0
	global_load_lds_dwordx4 v200, s[40:41]
	s_waitcnt lgkmcnt(8)
	s_barrier
	s_waitcnt lgkmcnt(0)
	s_setprio 1
	v_mfma_f32_16x16x32_bf16 v[124:127], v[146:149], v[162:165], v[124:127]
	v_mfma_f32_16x16x32_bf16 v[120:123], v[154:157], v[162:165], v[120:123]
	v_mfma_f32_16x16x32_bf16 v[116:119], v[146:149], v[170:173], v[116:119]
	v_mfma_f32_16x16x32_bf16 v[112:115], v[154:157], v[170:173], v[112:115]
	v_mfma_f32_16x16x32_bf16 v[108:111], v[146:149], v[178:181], v[108:111]
	v_mfma_f32_16x16x32_bf16 v[104:107], v[154:157], v[178:181], v[104:107]
	v_mfma_f32_16x16x32_bf16 v[100:103], v[146:149], v[186:189], v[100:103]
	v_mfma_f32_16x16x32_bf16 v[92:95], v[154:157], v[186:189], v[92:95]
	v_mfma_f32_16x16x32_bf16 v[124:127], v[150:153], v[166:169], v[124:127]
	v_mfma_f32_16x16x32_bf16 v[120:123], v[158:161], v[166:169], v[120:123]
	v_mfma_f32_16x16x32_bf16 v[116:119], v[150:153], v[174:177], v[116:119]
	v_mfma_f32_16x16x32_bf16 v[112:115], v[158:161], v[174:177], v[112:115]
	v_mfma_f32_16x16x32_bf16 v[108:111], v[150:153], v[182:185], v[108:111]
	v_mfma_f32_16x16x32_bf16 v[104:107], v[158:161], v[182:185], v[104:107]
	v_mfma_f32_16x16x32_bf16 v[100:103], v[150:153], v[210:213], v[100:103]
	v_mfma_f32_16x16x32_bf16 v[92:95], v[158:161], v[210:213], v[92:95]
	s_setprio 0
	s_barrier
	s_add_i32 s40, 0, 0x1c000
	v_add_u32_e32 v194, s40, v143
	s_add_i32 s41, s46, s13
	ds_read_b128 v[214:217], v194
	ds_read_b128 v[234:237], v194 offset:1024
	ds_read_b128 v[238:241], v194 offset:2048
	ds_read_b128 v[242:245], v194 offset:3072
	v_lshl_add_u64 v[194:195], v[246:247], 0, s[58:59]
	s_mov_b32 m0, s41
	s_nop 0
	global_load_lds_dwordx4 v[194:195], off
	v_lshl_add_u64 v[194:195], v[202:203], 0, s[58:59]
	s_add_i32 m0, s41, 0x2000
	s_nop 0
	global_load_lds_dwordx4 v[194:195], off
	s_barrier
	s_waitcnt lgkmcnt(0)
	s_setprio 1
	v_mfma_f32_16x16x32_bf16 v[96:99], v[214:217], v[162:165], v[96:99]
	v_mfma_f32_16x16x32_bf16 v[88:91], v[238:241], v[162:165], v[88:91]
	v_mfma_f32_16x16x32_bf16 v[84:87], v[214:217], v[170:173], v[84:87]
	v_mfma_f32_16x16x32_bf16 v[80:83], v[238:241], v[170:173], v[80:83]
	v_mfma_f32_16x16x32_bf16 v[76:79], v[214:217], v[178:181], v[76:79]
	v_mfma_f32_16x16x32_bf16 v[72:75], v[238:241], v[178:181], v[72:75]
	v_mfma_f32_16x16x32_bf16 v[68:71], v[214:217], v[186:189], v[68:71]
	v_mfma_f32_16x16x32_bf16 v[64:67], v[238:241], v[186:189], v[64:67]
	v_mfma_f32_16x16x32_bf16 v[96:99], v[234:237], v[166:169], v[96:99]
	v_mfma_f32_16x16x32_bf16 v[88:91], v[242:245], v[166:169], v[88:91]
	v_mfma_f32_16x16x32_bf16 v[84:87], v[234:237], v[174:177], v[84:87]
	v_mfma_f32_16x16x32_bf16 v[80:83], v[242:245], v[174:177], v[80:83]
	v_mfma_f32_16x16x32_bf16 v[76:79], v[234:237], v[182:185], v[76:79]
	v_mfma_f32_16x16x32_bf16 v[72:75], v[242:245], v[182:185], v[72:75]
	v_mfma_f32_16x16x32_bf16 v[68:71], v[234:237], v[210:213], v[68:71]
	v_mfma_f32_16x16x32_bf16 v[64:67], v[242:245], v[210:213], v[64:67]
	s_setprio 0
	s_mov_b32 m0, s97
	v_lshl_add_u64 v[194:195], v[208:209], 0, s[58:59]
	s_barrier
	ds_read_b128 v[162:165], v145 offset:49152
	ds_read_b128 v[166:169], v145 offset:50176
	ds_read_b128 v[170:173], v145 offset:51200
	ds_read_b128 v[174:177], v145 offset:52224
	ds_read_b128 v[178:181], v145 offset:53248
	ds_read_b128 v[182:185], v145 offset:54272
	ds_read_b128 v[186:189], v145 offset:55296
	ds_read_b128 v[210:213], v145 offset:56320
	global_load_lds_dwordx4 v[194:195], off
	v_lshl_add_u64 v[194:195], v[222:223], 0, s[58:59]
	s_mov_b32 m0, s42
	s_nop 0
	global_load_lds_dwordx4 v[194:195], off
	s_barrier
; #define PG8_LDA(dst, b, h) do { _Pragma("unroll") for (int m = 0; m < 4; ++m) _Pragma("unroll") for (int k = 0; k < 2; ++k) dst[m][k] = *(const LAS bf16x8*)(lds + PG8_SA(b, h) + aoff + m * 2048 + k * 1024); } while (0)
; #define PG8_MMA(ai, bj, At, Bt_) do { __builtin_amdgcn_s_setprio(1); _Pragma("unroll") for (int m = 0; m < 4; ++m) _Pragma("unroll") for (int n = 0; n < 2; ++n) _Pragma("unroll") for (int k = 0; k < 2; ++k) \
;     acc[ai][bj][m][n] = __builtin_amdgcn_mfma_f32_16x16x32_bf16(Bt_[n][k], At[m][k], acc[ai][bj][m][n], 0, 0, 0); __builtin_amdgcn_s_setprio(0); } while (0)
; #define PG8_WAIT_V(n) asm volatile("s_waitcnt vmcnt(" #n ")" ::: "memory")
; #define PG8_WAIT_L(n) asm volatile("s_waitcnt lgkmcnt(" #n ")" ::: "memory")
; #define PG8_BAR __builtin_amdgcn_s_barrier()
; #define PG8_SCHED __builtin_amdgcn_sched_barrier(0)
; DI u32x4 pack8v(const f32x4& a, const f32x4& b) { u32x4 w; w.x = pk2(a[0], a[1]); w.y = pk2(a[2], a[3]); w.z = pk2(b[0], b[1]); w.w = pk2(b[2], b[3]); return w; }
; #define PG8_STA(bufoff, gbase, ld2) PG8_STAGE3(bufoff, gbase, ld2, R0, R1)
; #define PG8_STB(bufoff, gbase, ld2) PG8_STAGE3(bufoff, gbase, ld2, Rb0, Rb1)
; #define PG8_LDA(dst, b, h) do { _Pragma("unroll") for (int m = 0; m < 4; ++m) _Pragma("unroll") for (int k = 0; k < 2; ++k) dst[m][k] = *(const LAS bf16x8*)(lds + PG8_SA(b, h) + aoff + m * 2048 + k * 1024); } while (0)
; #define PG8_WAIT_V(n) asm volatile("s_waitcnt vmcnt(" #n ")" ::: "memory")
; #define PG8_WAIT_L(n) asm volatile("s_waitcnt lgkmcnt(" #n ")" ::: "memory")
; template <class Sched, class Epi>
; DI void gemm_stream(char* smem, const Sched& S_, const Epi& E) {
;     ...
;       PG8_LDA(At, 1, 1); PG8_STA(PG8_SA(1, 0), a3, xa2);
;       PG8_BAR; PG8_WAIT_L(0); PG8_MMA(1, 0, At, B0); PG8_BAR; PG8_SCHED;
;       PG8_STB(PG8_SB(1, 1), b3 + xhB, xb2);
;       PG8_WAIT_V(6); PG8_BAR; PG8_MMA(1, 1, At, B1); PG8_BAR;
;     }
;   DI void operator()(const acc_t& acc, const Desc& u, int wr, int wc, int fr, int fq) const {
;     ...
;         for (int m = 0; m < 4; ++m) { const int tl = row0 + ai * HALF + m * 16, bl = tl / S, s = tl - bl * S;
; #pragma unroll
;           for (int bj = 0; bj < 2; ++bj) { const int c = u.pn * BM + bj * HALF + wc * 32 + 8 * fq, head = c >> 6, j = c & 63;
;             *(u32x4*)(Kb + ((size_t)(bl * 8 + head) * S + s) * 96 + j) = pack8v(acc[ai][bj][m][0], acc[ai][bj][m][1]); } }
	s_waitcnt lgkmcnt(0)
	s_setprio 1
	v_mfma_f32_16x16x32_bf16 v[60:63], v[146:149], v[162:165], v[60:63]
	v_mfma_f32_16x16x32_bf16 v[56:59], v[154:157], v[162:165], v[56:59]
	v_mfma_f32_16x16x32_bf16 v[52:55], v[146:149], v[170:173], v[52:55]
	v_mfma_f32_16x16x32_bf16 v[48:51], v[154:157], v[170:173], v[48:51]
	v_mfma_f32_16x16x32_bf16 v[44:47], v[146:149], v[178:181], v[44:47]
	v_mfma_f32_16x16x32_bf16 v[40:43], v[154:157], v[178:181], v[40:43]
	v_mfma_f32_16x16x32_bf16 v[32:35], v[146:149], v[186:189], v[32:35]
	v_mfma_f32_16x16x32_bf16 v[24:27], v[154:157], v[186:189], v[24:27]
	v_mfma_f32_16x16x32_bf16 v[60:63], v[150:153], v[166:169], v[60:63]
	v_mfma_f32_16x16x32_bf16 v[56:59], v[158:161], v[166:169], v[56:59]
	v_mfma_f32_16x16x32_bf16 v[52:55], v[150:153], v[174:177], v[52:55]
	v_mfma_f32_16x16x32_bf16 v[48:51], v[158:161], v[174:177], v[48:51]
	v_mfma_f32_16x16x32_bf16 v[44:47], v[150:153], v[182:185], v[44:47]
	v_mfma_f32_16x16x32_bf16 v[40:43], v[158:161], v[182:185], v[40:43]
	v_mfma_f32_16x16x32_bf16 v[32:35], v[150:153], v[210:213], v[32:35]
	v_mfma_f32_16x16x32_bf16 v[24:27], v[158:161], v[210:213], v[24:27]
	s_setprio 0
	s_barrier
	s_add_i32 s40, s40, s13
	v_lshl_add_u64 v[146:147], v[190:191], 0, s[58:59]
	s_mov_b32 m0, s40
	s_nop 0
	global_load_lds_dwordx4 v[146:147], off
	v_lshl_add_u64 v[146:147], v[218:219], 0, s[58:59]
	s_add_i32 m0, s40, 0x2000
	s_nop 0
	global_load_lds_dwordx4 v[146:147], off
	s_waitcnt vmcnt(6)
	s_barrier
	s_setprio 1
	v_mfma_f32_16x16x32_bf16 v[36:39], v[214:217], v[162:165], v[36:39]
	v_mfma_f32_16x16x32_bf16 v[28:31], v[238:241], v[162:165], v[28:31]
	v_mfma_f32_16x16x32_bf16 v[20:23], v[214:217], v[170:173], v[20:23]
	v_mfma_f32_16x16x32_bf16 v[16:19], v[238:241], v[170:173], v[16:19]
	v_mfma_f32_16x16x32_bf16 v[12:15], v[214:217], v[178:181], v[12:15]
	v_mfma_f32_16x16x32_bf16 v[8:11], v[238:241], v[178:181], v[8:11]
	v_mfma_f32_16x16x32_bf16 v[4:7], v[214:217], v[186:189], v[4:7]
	v_mfma_f32_16x16x32_bf16 v[0:3], v[238:241], v[186:189], v[0:3]
	v_mfma_f32_16x16x32_bf16 v[36:39], v[234:237], v[166:169], v[36:39]
	v_mfma_f32_16x16x32_bf16 v[28:31], v[242:245], v[166:169], v[28:31]
	v_mfma_f32_16x16x32_bf16 v[20:23], v[234:237], v[174:177], v[20:23]
	v_mfma_f32_16x16x32_bf16 v[16:19], v[242:245], v[174:177], v[16:19]
	v_mfma_f32_16x16x32_bf16 v[12:15], v[234:237], v[182:185], v[12:15]
	v_mfma_f32_16x16x32_bf16 v[8:11], v[242:245], v[182:185], v[8:11]
	v_mfma_f32_16x16x32_bf16 v[4:7], v[234:237], v[210:213], v[4:7]
	v_mfma_f32_16x16x32_bf16 v[0:3], v[242:245], v[210:213], v[0:3]
	s_setprio 0
	s_add_u32 s36, s36, 0x100
	s_addc_u32 s37, s37, 0
	s_add_u32 vcc_lo, vcc_lo, 0x100
	s_addc_u32 vcc_hi, vcc_hi, 0
	s_cmp_ge_i32 s52, s5
	s_mov_b32 s40, s52
	s_barrier
	s_cbranch_scc0 .LBB0_654
	v_readlane_b32 s46, v254, 46
	v_lshl_add_u32 v138, s4, 8, v142
	s_mov_b64 s[44:45], -1
	s_mov_b64 s[36:37], 0
	s_cmp_lt_i32 s91, 1
	s_mov_b64 s[40:41], 0
	v_readlane_b32 s47, v254, 47
	s_movk_i32 s50, 0x100
	s_mov_b32 s51, 0x78787879
	s_cbranch_scc1 .LBB0_659
	s_cmp_eq_u32 s91, 1
	s_mov_b64 s[40:41], -1
	s_cbranch_scc0 .LBB0_658
	v_mul_hi_i32 v139, v138, s51
	v_lshrrev_b32_e32 v140, 31, v139
	v_ashrrev_i32_e32 v139, 11, v139
	s_lshl_b32 s4, s9, 8
	v_add_u32_e32 v139, v139, v140
	s_movk_i32 s20, 0xef00
	s_or_b32 s4, s4, s90
	v_mad_i32_i24 v140, v139, s20, v138
	v_lshlrev_b32_e32 v139, 3, v139
	s_ashr_i32 s4, s4, 6
	v_ashrrev_i32_e32 v141, 31, v140
	v_add_u32_e32 v150, s4, v139
	s_movk_i32 s44, 0x1100
	s_or_b32 s5, s4, 2
	v_mad_i64_i32 v[150:151], s[40:41], v150, s44, v[140:141]
	v_add_u32_e32 v139, s5, v139
	v_mad_u64_u32 v[152:153], s[40:41], v150, s17, v[132:133]
	v_mad_i64_i32 v[140:141], s[40:41], v139, s44, v[140:141]
	v_or_b32_e32 v139, 16, v138
	v_mad_i32_i24 v153, v151, s17, v153
	v_mad_u64_u32 v[150:151], s[40:41], v140, s17, v[132:133]
	v_mul_hi_i32 v140, v139, s51
	v_mad_i32_i24 v151, v141, s17, v151
	v_lshrrev_b32_e32 v141, 31, v140
	v_ashrrev_i32_e32 v140, 11, v140
	v_cvt_pk_bf16_f32 v146, v124, v125
	v_cvt_pk_bf16_f32 v147, v126, v127
	v_cvt_pk_bf16_f32 v148, v120, v121
	v_cvt_pk_bf16_f32 v149, v122, v123
	v_add_u32_e32 v141, v140, v141
	global_store_dwordx4 v[152:153], v[146:149], off
	v_mad_i32_i24 v140, v141, s20, v139
	v_lshlrev_b32_e32 v139, 3, v141
	v_cvt_pk_bf16_f32 v146, v96, v97
	v_cvt_pk_bf16_f32 v147, v98, v99
	v_cvt_pk_bf16_f32 v148, v88, v89
	v_cvt_pk_bf16_f32 v149, v90, v91
	global_store_dwordx4 v[150:151], v[146:149], off
	v_ashrrev_i32_e32 v141, 31, v140
	v_add_u32_e32 v150, s4, v139
	v_mad_i64_i32 v[150:151], s[40:41], v150, s44, v[140:141]
	v_add_u32_e32 v139, s5, v139
	v_mad_u64_u32 v[152:153], s[40:41], v150, s17, v[132:133]
	v_mad_i64_i32 v[140:141], s[40:41], v139, s44, v[140:141]
	v_or_b32_e32 v139, 32, v138
	v_mad_i32_i24 v153, v151, s17, v153
	v_mad_u64_u32 v[150:151], s[40:41], v140, s17, v[132:133]
	v_mul_hi_i32 v140, v139, s51
	v_mad_i32_i24 v151, v141, s17, v151
	v_lshrrev_b32_e32 v141, 31, v140
	v_ashrrev_i32_e32 v140, 11, v140
	v_cvt_pk_bf16_f32 v146, v116, v117
	v_cvt_pk_bf16_f32 v147, v118, v119
	v_cvt_pk_bf16_f32 v148, v112, v113
	v_cvt_pk_bf16_f32 v149, v114, v115
	v_add_u32_e32 v141, v140, v141
	global_store_dwordx4 v[152:153], v[146:149], off
	v_mad_i32_i24 v140, v141, s20, v139
	v_lshlrev_b32_e32 v139, 3, v141
	v_cvt_pk_bf16_f32 v146, v84, v85
	v_cvt_pk_bf16_f32 v147, v86, v87
	v_cvt_pk_bf16_f32 v148, v80, v81
	v_cvt_pk_bf16_f32 v149, v82, v83
	global_store_dwordx4 v[150:151], v[146:149], off
	v_ashrrev_i32_e32 v141, 31, v140
	v_add_u32_e32 v150, s4, v139
	v_mad_i64_i32 v[150:151], s[40:41], v150, s44, v[140:141]
	v_add_u32_e32 v139, s5, v139
; DI u32x4 pack8v(const f32x4& a, const f32x4& b) { u32x4 w; w.x = pk2(a[0], a[1]); w.y = pk2(a[2], a[3]); w.z = pk2(b[0], b[1]); w.w = pk2(b[2], b[3]); return w; }
;   DI void operator()(const acc_t& acc, const Desc& u, int wr, int wc, int fr, int fq) const {
;     ...
;         for (int m = 0; m < 4; ++m) { const int tl = row0 + ai * HALF + m * 16, bl = tl / S, s = tl - bl * S;
; #pragma unroll
;           for (int bj = 0; bj < 2; ++bj) { const int c = u.pn * BM + bj * HALF + wc * 32 + 8 * fq, head = c >> 6, j = c & 63;
;             *(u32x4*)(Kb + ((size_t)(bl * 8 + head) * S + s) * 96 + j) = pack8v(acc[ai][bj][m][0], acc[ai][bj][m][1]); } }
	v_mad_u64_u32 v[152:153], s[40:41], v150, s17, v[132:133]
	v_mad_i64_i32 v[140:141], s[40:41], v139, s44, v[140:141]
	v_or_b32_e32 v139, 48, v138
	v_mad_i32_i24 v153, v151, s17, v153
	v_mad_u64_u32 v[150:151], s[40:41], v140, s17, v[132:133]
	v_mul_hi_i32 v140, v139, s51
	v_mad_i32_i24 v151, v141, s17, v151
	v_lshrrev_b32_e32 v141, 31, v140
	v_ashrrev_i32_e32 v140, 11, v140
	v_cvt_pk_bf16_f32 v146, v108, v109
	v_cvt_pk_bf16_f32 v147, v110, v111
	v_cvt_pk_bf16_f32 v148, v104, v105
	v_cvt_pk_bf16_f32 v149, v106, v107
	v_add_u32_e32 v141, v140, v141
	global_store_dwordx4 v[152:153], v[146:149], off
	v_mad_i32_i24 v140, v141, s20, v139
	v_lshlrev_b32_e32 v139, 3, v141
	v_cvt_pk_bf16_f32 v146, v76, v77
	v_cvt_pk_bf16_f32 v147, v78, v79
	v_cvt_pk_bf16_f32 v148, v72, v73
	v_cvt_pk_bf16_f32 v149, v74, v75
	global_store_dwordx4 v[150:151], v[146:149], off
	v_ashrrev_i32_e32 v141, 31, v140
	v_add_u32_e32 v150, s4, v139
	v_mad_i64_i32 v[150:151], s[40:41], v150, s44, v[140:141]
	v_add_u32_e32 v139, s5, v139
	v_mad_u64_u32 v[152:153], s[40:41], v150, s17, v[132:133]
	v_mad_i64_i32 v[140:141], s[40:41], v139, s44, v[140:141]
	v_add_u32_e32 v139, 0x80, v138
	v_mad_i32_i24 v153, v151, s17, v153
	v_mad_u64_u32 v[150:151], s[40:41], v140, s17, v[132:133]
	v_mul_hi_i32 v140, v139, s51
	v_mad_i32_i24 v151, v141, s17, v151
	v_lshrrev_b32_e32 v141, 31, v140
	v_ashrrev_i32_e32 v140, 11, v140
	v_cvt_pk_bf16_f32 v146, v100, v101
	v_cvt_pk_bf16_f32 v147, v102, v103
	v_cvt_pk_bf16_f32 v148, v92, v93
	v_cvt_pk_bf16_f32 v149, v94, v95
	v_add_u32_e32 v141, v140, v141
	global_store_dwordx4 v[152:153], v[146:149], off
	v_mad_i32_i24 v140, v141, s20, v139
	v_lshlrev_b32_e32 v139, 3, v141
	v_cvt_pk_bf16_f32 v146, v68, v69
	v_cvt_pk_bf16_f32 v147, v70, v71
	v_cvt_pk_bf16_f32 v148, v64, v65
	v_cvt_pk_bf16_f32 v149, v66, v67
	global_store_dwordx4 v[150:151], v[146:149], off
	v_ashrrev_i32_e32 v141, 31, v140
	v_add_u32_e32 v150, s4, v139
	v_mad_i64_i32 v[150:151], s[40:41], v150, s44, v[140:141]
	v_add_u32_e32 v139, s5, v139
	v_mad_u64_u32 v[152:153], s[40:41], v150, s17, v[132:133]
	v_mad_i64_i32 v[140:141], s[40:41], v139, s44, v[140:141]
	v_add_u32_e32 v139, 0x90, v138
	v_mad_i32_i24 v153, v151, s17, v153
	v_mad_u64_u32 v[150:151], s[40:41], v140, s17, v[132:133]
	v_mul_hi_i32 v140, v139, s51
	v_mad_i32_i24 v151, v141, s17, v151
	v_lshrrev_b32_e32 v141, 31, v140
	v_ashrrev_i32_e32 v140, 11, v140
	v_cvt_pk_bf16_f32 v146, v60, v61
	v_cvt_pk_bf16_f32 v147, v62, v63
	v_cvt_pk_bf16_f32 v148, v56, v57
	v_cvt_pk_bf16_f32 v149, v58, v59
	v_add_u32_e32 v141, v140, v141
	global_store_dwordx4 v[152:153], v[146:149], off
	v_mad_i32_i24 v140, v141, s20, v139
	v_lshlrev_b32_e32 v139, 3, v141
	v_cvt_pk_bf16_f32 v146, v36, v37
	v_cvt_pk_bf16_f32 v147, v38, v39
	v_cvt_pk_bf16_f32 v148, v28, v29
	v_cvt_pk_bf16_f32 v149, v30, v31
	global_store_dwordx4 v[150:151], v[146:149], off
	v_ashrrev_i32_e32 v141, 31, v140
	v_add_u32_e32 v150, s4, v139
	v_mad_i64_i32 v[150:151], s[40:41], v150, s44, v[140:141]
	v_add_u32_e32 v139, s5, v139
	v_mad_u64_u32 v[152:153], s[40:41], v150, s17, v[132:133]
	v_mad_i64_i32 v[140:141], s[40:41], v139, s44, v[140:141]
	v_add_u32_e32 v139, 0xa0, v138
	v_mad_i32_i24 v153, v151, s17, v153
	v_mad_u64_u32 v[150:151], s[40:41], v140, s17, v[132:133]
	v_mul_hi_i32 v140, v139, s51
	v_mad_i32_i24 v151, v141, s17, v151
	v_lshrrev_b32_e32 v141, 31, v140
	v_ashrrev_i32_e32 v140, 11, v140
	v_cvt_pk_bf16_f32 v146, v52, v53
	v_cvt_pk_bf16_f32 v147, v54, v55
	v_cvt_pk_bf16_f32 v148, v48, v49
	v_cvt_pk_bf16_f32 v149, v50, v51
	v_add_u32_e32 v141, v140, v141
	global_store_dwordx4 v[152:153], v[146:149], off
	v_mad_i32_i24 v140, v141, s20, v139
	v_lshlrev_b32_e32 v139, 3, v141
	v_cvt_pk_bf16_f32 v146, v20, v21
	v_cvt_pk_bf16_f32 v147, v22, v23
	v_cvt_pk_bf16_f32 v148, v16, v17
	v_cvt_pk_bf16_f32 v149, v18, v19
	global_store_dwordx4 v[150:151], v[146:149], off
	v_ashrrev_i32_e32 v141, 31, v140
	v_add_u32_e32 v150, s4, v139
	v_mad_i64_i32 v[150:151], s[40:41], v150, s44, v[140:141]
	v_add_u32_e32 v139, s5, v139
	v_mad_u64_u32 v[152:153], s[40:41], v150, s17, v[132:133]
	v_mad_i64_i32 v[140:141], s[40:41], v139, s44, v[140:141]
	v_add_u32_e32 v139, 0xb0, v138
	v_mad_i32_i24 v153, v151, s17, v153
	v_mad_u64_u32 v[150:151], s[40:41], v140, s17, v[132:133]
	v_mul_hi_i32 v140, v139, s51
	v_mad_i32_i24 v151, v141, s17, v151
	v_lshrrev_b32_e32 v141, 31, v140
	v_ashrrev_i32_e32 v140, 11, v140
	v_cvt_pk_bf16_f32 v146, v44, v45
	v_cvt_pk_bf16_f32 v147, v46, v47
	v_cvt_pk_bf16_f32 v148, v40, v41
	v_cvt_pk_bf16_f32 v149, v42, v43
	v_add_u32_e32 v141, v140, v141
	global_store_dwordx4 v[152:153], v[146:149], off
	v_mad_i32_i24 v140, v141, s20, v139
	v_lshlrev_b32_e32 v139, 3, v141
	v_cvt_pk_bf16_f32 v146, v12, v13
	v_cvt_pk_bf16_f32 v147, v14, v15
	v_cvt_pk_bf16_f32 v148, v8, v9
	v_cvt_pk_bf16_f32 v149, v10, v11
	global_store_dwordx4 v[150:151], v[146:149], off
	v_ashrrev_i32_e32 v141, 31, v140
	v_add_u32_e32 v150, s4, v139
	v_mad_i64_i32 v[150:151], s[40:41], v150, s44, v[140:141]
	v_add_u32_e32 v139, s5, v139
	v_mad_u64_u32 v[152:153], s[40:41], v150, s17, v[132:133]
	v_mad_i64_i32 v[140:141], s[4:5], v139, s44, v[140:141]
	v_cvt_pk_bf16_f32 v146, v32, v33
	v_cvt_pk_bf16_f32 v147, v34, v35
	v_cvt_pk_bf16_f32 v148, v24, v25
	v_cvt_pk_bf16_f32 v149, v26, v27
	v_mad_i32_i24 v153, v151, s17, v153
	v_mad_u64_u32 v[150:151], s[4:5], v140, s17, v[132:133]
	global_store_dwordx4 v[152:153], v[146:149], off
	v_mad_i32_i24 v151, v141, s17, v151
	s_movk_i32 s80, 0xef00
	v_cvt_pk_bf16_f32 v146, v4, v5
	v_cvt_pk_bf16_f32 v147, v6, v7
	v_cvt_pk_bf16_f32 v148, v0, v1
	v_cvt_pk_bf16_f32 v149, v2, v3
	global_store_dwordx4 v[150:151], v[146:149], off
	s_mov_b64 s[40:41], 0

; #define PG8_LDA(dst, b, h) do { _Pragma("unroll") for (int m = 0; m < 4; ++m) _Pragma("unroll") for (int k = 0; k < 2; ++k) dst[m][k] = *(const LAS bf16x8*)(lds + PG8_SA(b, h) + aoff + m * 2048 + k * 1024); } while (0)
; #define PG8_LDB(dst, b, h) do { _Pragma("unroll") for (int n = 0; n < 2; ++n) _Pragma("unroll") for (int k = 0; k < 2; ++k) dst[n][k] = *(const LAS bf16x8*)(lds + PG8_SB(b, h) + boff + n * 2048 + k * 1024); } while (0)
; #define PG8_MMA(ai, bj, At, Bt_) do { __builtin_amdgcn_s_setprio(1); _Pragma("unroll") for (int m = 0; m < 4; ++m) _Pragma("unroll") for (int n = 0; n < 2; ++n) _Pragma("unroll") for (int k = 0; k < 2; ++k) \
;     acc[ai][bj][m][n] = __builtin_amdgcn_mfma_f32_16x16x32_bf16(Bt_[n][k], At[m][k], acc[ai][bj][m][n], 0, 0, 0); __builtin_amdgcn_s_setprio(0); } while (0)
; #define PG8_WAIT_V(n) asm volatile("s_waitcnt vmcnt(" #n ")" ::: "memory")
; #define PG8_WAIT_L(n) asm volatile("s_waitcnt lgkmcnt(" #n ")" ::: "memory")
; #define PG8_BAR __builtin_amdgcn_s_barrier()
; #define PG8_SCHED __builtin_amdgcn_sched_barrier(0)
; #define PG8_STA(bufoff, gbase, ld2) PG8_STAGE3(bufoff, gbase, ld2, R0, R1)
; #define PG8_STB(bufoff, gbase, ld2) PG8_STAGE3(bufoff, gbase, ld2, Rb0, Rb1)
; #define PG8_LDA(dst, b, h) do { _Pragma("unroll") for (int m = 0; m < 4; ++m) _Pragma("unroll") for (int k = 0; k < 2; ++k) dst[m][k] = *(const LAS bf16x8*)(lds + PG8_SA(b, h) + aoff + m * 2048 + k * 1024); } while (0)
; #define PG8_WAIT_V(n) asm volatile("s_waitcnt vmcnt(" #n ")" ::: "memory")
; #define PG8_BAR __builtin_amdgcn_s_barrier()
; template <class Sched, class Epi>
; DI void gemm_stream(char* smem, const Sched& S_, const Epi& E) {
;     ...
;       const int xa2 = (last ? nxt.lda : cur.lda) * 2, xb2 = (last ? nxt.ldb : cur.ldb) * 2;
;       const size_t xhA = (size_t)HALF * xa2, xhB = (size_t)HALF * xb2;
;       PG8_LDB(B0, 0, 0); PG8_SCHED; PG8_LDA(At, 0, 0); PG8_STA(PG8_SA(1, 1), a1 + hA, la2);
;       PG8_WAIT_L(8); PG8_BAR; PG8_WAIT_L(0); PG8_MMA(0, 0, At, B0); PG8_BAR; PG8_SCHED;
;       PG8_LDB(B1, 0, 1); PG8_STB(PG8_SB(0, 0), b2, xb2);
;       PG8_BAR; PG8_WAIT_L(0); PG8_MMA(0, 1, At, B1); PG8_BAR;
;       PG8_LDA(At, 0, 1); PG8_STA(PG8_SA(0, 0), a2, xa2);
;       PG8_BAR; PG8_WAIT_L(0); PG8_MMA(1, 0, At, B0); PG8_BAR; PG8_SCHED;
;       PG8_STB(PG8_SB(0, 1), b2 + xhB, xb2);
;       PG8_WAIT_V(6); PG8_BAR; PG8_MMA(1, 1, At, B1); PG8_BAR;
.LBB0_933:
	s_add_i32 s53, s40, 2
	s_add_u32 s42, s36, 0x80
	s_addc_u32 s41, s37, 0
	s_cmp_eq_u32 vcc_lo, s40
	s_cselect_b32 s41, s1, s41
	s_cselect_b32 s40, s0, s42
	s_cselect_b32 s42, s4, s20
	s_cselect_b32 s43, s87, s63
	s_cselect_b32 s45, s27, s52
	s_cselect_b32 s44, s26, vcc_hi
	s_add_i32 s64, 0, 0x10000
	v_add_u32_e32 v158, s64, v143
	ds_read_b128 v[146:149], v158
	ds_read_b128 v[150:153], v158 offset:1024
	ds_read_b128 v[154:157], v158 offset:2048
	ds_read_b128 v[158:161], v158 offset:3072
	s_lshl_b32 s50, s42, 1
	s_lshl_b32 s46, s43, 1
	s_ashr_i32 s51, s50, 31
	s_ashr_i32 s47, s46, 31
	s_lshl_b64 s[42:43], s[50:51], 7
	v_lshl_add_u64 v[190:191], s[36:37], 0, v[138:139]
	s_add_i32 m0, s49, 0xc000
	ds_read_b128 v[162:165], v145
	ds_read_b128 v[166:169], v145 offset:1024
	ds_read_b128 v[170:173], v145 offset:2048
	ds_read_b128 v[174:177], v145 offset:3072
	ds_read_b128 v[178:181], v145 offset:4096
	ds_read_b128 v[182:185], v145 offset:5120
	ds_read_b128 v[186:189], v145 offset:6144
	ds_read_b128 v[210:213], v145 offset:7168
	global_load_lds_dwordx4 v[190:191], off
	v_lshl_add_u64 v[190:191], s[36:37], 0, v[140:141]
	s_add_i32 m0, s49, 0xe000
	s_nop 0
	global_load_lds_dwordx4 v[190:191], off
	s_waitcnt lgkmcnt(8)
	s_barrier
	s_waitcnt lgkmcnt(0)
	s_setprio 1
	v_mfma_f32_16x16x32_bf16 v[124:127], v[146:149], v[162:165], v[124:127]
	v_mfma_f32_16x16x32_bf16 v[120:123], v[154:157], v[162:165], v[120:123]
	v_mfma_f32_16x16x32_bf16 v[116:119], v[146:149], v[170:173], v[116:119]
	v_mfma_f32_16x16x32_bf16 v[112:115], v[154:157], v[170:173], v[112:115]
	v_mfma_f32_16x16x32_bf16 v[108:111], v[146:149], v[178:181], v[108:111]
	v_mfma_f32_16x16x32_bf16 v[104:107], v[154:157], v[178:181], v[104:107]
	v_mfma_f32_16x16x32_bf16 v[100:103], v[146:149], v[186:189], v[100:103]
	v_mfma_f32_16x16x32_bf16 v[92:95], v[154:157], v[186:189], v[92:95]
	v_mfma_f32_16x16x32_bf16 v[124:127], v[150:153], v[166:169], v[124:127]
	v_mfma_f32_16x16x32_bf16 v[120:123], v[158:161], v[166:169], v[120:123]
	v_mfma_f32_16x16x32_bf16 v[116:119], v[150:153], v[174:177], v[116:119]
	v_mfma_f32_16x16x32_bf16 v[112:115], v[158:161], v[174:177], v[112:115]
	v_mfma_f32_16x16x32_bf16 v[108:111], v[150:153], v[182:185], v[108:111]
	v_mfma_f32_16x16x32_bf16 v[104:107], v[158:161], v[182:185], v[104:107]
	v_mfma_f32_16x16x32_bf16 v[100:103], v[150:153], v[210:213], v[100:103]
	v_mfma_f32_16x16x32_bf16 v[92:95], v[158:161], v[210:213], v[92:95]
	s_setprio 0
	s_barrier
	s_add_i32 s65, 0, 0x14000
	v_add_u32_e32 v190, s65, v143
	s_add_i32 s51, s64, s34
	ds_read_b128 v[214:217], v190
	ds_read_b128 v[234:237], v190 offset:1024
	ds_read_b128 v[238:241], v190 offset:2048
	ds_read_b128 v[242:245], v190 offset:3072
	v_mad_u64_u32 v[190:191], s[56:57], s46, v135, v[128:129]
	s_mov_b32 m0, s51
	v_mad_u64_u32 v[194:195], s[56:57], s46, v137, v[130:131]
	global_load_lds_dwordx4 v190, s[44:45]
	s_add_i32 m0, s51, 0x2000
	v_mov_b32_e32 v191, v221
	global_load_lds_dwordx4 v194, s[44:45]
	s_barrier
	s_waitcnt lgkmcnt(0)
	v_mov_b32_e32 v195, v221
	v_lshl_add_u64 v[200:201], s[44:45], 0, v[190:191]
	v_lshl_add_u64 v[202:203], s[44:45], 0, v[194:195]
	s_setprio 1
	s_waitcnt lgkmcnt(0)
	v_mfma_f32_16x16x32_bf16 v[96:99], v[214:217], v[162:165], v[96:99]
	v_mfma_f32_16x16x32_bf16 v[88:91], v[238:241], v[162:165], v[88:91]
	v_mfma_f32_16x16x32_bf16 v[84:87], v[214:217], v[170:173], v[84:87]
	v_mfma_f32_16x16x32_bf16 v[80:83], v[238:241], v[170:173], v[80:83]
	v_mfma_f32_16x16x32_bf16 v[76:79], v[214:217], v[178:181], v[76:79]
	v_mfma_f32_16x16x32_bf16 v[72:75], v[238:241], v[178:181], v[72:75]
	v_mfma_f32_16x16x32_bf16 v[68:71], v[214:217], v[186:189], v[68:71]
	v_mfma_f32_16x16x32_bf16 v[64:67], v[238:241], v[186:189], v[64:67]
	v_mfma_f32_16x16x32_bf16 v[96:99], v[234:237], v[166:169], v[96:99]
	v_mfma_f32_16x16x32_bf16 v[88:91], v[242:245], v[166:169], v[88:91]
	v_mfma_f32_16x16x32_bf16 v[84:87], v[234:237], v[174:177], v[84:87]
	v_mfma_f32_16x16x32_bf16 v[80:83], v[242:245], v[174:177], v[80:83]
	v_mfma_f32_16x16x32_bf16 v[76:79], v[234:237], v[182:185], v[76:79]
	v_mfma_f32_16x16x32_bf16 v[72:75], v[242:245], v[182:185], v[72:75]
	v_mfma_f32_16x16x32_bf16 v[68:71], v[234:237], v[210:213], v[68:71]
	v_mfma_f32_16x16x32_bf16 v[64:67], v[242:245], v[210:213], v[64:67]
	s_setprio 0
	s_mov_b32 m0, s49
	v_mad_u64_u32 v[208:209], s[56:57], s50, v129, v[128:129]
	s_barrier
	ds_read_b128 v[162:165], v145 offset:16384
	ds_read_b128 v[166:169], v145 offset:17408
	ds_read_b128 v[170:173], v145 offset:18432
	ds_read_b128 v[174:177], v145 offset:19456
	ds_read_b128 v[178:181], v145 offset:20480
	ds_read_b128 v[182:185], v145 offset:21504
	ds_read_b128 v[186:189], v145 offset:22528
	ds_read_b128 v[210:213], v145 offset:23552
	global_load_lds_dwordx4 v208, s[40:41]
	v_mad_u64_u32 v[218:219], s[50:51], s50, v131, v[130:131]
	s_mov_b32 m0, s60
	v_mov_b32_e32 v209, v221
	global_load_lds_dwordx4 v218, s[40:41]
	s_barrier
	s_waitcnt lgkmcnt(0)
	v_mov_b32_e32 v219, v221
	v_lshl_add_u64 v[222:223], s[40:41], 0, v[208:209]
	v_lshl_add_u64 v[246:247], s[40:41], 0, v[218:219]
	s_setprio 1
	s_waitcnt lgkmcnt(0)
	v_mfma_f32_16x16x32_bf16 v[60:63], v[146:149], v[162:165], v[60:63]
	s_lshl_b64 s[46:47], s[46:47], 7
	v_mfma_f32_16x16x32_bf16 v[56:59], v[154:157], v[162:165], v[56:59]
	v_mfma_f32_16x16x32_bf16 v[52:55], v[146:149], v[170:173], v[52:55]
	v_mfma_f32_16x16x32_bf16 v[48:51], v[154:157], v[170:173], v[48:51]
	v_mfma_f32_16x16x32_bf16 v[44:47], v[146:149], v[178:181], v[44:47]
	v_mfma_f32_16x16x32_bf16 v[40:43], v[154:157], v[178:181], v[40:43]
	v_mfma_f32_16x16x32_bf16 v[32:35], v[146:149], v[186:189], v[32:35]
	v_mfma_f32_16x16x32_bf16 v[24:27], v[154:157], v[186:189], v[24:27]
	v_mfma_f32_16x16x32_bf16 v[60:63], v[150:153], v[166:169], v[60:63]
	v_mfma_f32_16x16x32_bf16 v[56:59], v[158:161], v[166:169], v[56:59]
	v_mfma_f32_16x16x32_bf16 v[52:55], v[150:153], v[174:177], v[52:55]
	v_mfma_f32_16x16x32_bf16 v[48:51], v[158:161], v[174:177], v[48:51]
	v_mfma_f32_16x16x32_bf16 v[44:47], v[150:153], v[182:185], v[44:47]
	v_mfma_f32_16x16x32_bf16 v[40:43], v[158:161], v[182:185], v[40:43]
	v_mfma_f32_16x16x32_bf16 v[32:35], v[150:153], v[210:213], v[32:35]
	v_mfma_f32_16x16x32_bf16 v[24:27], v[158:161], v[210:213], v[24:27]
	s_setprio 0
	s_barrier
; #define PG8_LDA(dst, b, h) do { _Pragma("unroll") for (int m = 0; m < 4; ++m) _Pragma("unroll") for (int k = 0; k < 2; ++k) dst[m][k] = *(const LAS bf16x8*)(lds + PG8_SA(b, h) + aoff + m * 2048 + k * 1024); } while (0)
; #define PG8_LDB(dst, b, h) do { _Pragma("unroll") for (int n = 0; n < 2; ++n) _Pragma("unroll") for (int k = 0; k < 2; ++k) dst[n][k] = *(const LAS bf16x8*)(lds + PG8_SB(b, h) + boff + n * 2048 + k * 1024); } while (0)
; #define PG8_MMA(ai, bj, At, Bt_) do { __builtin_amdgcn_s_setprio(1); _Pragma("unroll") for (int m = 0; m < 4; ++m) _Pragma("unroll") for (int n = 0; n < 2; ++n) _Pragma("unroll") for (int k = 0; k < 2; ++k) \
;     acc[ai][bj][m][n] = __builtin_amdgcn_mfma_f32_16x16x32_bf16(Bt_[n][k], At[m][k], acc[ai][bj][m][n], 0, 0, 0); __builtin_amdgcn_s_setprio(0); } while (0)
; #define PG8_WAIT_V(n) asm volatile("s_waitcnt vmcnt(" #n ")" ::: "memory")
; #define PG8_WAIT_L(n) asm volatile("s_waitcnt lgkmcnt(" #n ")" ::: "memory")
; #define PG8_BAR __builtin_amdgcn_s_barrier()
; #define PG8_SCHED __builtin_amdgcn_sched_barrier(0)
; #define PG8_STA(bufoff, gbase, ld2) PG8_STAGE3(bufoff, gbase, ld2, R0, R1)
; #define PG8_STB(bufoff, gbase, ld2) PG8_STAGE3(bufoff, gbase, ld2, Rb0, Rb1)
; #define PG8_LDA(dst, b, h) do { _Pragma("unroll") for (int m = 0; m < 4; ++m) _Pragma("unroll") for (int k = 0; k < 2; ++k) dst[m][k] = *(const LAS bf16x8*)(lds + PG8_SA(b, h) + aoff + m * 2048 + k * 1024); } while (0)
; #define PG8_LDB(dst, b, h) do { _Pragma("unroll") for (int n = 0; n < 2; ++n) _Pragma("unroll") for (int k = 0; k < 2; ++k) dst[n][k] = *(const LAS bf16x8*)(lds + PG8_SB(b, h) + boff + n * 2048 + k * 1024); } while (0)
; #define PG8_WAIT_V(n) asm volatile("s_waitcnt vmcnt(" #n ")" ::: "memory")
; #define PG8_BAR __builtin_amdgcn_s_barrier()
; template <class Sched, class Epi>
; DI void gemm_stream(char* smem, const Sched& S_, const Epi& E) {
;     ...
;       PG8_STB(PG8_SB(0, 1), b2 + xhB, xb2);
;       PG8_WAIT_V(6); PG8_BAR; PG8_MMA(1, 1, At, B1); PG8_BAR;
;       PG8_LDB(B0, 1, 0); PG8_SCHED; PG8_LDA(At, 1, 0); PG8_STA(PG8_SA(0, 1), a2 + xhA, xa2);
;       PG8_WAIT_L(8); PG8_BAR; PG8_WAIT_L(0); PG8_MMA(0, 0, At, B0); PG8_BAR; PG8_SCHED;
;       PG8_LDB(B1, 1, 1); PG8_STB(PG8_SB(1, 0), b3, xb2);
;       PG8_BAR; PG8_WAIT_L(0); PG8_MMA(0, 1, At, B1); PG8_BAR;
;       PG8_LDA(At, 1, 1); PG8_STA(PG8_SA(1, 0), a3, xa2);
	s_add_u32 s44, s44, s46
	s_addc_u32 s45, s45, s47
	s_add_i32 s46, s65, s34
	s_mov_b32 m0, s46
	s_nop 0
	global_load_lds_dwordx4 v190, s[44:45]
	s_add_i32 m0, s46, 0x2000
	v_lshl_add_u64 v[190:191], s[44:45], 0, v[190:191]
	global_load_lds_dwordx4 v194, s[44:45]
	s_waitcnt vmcnt(6)
	v_lshl_add_u64 v[194:195], s[44:45], 0, v[194:195]
	s_barrier
	s_setprio 1
	v_mfma_f32_16x16x32_bf16 v[36:39], v[214:217], v[162:165], v[36:39]
	v_mfma_f32_16x16x32_bf16 v[28:31], v[238:241], v[162:165], v[28:31]
	v_mfma_f32_16x16x32_bf16 v[20:23], v[214:217], v[170:173], v[20:23]
	v_mfma_f32_16x16x32_bf16 v[16:19], v[238:241], v[170:173], v[16:19]
	v_mfma_f32_16x16x32_bf16 v[12:15], v[214:217], v[178:181], v[12:15]
	v_mfma_f32_16x16x32_bf16 v[8:11], v[238:241], v[178:181], v[8:11]
	v_mfma_f32_16x16x32_bf16 v[4:7], v[214:217], v[186:189], v[4:7]
	v_mfma_f32_16x16x32_bf16 v[0:3], v[238:241], v[186:189], v[0:3]
	v_mfma_f32_16x16x32_bf16 v[36:39], v[234:237], v[166:169], v[36:39]
	v_mfma_f32_16x16x32_bf16 v[28:31], v[242:245], v[166:169], v[28:31]
	v_mfma_f32_16x16x32_bf16 v[20:23], v[234:237], v[174:177], v[20:23]
	v_mfma_f32_16x16x32_bf16 v[16:19], v[242:245], v[174:177], v[16:19]
	v_mfma_f32_16x16x32_bf16 v[12:15], v[234:237], v[182:185], v[12:15]
	v_mfma_f32_16x16x32_bf16 v[8:11], v[242:245], v[182:185], v[8:11]
	v_mfma_f32_16x16x32_bf16 v[4:7], v[234:237], v[210:213], v[4:7]
	v_mfma_f32_16x16x32_bf16 v[0:3], v[242:245], v[210:213], v[0:3]
	s_setprio 0
	s_add_i32 s44, 0, 0x18000
	v_add_u32_e32 v158, s44, v143
	s_barrier
	ds_read_b128 v[146:149], v158
	ds_read_b128 v[150:153], v158 offset:1024
	ds_read_b128 v[154:157], v158 offset:2048
	ds_read_b128 v[158:161], v158 offset:3072
	s_add_u32 s40, s40, s42
	s_addc_u32 s41, s41, s43
	s_mov_b32 m0, s89
	ds_read_b128 v[162:165], v145 offset:32768
	ds_read_b128 v[166:169], v145 offset:33792
	ds_read_b128 v[170:173], v145 offset:34816
	ds_read_b128 v[174:177], v145 offset:35840
	ds_read_b128 v[178:181], v145 offset:36864
	ds_read_b128 v[182:185], v145 offset:37888
	ds_read_b128 v[186:189], v145 offset:38912
	ds_read_b128 v[210:213], v145 offset:39936
	global_load_lds_dwordx4 v208, s[40:41]
	s_mov_b32 m0, s90
	s_nop 0
	global_load_lds_dwordx4 v218, s[40:41]
	s_waitcnt lgkmcnt(8)
	s_barrier
	s_waitcnt lgkmcnt(0)
	s_setprio 1
	v_mfma_f32_16x16x32_bf16 v[124:127], v[146:149], v[162:165], v[124:127]
	v_mfma_f32_16x16x32_bf16 v[120:123], v[154:157], v[162:165], v[120:123]
	v_mfma_f32_16x16x32_bf16 v[116:119], v[146:149], v[170:173], v[116:119]
	v_mfma_f32_16x16x32_bf16 v[112:115], v[154:157], v[170:173], v[112:115]
	v_mfma_f32_16x16x32_bf16 v[108:111], v[146:149], v[178:181], v[108:111]
	v_mfma_f32_16x16x32_bf16 v[104:107], v[154:157], v[178:181], v[104:107]
	v_mfma_f32_16x16x32_bf16 v[100:103], v[146:149], v[186:189], v[100:103]
	v_mfma_f32_16x16x32_bf16 v[92:95], v[154:157], v[186:189], v[92:95]
	v_mfma_f32_16x16x32_bf16 v[124:127], v[150:153], v[166:169], v[124:127]
	v_mfma_f32_16x16x32_bf16 v[120:123], v[158:161], v[166:169], v[120:123]
	v_mfma_f32_16x16x32_bf16 v[116:119], v[150:153], v[174:177], v[116:119]
	v_mfma_f32_16x16x32_bf16 v[112:115], v[158:161], v[174:177], v[112:115]
	v_mfma_f32_16x16x32_bf16 v[108:111], v[150:153], v[182:185], v[108:111]
	v_mfma_f32_16x16x32_bf16 v[104:107], v[158:161], v[182:185], v[104:107]
	v_mfma_f32_16x16x32_bf16 v[100:103], v[150:153], v[210:213], v[100:103]
	v_mfma_f32_16x16x32_bf16 v[92:95], v[158:161], v[210:213], v[92:95]
	s_setprio 0
	s_barrier
	s_add_i32 s40, 0, 0x1c000
	s_add_i32 s41, s44, s34
	v_add_u32_e32 v204, s40, v143
	v_lshl_add_u64 v[200:201], v[200:201], 0, s[58:59]
	s_mov_b32 m0, s41
	ds_read_b128 v[214:217], v204
	ds_read_b128 v[234:237], v204 offset:1024
	ds_read_b128 v[238:241], v204 offset:2048
	ds_read_b128 v[242:245], v204 offset:3072
	global_load_lds_dwordx4 v[200:201], off
	v_lshl_add_u64 v[200:201], v[202:203], 0, s[58:59]
	s_add_i32 m0, s41, 0x2000
	s_nop 0
	global_load_lds_dwordx4 v[200:201], off
	s_barrier
	s_waitcnt lgkmcnt(0)
	s_setprio 1
	v_mfma_f32_16x16x32_bf16 v[96:99], v[214:217], v[162:165], v[96:99]
	v_mfma_f32_16x16x32_bf16 v[88:91], v[238:241], v[162:165], v[88:91]
	v_mfma_f32_16x16x32_bf16 v[84:87], v[214:217], v[170:173], v[84:87]
	v_mfma_f32_16x16x32_bf16 v[80:83], v[238:241], v[170:173], v[80:83]
	v_mfma_f32_16x16x32_bf16 v[76:79], v[214:217], v[178:181], v[76:79]
	v_mfma_f32_16x16x32_bf16 v[72:75], v[238:241], v[178:181], v[72:75]
	v_mfma_f32_16x16x32_bf16 v[68:71], v[214:217], v[186:189], v[68:71]
	v_mfma_f32_16x16x32_bf16 v[64:67], v[238:241], v[186:189], v[64:67]
	v_mfma_f32_16x16x32_bf16 v[96:99], v[234:237], v[166:169], v[96:99]
	v_mfma_f32_16x16x32_bf16 v[88:91], v[242:245], v[166:169], v[88:91]
	v_mfma_f32_16x16x32_bf16 v[84:87], v[234:237], v[174:177], v[84:87]
	v_mfma_f32_16x16x32_bf16 v[80:83], v[242:245], v[174:177], v[80:83]
	v_mfma_f32_16x16x32_bf16 v[76:79], v[234:237], v[182:185], v[76:79]
	v_mfma_f32_16x16x32_bf16 v[72:75], v[242:245], v[182:185], v[72:75]
	v_mfma_f32_16x16x32_bf16 v[68:71], v[234:237], v[210:213], v[68:71]
	v_mfma_f32_16x16x32_bf16 v[64:67], v[242:245], v[210:213], v[64:67]
	s_setprio 0
	s_mov_b32 m0, s9
	v_lshl_add_u64 v[200:201], v[222:223], 0, s[58:59]
	s_barrier
	ds_read_b128 v[162:165], v145 offset:49152
	ds_read_b128 v[166:169], v145 offset:50176
	ds_read_b128 v[170:173], v145 offset:51200
	ds_read_b128 v[174:177], v145 offset:52224
	ds_read_b128 v[178:181], v145 offset:53248
	ds_read_b128 v[182:185], v145 offset:54272
	ds_read_b128 v[186:189], v145 offset:55296
	ds_read_b128 v[210:213], v145 offset:56320
	global_load_lds_dwordx4 v[200:201], off
	v_lshl_add_u64 v[200:201], v[246:247], 0, s[58:59]
	s_mov_b32 m0, s88
	s_nop 0
	global_load_lds_dwordx4 v[200:201], off
	s_barrier
; #define PG8_LDA(dst, b, h) do { _Pragma("unroll") for (int m = 0; m < 4; ++m) _Pragma("unroll") for (int k = 0; k < 2; ++k) dst[m][k] = *(const LAS bf16x8*)(lds + PG8_SA(b, h) + aoff + m * 2048 + k * 1024); } while (0)
; #define PG8_MMA(ai, bj, At, Bt_) do { __builtin_amdgcn_s_setprio(1); _Pragma("unroll") for (int m = 0; m < 4; ++m) _Pragma("unroll") for (int n = 0; n < 2; ++n) _Pragma("unroll") for (int k = 0; k < 2; ++k) \
;     acc[ai][bj][m][n] = __builtin_amdgcn_mfma_f32_16x16x32_bf16(Bt_[n][k], At[m][k], acc[ai][bj][m][n], 0, 0, 0); __builtin_amdgcn_s_setprio(0); } while (0)
; #define PG8_WAIT_V(n) asm volatile("s_waitcnt vmcnt(" #n ")" ::: "memory")
; #define PG8_WAIT_L(n) asm volatile("s_waitcnt lgkmcnt(" #n ")" ::: "memory")
; #define PG8_BAR __builtin_amdgcn_s_barrier()
; #define PG8_SCHED __builtin_amdgcn_sched_barrier(0)
; DI u32x4 pack8v(const f32x4& a, const f32x4& b) { u32x4 w; w.x = pk2(a[0], a[1]); w.y = pk2(a[2], a[3]); w.z = pk2(b[0], b[1]); w.w = pk2(b[2], b[3]); return w; }
; #define PG8_STA(bufoff, gbase, ld2) PG8_STAGE3(bufoff, gbase, ld2, R0, R1)
; #define PG8_STB(bufoff, gbase, ld2) PG8_STAGE3(bufoff, gbase, ld2, Rb0, Rb1)
; #define PG8_LDA(dst, b, h) do { _Pragma("unroll") for (int m = 0; m < 4; ++m) _Pragma("unroll") for (int k = 0; k < 2; ++k) dst[m][k] = *(const LAS bf16x8*)(lds + PG8_SA(b, h) + aoff + m * 2048 + k * 1024); } while (0)
; #define PG8_WAIT_V(n) asm volatile("s_waitcnt vmcnt(" #n ")" ::: "memory")
; #define PG8_WAIT_L(n) asm volatile("s_waitcnt lgkmcnt(" #n ")" ::: "memory")
; template <class Sched, class Epi>
; DI void gemm_stream(char* smem, const Sched& S_, const Epi& E) {
;     ...
;       PG8_LDA(At, 1, 1); PG8_STA(PG8_SA(1, 0), a3, xa2);
;       PG8_BAR; PG8_WAIT_L(0); PG8_MMA(1, 0, At, B0); PG8_BAR; PG8_SCHED;
;       PG8_STB(PG8_SB(1, 1), b3 + xhB, xb2);
;       PG8_WAIT_V(6); PG8_BAR; PG8_MMA(1, 1, At, B1); PG8_BAR;
;     }
;   DI void operator()(const acc_t& acc, const Desc& u, int wr, int wc, int fr, int fq) const {
;     ...
;         for (int m = 0; m < 4; ++m) { const int tl = row0 + ai * HALF + m * 16, bl = tl / S, s = tl - bl * S;
; #pragma unroll
;           for (int bj = 0; bj < 2; ++bj) { const int c = u.pn * BM + bj * HALF + wc * 32 + 8 * fq, head = c >> 6, j = c & 63;
;             *(u32x4*)(Kb + ((size_t)(bl * 8 + head) * S + s) * 96 + j) = pack8v(acc[ai][bj][m][0], acc[ai][bj][m][1]); } }
	s_waitcnt lgkmcnt(0)
	s_setprio 1
	v_mfma_f32_16x16x32_bf16 v[60:63], v[146:149], v[162:165], v[60:63]
	v_mfma_f32_16x16x32_bf16 v[56:59], v[154:157], v[162:165], v[56:59]
	v_mfma_f32_16x16x32_bf16 v[52:55], v[146:149], v[170:173], v[52:55]
	v_mfma_f32_16x16x32_bf16 v[48:51], v[154:157], v[170:173], v[48:51]
	v_mfma_f32_16x16x32_bf16 v[44:47], v[146:149], v[178:181], v[44:47]
	v_mfma_f32_16x16x32_bf16 v[40:43], v[154:157], v[178:181], v[40:43]
	v_mfma_f32_16x16x32_bf16 v[32:35], v[146:149], v[186:189], v[32:35]
	v_mfma_f32_16x16x32_bf16 v[24:27], v[154:157], v[186:189], v[24:27]
	v_mfma_f32_16x16x32_bf16 v[60:63], v[150:153], v[166:169], v[60:63]
	v_mfma_f32_16x16x32_bf16 v[56:59], v[158:161], v[166:169], v[56:59]
	v_mfma_f32_16x16x32_bf16 v[52:55], v[150:153], v[174:177], v[52:55]
	v_mfma_f32_16x16x32_bf16 v[48:51], v[158:161], v[174:177], v[48:51]
	v_mfma_f32_16x16x32_bf16 v[44:47], v[150:153], v[182:185], v[44:47]
	v_mfma_f32_16x16x32_bf16 v[40:43], v[158:161], v[182:185], v[40:43]
	v_mfma_f32_16x16x32_bf16 v[32:35], v[150:153], v[210:213], v[32:35]
	v_mfma_f32_16x16x32_bf16 v[24:27], v[158:161], v[210:213], v[24:27]
	s_setprio 0
	s_barrier
	s_add_i32 s40, s40, s34
	v_lshl_add_u64 v[146:147], v[190:191], 0, s[58:59]
	s_mov_b32 m0, s40
	s_nop 0
	global_load_lds_dwordx4 v[146:147], off
	v_lshl_add_u64 v[146:147], v[194:195], 0, s[58:59]
	s_add_i32 m0, s40, 0x2000
	s_nop 0
	global_load_lds_dwordx4 v[146:147], off
	s_waitcnt vmcnt(6)
	s_barrier
	s_setprio 1
	v_mfma_f32_16x16x32_bf16 v[36:39], v[214:217], v[162:165], v[36:39]
	v_mfma_f32_16x16x32_bf16 v[28:31], v[238:241], v[162:165], v[28:31]
	v_mfma_f32_16x16x32_bf16 v[20:23], v[214:217], v[170:173], v[20:23]
	v_mfma_f32_16x16x32_bf16 v[16:19], v[238:241], v[170:173], v[16:19]
	v_mfma_f32_16x16x32_bf16 v[12:15], v[214:217], v[178:181], v[12:15]
	v_mfma_f32_16x16x32_bf16 v[8:11], v[238:241], v[178:181], v[8:11]
	v_mfma_f32_16x16x32_bf16 v[4:7], v[214:217], v[186:189], v[4:7]
	v_mfma_f32_16x16x32_bf16 v[0:3], v[238:241], v[186:189], v[0:3]
	v_mfma_f32_16x16x32_bf16 v[36:39], v[234:237], v[166:169], v[36:39]
	v_mfma_f32_16x16x32_bf16 v[28:31], v[242:245], v[166:169], v[28:31]
	v_mfma_f32_16x16x32_bf16 v[20:23], v[234:237], v[174:177], v[20:23]
	v_mfma_f32_16x16x32_bf16 v[16:19], v[242:245], v[174:177], v[16:19]
	v_mfma_f32_16x16x32_bf16 v[12:15], v[234:237], v[182:185], v[12:15]
	v_mfma_f32_16x16x32_bf16 v[8:11], v[242:245], v[182:185], v[8:11]
	v_mfma_f32_16x16x32_bf16 v[4:7], v[234:237], v[210:213], v[4:7]
	v_mfma_f32_16x16x32_bf16 v[0:3], v[242:245], v[210:213], v[0:3]
	s_setprio 0
	s_add_u32 s36, s36, 0x100
	s_addc_u32 s37, s37, 0
	s_add_u32 vcc_hi, vcc_hi, 0x100
	s_addc_u32 s52, s52, 0
	s_cmp_ge_i32 s53, s5
	s_mov_b32 s40, s53
	s_barrier
	s_cbranch_scc0 .LBB0_933
	v_readlane_b32 s44, v252, 27
	v_lshl_add_u32 v138, s29, 8, v142
	s_mov_b64 s[42:43], -1
	s_mov_b64 s[36:37], 0
	s_cmp_lt_i32 s97, 1
	s_mov_b64 s[40:41], 0
	v_readlane_b32 s45, v252, 28
	s_movk_i32 s50, 0x100
	s_mov_b32 s51, 0x78787879
	s_cbranch_scc1 .LBB0_938
	s_cmp_eq_u32 s97, 1
	s_mov_b64 s[40:41], -1
	s_cbranch_scc0 .LBB0_937
	v_mul_hi_i32 v139, v138, s51
	v_lshrrev_b32_e32 v140, 31, v139
	v_ashrrev_i32_e32 v139, 11, v139
	s_lshl_b32 s5, s33, 8
	v_add_u32_e32 v139, v139, v140
	s_movk_i32 s29, 0xef00
	s_or_b32 s5, s5, s67
	v_mad_i32_i24 v140, v139, s29, v138
	v_lshlrev_b32_e32 v139, 3, v139
	s_ashr_i32 s5, s5, 6
	v_ashrrev_i32_e32 v141, 31, v140
	v_add_u32_e32 v150, s5, v139
	s_movk_i32 s42, 0x1100
	s_or_b32 s20, s5, 2
	v_mad_i64_i32 v[150:151], s[40:41], v150, s42, v[140:141]
	v_add_u32_e32 v139, s20, v139
	v_mad_u64_u32 v[152:153], s[40:41], v150, s17, v[132:133]
	v_mad_i64_i32 v[140:141], s[40:41], v139, s42, v[140:141]
	v_or_b32_e32 v139, 16, v138
	v_mad_i32_i24 v153, v151, s17, v153
	v_mad_u64_u32 v[150:151], s[40:41], v140, s17, v[132:133]
	v_mul_hi_i32 v140, v139, s51
	v_mad_i32_i24 v151, v141, s17, v151
	v_lshrrev_b32_e32 v141, 31, v140
	v_ashrrev_i32_e32 v140, 11, v140
	v_cvt_pk_bf16_f32 v146, v124, v125
	v_cvt_pk_bf16_f32 v147, v126, v127
	v_cvt_pk_bf16_f32 v148, v120, v121
	v_cvt_pk_bf16_f32 v149, v122, v123
	v_add_u32_e32 v141, v140, v141
	global_store_dwordx4 v[152:153], v[146:149], off
	v_mad_i32_i24 v140, v141, s29, v139
	v_lshlrev_b32_e32 v139, 3, v141
	v_cvt_pk_bf16_f32 v146, v96, v97
	v_cvt_pk_bf16_f32 v147, v98, v99
	v_cvt_pk_bf16_f32 v148, v88, v89
	v_cvt_pk_bf16_f32 v149, v90, v91
	global_store_dwordx4 v[150:151], v[146:149], off
	v_ashrrev_i32_e32 v141, 31, v140
	v_add_u32_e32 v150, s5, v139
	v_mad_i64_i32 v[150:151], s[40:41], v150, s42, v[140:141]
	v_add_u32_e32 v139, s20, v139
	v_mad_u64_u32 v[152:153], s[40:41], v150, s17, v[132:133]
	v_mad_i64_i32 v[140:141], s[40:41], v139, s42, v[140:141]
	v_or_b32_e32 v139, 32, v138
	v_mad_i32_i24 v153, v151, s17, v153
	v_mad_u64_u32 v[150:151], s[40:41], v140, s17, v[132:133]
	v_mul_hi_i32 v140, v139, s51
	v_mad_i32_i24 v151, v141, s17, v151
	v_lshrrev_b32_e32 v141, 31, v140
	v_ashrrev_i32_e32 v140, 11, v140
	v_cvt_pk_bf16_f32 v146, v116, v117
	v_cvt_pk_bf16_f32 v147, v118, v119
	v_cvt_pk_bf16_f32 v148, v112, v113
	v_cvt_pk_bf16_f32 v149, v114, v115
	v_add_u32_e32 v141, v140, v141
	global_store_dwordx4 v[152:153], v[146:149], off
	v_mad_i32_i24 v140, v141, s29, v139
	v_lshlrev_b32_e32 v139, 3, v141
	v_cvt_pk_bf16_f32 v146, v84, v85
	v_cvt_pk_bf16_f32 v147, v86, v87
	v_cvt_pk_bf16_f32 v148, v80, v81
	v_cvt_pk_bf16_f32 v149, v82, v83
	global_store_dwordx4 v[150:151], v[146:149], off
	v_ashrrev_i32_e32 v141, 31, v140
	v_add_u32_e32 v150, s5, v139
	v_mad_i64_i32 v[150:151], s[40:41], v150, s42, v[140:141]
	v_add_u32_e32 v139, s20, v139
; DI u32x4 pack8v(const f32x4& a, const f32x4& b) { u32x4 w; w.x = pk2(a[0], a[1]); w.y = pk2(a[2], a[3]); w.z = pk2(b[0], b[1]); w.w = pk2(b[2], b[3]); return w; }
;   DI void operator()(const acc_t& acc, const Desc& u, int wr, int wc, int fr, int fq) const {
;     ...
;         for (int m = 0; m < 4; ++m) { const int tl = row0 + ai * HALF + m * 16, bl = tl / S, s = tl - bl * S;
; #pragma unroll
;           for (int bj = 0; bj < 2; ++bj) { const int c = u.pn * BM + bj * HALF + wc * 32 + 8 * fq, head = c >> 6, j = c & 63;
;             *(u32x4*)(Kb + ((size_t)(bl * 8 + head) * S + s) * 96 + j) = pack8v(acc[ai][bj][m][0], acc[ai][bj][m][1]); } }
	v_mad_u64_u32 v[152:153], s[40:41], v150, s17, v[132:133]
	v_mad_i64_i32 v[140:141], s[40:41], v139, s42, v[140:141]
	v_or_b32_e32 v139, 48, v138
	v_mad_i32_i24 v153, v151, s17, v153
	v_mad_u64_u32 v[150:151], s[40:41], v140, s17, v[132:133]
	v_mul_hi_i32 v140, v139, s51
	v_mad_i32_i24 v151, v141, s17, v151
	v_lshrrev_b32_e32 v141, 31, v140
	v_ashrrev_i32_e32 v140, 11, v140
	v_cvt_pk_bf16_f32 v146, v108, v109
	v_cvt_pk_bf16_f32 v147, v110, v111
	v_cvt_pk_bf16_f32 v148, v104, v105
	v_cvt_pk_bf16_f32 v149, v106, v107
	v_add_u32_e32 v141, v140, v141
	global_store_dwordx4 v[152:153], v[146:149], off
	v_mad_i32_i24 v140, v141, s29, v139
	v_lshlrev_b32_e32 v139, 3, v141
	v_cvt_pk_bf16_f32 v146, v76, v77
	v_cvt_pk_bf16_f32 v147, v78, v79
	v_cvt_pk_bf16_f32 v148, v72, v73
	v_cvt_pk_bf16_f32 v149, v74, v75
	global_store_dwordx4 v[150:151], v[146:149], off
	v_ashrrev_i32_e32 v141, 31, v140
	v_add_u32_e32 v150, s5, v139
	v_mad_i64_i32 v[150:151], s[40:41], v150, s42, v[140:141]
	v_add_u32_e32 v139, s20, v139
	v_mad_u64_u32 v[152:153], s[40:41], v150, s17, v[132:133]
	v_mad_i64_i32 v[140:141], s[40:41], v139, s42, v[140:141]
	v_add_u32_e32 v139, 0x80, v138
	v_mad_i32_i24 v153, v151, s17, v153
	v_mad_u64_u32 v[150:151], s[40:41], v140, s17, v[132:133]
	v_mul_hi_i32 v140, v139, s51
	v_mad_i32_i24 v151, v141, s17, v151
	v_lshrrev_b32_e32 v141, 31, v140
	v_ashrrev_i32_e32 v140, 11, v140
	v_cvt_pk_bf16_f32 v146, v100, v101
	v_cvt_pk_bf16_f32 v147, v102, v103
	v_cvt_pk_bf16_f32 v148, v92, v93
	v_cvt_pk_bf16_f32 v149, v94, v95
	v_add_u32_e32 v141, v140, v141
	global_store_dwordx4 v[152:153], v[146:149], off
	v_mad_i32_i24 v140, v141, s29, v139
	v_lshlrev_b32_e32 v139, 3, v141
	v_cvt_pk_bf16_f32 v146, v68, v69
	v_cvt_pk_bf16_f32 v147, v70, v71
	v_cvt_pk_bf16_f32 v148, v64, v65
	v_cvt_pk_bf16_f32 v149, v66, v67
	global_store_dwordx4 v[150:151], v[146:149], off
	v_ashrrev_i32_e32 v141, 31, v140
	v_add_u32_e32 v150, s5, v139
	v_mad_i64_i32 v[150:151], s[40:41], v150, s42, v[140:141]
	v_add_u32_e32 v139, s20, v139
	v_mad_u64_u32 v[152:153], s[40:41], v150, s17, v[132:133]
	v_mad_i64_i32 v[140:141], s[40:41], v139, s42, v[140:141]
	v_add_u32_e32 v139, 0x90, v138
	v_mad_i32_i24 v153, v151, s17, v153
	v_mad_u64_u32 v[150:151], s[40:41], v140, s17, v[132:133]
	v_mul_hi_i32 v140, v139, s51
	v_mad_i32_i24 v151, v141, s17, v151
	v_lshrrev_b32_e32 v141, 31, v140
	v_ashrrev_i32_e32 v140, 11, v140
	v_cvt_pk_bf16_f32 v146, v60, v61
	v_cvt_pk_bf16_f32 v147, v62, v63
	v_cvt_pk_bf16_f32 v148, v56, v57
	v_cvt_pk_bf16_f32 v149, v58, v59
	v_add_u32_e32 v141, v140, v141
	global_store_dwordx4 v[152:153], v[146:149], off
	v_mad_i32_i24 v140, v141, s29, v139
	v_lshlrev_b32_e32 v139, 3, v141
	v_cvt_pk_bf16_f32 v146, v36, v37
	v_cvt_pk_bf16_f32 v147, v38, v39
	v_cvt_pk_bf16_f32 v148, v28, v29
	v_cvt_pk_bf16_f32 v149, v30, v31
	global_store_dwordx4 v[150:151], v[146:149], off
	v_ashrrev_i32_e32 v141, 31, v140
	v_add_u32_e32 v150, s5, v139
	v_mad_i64_i32 v[150:151], s[40:41], v150, s42, v[140:141]
	v_add_u32_e32 v139, s20, v139
	v_mad_u64_u32 v[152:153], s[40:41], v150, s17, v[132:133]
	v_mad_i64_i32 v[140:141], s[40:41], v139, s42, v[140:141]
	v_add_u32_e32 v139, 0xa0, v138
	v_mad_i32_i24 v153, v151, s17, v153
	v_mad_u64_u32 v[150:151], s[40:41], v140, s17, v[132:133]
	v_mul_hi_i32 v140, v139, s51
	v_mad_i32_i24 v151, v141, s17, v151
	v_lshrrev_b32_e32 v141, 31, v140
	v_ashrrev_i32_e32 v140, 11, v140
	v_cvt_pk_bf16_f32 v146, v52, v53
	v_cvt_pk_bf16_f32 v147, v54, v55
	v_cvt_pk_bf16_f32 v148, v48, v49
	v_cvt_pk_bf16_f32 v149, v50, v51
	v_add_u32_e32 v141, v140, v141
	global_store_dwordx4 v[152:153], v[146:149], off
	v_mad_i32_i24 v140, v141, s29, v139
	v_lshlrev_b32_e32 v139, 3, v141
	v_cvt_pk_bf16_f32 v146, v20, v21
	v_cvt_pk_bf16_f32 v147, v22, v23
	v_cvt_pk_bf16_f32 v148, v16, v17
	v_cvt_pk_bf16_f32 v149, v18, v19
	global_store_dwordx4 v[150:151], v[146:149], off
	v_ashrrev_i32_e32 v141, 31, v140
	v_add_u32_e32 v150, s5, v139
	v_mad_i64_i32 v[150:151], s[40:41], v150, s42, v[140:141]
	v_add_u32_e32 v139, s20, v139
	v_mad_u64_u32 v[152:153], s[40:41], v150, s17, v[132:133]
	v_mad_i64_i32 v[140:141], s[40:41], v139, s42, v[140:141]
	v_add_u32_e32 v139, 0xb0, v138
	v_mad_i32_i24 v153, v151, s17, v153
	v_mad_u64_u32 v[150:151], s[40:41], v140, s17, v[132:133]
	v_mul_hi_i32 v140, v139, s51
	v_mad_i32_i24 v151, v141, s17, v151
	v_lshrrev_b32_e32 v141, 31, v140
	v_ashrrev_i32_e32 v140, 11, v140
	v_cvt_pk_bf16_f32 v146, v44, v45
	v_cvt_pk_bf16_f32 v147, v46, v47
	v_cvt_pk_bf16_f32 v148, v40, v41
	v_cvt_pk_bf16_f32 v149, v42, v43
	v_add_u32_e32 v141, v140, v141
	global_store_dwordx4 v[152:153], v[146:149], off
	v_mad_i32_i24 v140, v141, s29, v139
	v_lshlrev_b32_e32 v139, 3, v141
	v_cvt_pk_bf16_f32 v146, v12, v13
	v_cvt_pk_bf16_f32 v147, v14, v15
	v_cvt_pk_bf16_f32 v148, v8, v9
	v_cvt_pk_bf16_f32 v149, v10, v11
	global_store_dwordx4 v[150:151], v[146:149], off
	v_ashrrev_i32_e32 v141, 31, v140
	v_add_u32_e32 v150, s5, v139
	v_mad_i64_i32 v[150:151], s[40:41], v150, s42, v[140:141]
	v_add_u32_e32 v139, s20, v139
	v_mad_u64_u32 v[152:153], s[40:41], v150, s17, v[132:133]
	v_mad_i64_i32 v[140:141], s[40:41], v139, s42, v[140:141]
	v_cvt_pk_bf16_f32 v146, v32, v33
	v_cvt_pk_bf16_f32 v147, v34, v35
	v_cvt_pk_bf16_f32 v148, v24, v25
	v_cvt_pk_bf16_f32 v149, v26, v27
	v_mad_i32_i24 v153, v151, s17, v153
	v_mad_u64_u32 v[150:151], s[40:41], v140, s17, v[132:133]
	global_store_dwordx4 v[152:153], v[146:149], off
	v_mad_i32_i24 v151, v141, s17, v151
	s_movk_i32 s80, 0xef00
	v_cvt_pk_bf16_f32 v146, v4, v5
	v_cvt_pk_bf16_f32 v147, v6, v7
	v_cvt_pk_bf16_f32 v148, v0, v1
	v_cvt_pk_bf16_f32 v149, v2, v3
	global_store_dwordx4 v[150:151], v[146:149], off
	s_mov_b64 s[40:41], 0

; #define PG8_LDA(dst, b, h) do { _Pragma("unroll") for (int m = 0; m < 4; ++m) _Pragma("unroll") for (int k = 0; k < 2; ++k) dst[m][k] = *(const LAS bf16x8*)(lds + PG8_SA(b, h) + aoff + m * 2048 + k * 1024); } while (0)
; #define PG8_LDB(dst, b, h) do { _Pragma("unroll") for (int n = 0; n < 2; ++n) _Pragma("unroll") for (int k = 0; k < 2; ++k) dst[n][k] = *(const LAS bf16x8*)(lds + PG8_SB(b, h) + boff + n * 2048 + k * 1024); } while (0)
; #define PG8_MMA(ai, bj, At, Bt_) do { __builtin_amdgcn_s_setprio(1); _Pragma("unroll") for (int m = 0; m < 4; ++m) _Pragma("unroll") for (int n = 0; n < 2; ++n) _Pragma("unroll") for (int k = 0; k < 2; ++k) \
;     acc[ai][bj][m][n] = __builtin_amdgcn_mfma_f32_16x16x32_bf16(Bt_[n][k], At[m][k], acc[ai][bj][m][n], 0, 0, 0); __builtin_amdgcn_s_setprio(0); } while (0)
; #define PG8_WAIT_V(n) asm volatile("s_waitcnt vmcnt(" #n ")" ::: "memory")
; #define PG8_WAIT_L(n) asm volatile("s_waitcnt lgkmcnt(" #n ")" ::: "memory")
; #define PG8_BAR __builtin_amdgcn_s_barrier()
; #define PG8_SCHED __builtin_amdgcn_sched_barrier(0)
; #define PG8_STA(bufoff, gbase, ld2) PG8_STAGE3(bufoff, gbase, ld2, R0, R1)
; #define PG8_STB(bufoff, gbase, ld2) PG8_STAGE3(bufoff, gbase, ld2, Rb0, Rb1)
; #define PG8_BAR __builtin_amdgcn_s_barrier()
; template <class Sched, class Epi>
; DI void gemm_stream(char* smem, const Sched& S_, const Epi& E) {
;     ...
;       const bool last = (t == nt - 2);
;       const char* a1 = cA + (size_t)(t + 1) * kstep;
;       const char* a2 = last ? nA : cA + (size_t)(t + 2) * kstep; const char* b2 = last ? nB : cB + (size_t)(t + 2) * kstep;
;       const char* a3 = a2 + kstep; const char* b3 = b2 + kstep;
;       const int xa2 = (last ? nxt.lda : cur.lda) * 2, xb2 = (last ? nxt.ldb : cur.ldb) * 2;
;       const size_t xhA = (size_t)HALF * xa2, xhB = (size_t)HALF * xb2;
;       PG8_LDB(B0, 0, 0); PG8_SCHED; PG8_LDA(At, 0, 0); PG8_STA(PG8_SA(1, 1), a1 + hA, la2);
;       PG8_WAIT_L(8); PG8_BAR; PG8_WAIT_L(0); PG8_MMA(0, 0, At, B0); PG8_BAR; PG8_SCHED;
;       PG8_LDB(B1, 0, 1); PG8_STB(PG8_SB(0, 0), b2, xb2);
;       PG8_BAR; PG8_WAIT_L(0); PG8_MMA(0, 1, At, B1); PG8_BAR;
;       PG8_LDA(At, 0, 1); PG8_STA(PG8_SA(0, 0), a2, xa2);
;       PG8_BAR; PG8_WAIT_L(0); PG8_MMA(1, 0, At, B0); PG8_BAR; PG8_SCHED;
;       PG8_STB(PG8_SB(0, 1), b2 + xhB, xb2);
;       PG8_WAIT_V(6); PG8_BAR; PG8_MMA(1, 1, At, B1); PG8_BAR;
.LBB0_1166:
	s_add_i32 s53, s46, 2
	s_add_u32 s50, s44, 0x80
	s_addc_u32 s47, s45, 0
	s_cmp_eq_u32 s62, s46
	s_cselect_b32 s47, s41, s47
	s_cselect_b32 s46, s40, s50
	s_cselect_b32 s50, s13, s20
	s_cselect_b32 s51, s3, s16
	s_cselect_b32 s89, s1, s52
	s_cselect_b32 s88, s0, s63
	s_add_i32 s64, 0, 0x10000
	v_add_u32_e32 v144, s64, v239
	ds_read_b128 v[132:135], v144
	ds_read_b128 v[136:139], v144 offset:1024
	ds_read_b128 v[140:143], v144 offset:2048
	ds_read_b128 v[144:147], v144 offset:3072
	s_lshl_b32 vcc_lo, s50, 1
	s_lshl_b32 s90, s51, 1
	s_ashr_i32 vcc_hi, vcc_lo, 31
	s_ashr_i32 s91, s90, 31
	s_lshl_b64 s[50:51], vcc, 7
	v_lshl_add_u64 v[180:181], s[44:45], 0, v[128:129]
	s_add_i32 m0, s39, 0xc000
	ds_read_b128 v[148:151], v241
	ds_read_b128 v[152:155], v241 offset:1024
	ds_read_b128 v[156:159], v241 offset:2048
	ds_read_b128 v[160:163], v241 offset:3072
	ds_read_b128 v[164:167], v241 offset:4096
	ds_read_b128 v[168:171], v241 offset:5120
	ds_read_b128 v[172:175], v241 offset:6144
	ds_read_b128 v[176:179], v241 offset:7168
	global_load_lds_dwordx4 v[180:181], off
	v_lshl_add_u64 v[180:181], s[44:45], 0, v[130:131]
	s_add_i32 m0, s39, 0xe000
	s_nop 0
	global_load_lds_dwordx4 v[180:181], off
	s_waitcnt lgkmcnt(8)
	s_barrier
	s_waitcnt lgkmcnt(0)
	s_setprio 1
	v_mfma_f32_16x16x32_bf16 v[124:127], v[132:135], v[148:151], v[124:127]
	v_mfma_f32_16x16x32_bf16 v[120:123], v[140:143], v[148:151], v[120:123]
	v_mfma_f32_16x16x32_bf16 v[116:119], v[132:135], v[156:159], v[116:119]
	v_mfma_f32_16x16x32_bf16 v[112:115], v[140:143], v[156:159], v[112:115]
	v_mfma_f32_16x16x32_bf16 v[100:103], v[132:135], v[164:167], v[100:103]
	v_mfma_f32_16x16x32_bf16 v[96:99], v[140:143], v[164:167], v[96:99]
	v_mfma_f32_16x16x32_bf16 v[84:87], v[132:135], v[172:175], v[84:87]
	v_mfma_f32_16x16x32_bf16 v[80:83], v[140:143], v[172:175], v[80:83]
	v_mfma_f32_16x16x32_bf16 v[124:127], v[136:139], v[152:155], v[124:127]
	v_mfma_f32_16x16x32_bf16 v[120:123], v[144:147], v[152:155], v[120:123]
	v_mfma_f32_16x16x32_bf16 v[116:119], v[136:139], v[160:163], v[116:119]
	v_mfma_f32_16x16x32_bf16 v[112:115], v[144:147], v[160:163], v[112:115]
	v_mfma_f32_16x16x32_bf16 v[100:103], v[136:139], v[168:171], v[100:103]
	v_mfma_f32_16x16x32_bf16 v[96:99], v[144:147], v[168:171], v[96:99]
	v_mfma_f32_16x16x32_bf16 v[84:87], v[136:139], v[176:179], v[84:87]
	v_mfma_f32_16x16x32_bf16 v[80:83], v[144:147], v[176:179], v[80:83]
	s_setprio 0
	s_barrier
	s_add_i32 s65, 0, 0x14000
	s_add_i32 s64, s64, s60
	v_add_u32_e32 v195, s65, v239
	v_mad_u64_u32 v[200:201], s[56:57], s90, v236, v[204:205]
	s_mov_b32 m0, s64
	ds_read_b128 v[180:183], v195
	ds_read_b128 v[184:187], v195 offset:1024
	ds_read_b128 v[188:191], v195 offset:2048
	ds_read_b128 v[210:213], v195 offset:3072
	global_load_lds_dwordx4 v200, s[88:89]
	v_mad_u64_u32 v[202:203], s[56:57], s90, v237, v[206:207]
	s_add_i32 m0, s64, 0x2000
	v_mov_b32_e32 v201, v221
	global_load_lds_dwordx4 v202, s[88:89]
	s_barrier
	s_waitcnt lgkmcnt(0)
	v_mov_b32_e32 v203, v221
	v_lshl_add_u64 v[214:215], s[88:89], 0, v[200:201]
	v_lshl_add_u64 v[216:217], s[88:89], 0, v[202:203]
	s_setprio 1
	s_waitcnt lgkmcnt(0)
	v_mfma_f32_16x16x32_bf16 v[108:111], v[180:183], v[148:151], v[108:111]
	v_mfma_f32_16x16x32_bf16 v[104:107], v[188:191], v[148:151], v[104:107]
	v_mfma_f32_16x16x32_bf16 v[92:95], v[180:183], v[156:159], v[92:95]
	v_mfma_f32_16x16x32_bf16 v[88:91], v[188:191], v[156:159], v[88:91]
	v_mfma_f32_16x16x32_bf16 v[76:79], v[180:183], v[164:167], v[76:79]
	v_mfma_f32_16x16x32_bf16 v[72:75], v[188:191], v[164:167], v[72:75]
	v_mfma_f32_16x16x32_bf16 v[68:71], v[180:183], v[172:175], v[68:71]
	v_mfma_f32_16x16x32_bf16 v[64:67], v[188:191], v[172:175], v[64:67]
	v_mfma_f32_16x16x32_bf16 v[108:111], v[184:187], v[152:155], v[108:111]
	v_mfma_f32_16x16x32_bf16 v[104:107], v[210:213], v[152:155], v[104:107]
	v_mfma_f32_16x16x32_bf16 v[92:95], v[184:187], v[160:163], v[92:95]
	v_mfma_f32_16x16x32_bf16 v[88:91], v[210:213], v[160:163], v[88:91]
	v_mfma_f32_16x16x32_bf16 v[76:79], v[184:187], v[168:171], v[76:79]
	v_mfma_f32_16x16x32_bf16 v[72:75], v[210:213], v[168:171], v[72:75]
	v_mfma_f32_16x16x32_bf16 v[68:71], v[184:187], v[176:179], v[68:71]
	v_mfma_f32_16x16x32_bf16 v[64:67], v[210:213], v[176:179], v[64:67]
	s_setprio 0
	s_mov_b32 m0, s39
	v_mad_u64_u32 v[218:219], s[56:57], vcc_lo, v234, v[204:205]
	s_barrier
	ds_read_b128 v[148:151], v241 offset:16384
	ds_read_b128 v[152:155], v241 offset:17408
	ds_read_b128 v[156:159], v241 offset:18432
	ds_read_b128 v[160:163], v241 offset:19456
	ds_read_b128 v[164:167], v241 offset:20480
	ds_read_b128 v[168:171], v241 offset:21504
	ds_read_b128 v[172:175], v241 offset:22528
	ds_read_b128 v[176:179], v241 offset:23552
	global_load_lds_dwordx4 v218, s[46:47]
	v_mad_u64_u32 v[222:223], s[56:57], vcc_lo, v235, v[206:207]
	s_mov_b32 m0, s38
	v_mov_b32_e32 v219, v221
	global_load_lds_dwordx4 v222, s[46:47]
	s_barrier
	s_waitcnt lgkmcnt(0)
	v_mov_b32_e32 v223, v221
	v_lshl_add_u64 v[242:243], s[46:47], 0, v[218:219]
	v_lshl_add_u64 v[244:245], s[46:47], 0, v[222:223]
	s_setprio 1
	s_waitcnt lgkmcnt(0)
	v_mfma_f32_16x16x32_bf16 v[60:63], v[132:135], v[148:151], v[60:63]
	s_lshl_b64 s[56:57], s[90:91], 7
	v_mfma_f32_16x16x32_bf16 v[56:59], v[140:143], v[148:151], v[56:59]
	v_mfma_f32_16x16x32_bf16 v[52:55], v[132:135], v[156:159], v[52:55]
	v_mfma_f32_16x16x32_bf16 v[48:51], v[140:143], v[156:159], v[48:51]
	v_mfma_f32_16x16x32_bf16 v[36:39], v[132:135], v[164:167], v[36:39]
	v_mfma_f32_16x16x32_bf16 v[32:35], v[140:143], v[164:167], v[32:35]
	v_mfma_f32_16x16x32_bf16 v[20:23], v[132:135], v[172:175], v[20:23]
	v_mfma_f32_16x16x32_bf16 v[16:19], v[140:143], v[172:175], v[16:19]
	v_mfma_f32_16x16x32_bf16 v[60:63], v[136:139], v[152:155], v[60:63]
	v_mfma_f32_16x16x32_bf16 v[56:59], v[144:147], v[152:155], v[56:59]
	v_mfma_f32_16x16x32_bf16 v[52:55], v[136:139], v[160:163], v[52:55]
	v_mfma_f32_16x16x32_bf16 v[48:51], v[144:147], v[160:163], v[48:51]
	v_mfma_f32_16x16x32_bf16 v[36:39], v[136:139], v[168:171], v[36:39]
	v_mfma_f32_16x16x32_bf16 v[32:35], v[144:147], v[168:171], v[32:35]
	v_mfma_f32_16x16x32_bf16 v[20:23], v[136:139], v[176:179], v[20:23]
	v_mfma_f32_16x16x32_bf16 v[16:19], v[144:147], v[176:179], v[16:19]
	s_setprio 0
	s_barrier
; #define PG8_LDA(dst, b, h) do { _Pragma("unroll") for (int m = 0; m < 4; ++m) _Pragma("unroll") for (int k = 0; k < 2; ++k) dst[m][k] = *(const LAS bf16x8*)(lds + PG8_SA(b, h) + aoff + m * 2048 + k * 1024); } while (0)
; #define PG8_LDB(dst, b, h) do { _Pragma("unroll") for (int n = 0; n < 2; ++n) _Pragma("unroll") for (int k = 0; k < 2; ++k) dst[n][k] = *(const LAS bf16x8*)(lds + PG8_SB(b, h) + boff + n * 2048 + k * 1024); } while (0)
; #define PG8_MMA(ai, bj, At, Bt_) do { __builtin_amdgcn_s_setprio(1); _Pragma("unroll") for (int m = 0; m < 4; ++m) _Pragma("unroll") for (int n = 0; n < 2; ++n) _Pragma("unroll") for (int k = 0; k < 2; ++k) \
;     acc[ai][bj][m][n] = __builtin_amdgcn_mfma_f32_16x16x32_bf16(Bt_[n][k], At[m][k], acc[ai][bj][m][n], 0, 0, 0); __builtin_amdgcn_s_setprio(0); } while (0)
; #define PG8_WAIT_V(n) asm volatile("s_waitcnt vmcnt(" #n ")" ::: "memory")
; #define PG8_WAIT_L(n) asm volatile("s_waitcnt lgkmcnt(" #n ")" ::: "memory")
; #define PG8_BAR __builtin_amdgcn_s_barrier()
; #define PG8_SCHED __builtin_amdgcn_sched_barrier(0)
; #define PG8_STA(bufoff, gbase, ld2) PG8_STAGE3(bufoff, gbase, ld2, R0, R1)
; #define PG8_STB(bufoff, gbase, ld2) PG8_STAGE3(bufoff, gbase, ld2, Rb0, Rb1)
; #define PG8_LDA(dst, b, h) do { _Pragma("unroll") for (int m = 0; m < 4; ++m) _Pragma("unroll") for (int k = 0; k < 2; ++k) dst[m][k] = *(const LAS bf16x8*)(lds + PG8_SA(b, h) + aoff + m * 2048 + k * 1024); } while (0)
; #define PG8_LDB(dst, b, h) do { _Pragma("unroll") for (int n = 0; n < 2; ++n) _Pragma("unroll") for (int k = 0; k < 2; ++k) dst[n][k] = *(const LAS bf16x8*)(lds + PG8_SB(b, h) + boff + n * 2048 + k * 1024); } while (0)
; #define PG8_WAIT_V(n) asm volatile("s_waitcnt vmcnt(" #n ")" ::: "memory")
; template <class Sched, class Epi>
; DI void gemm_stream(char* smem, const Sched& S_, const Epi& E) {
;     ...
;       PG8_STB(PG8_SB(0, 1), b2 + xhB, xb2);
;       PG8_WAIT_V(6); PG8_BAR; PG8_MMA(1, 1, At, B1); PG8_BAR;
;       PG8_LDB(B0, 1, 0); PG8_SCHED; PG8_LDA(At, 1, 0); PG8_STA(PG8_SA(0, 1), a2 + xhA, xa2);
;       PG8_WAIT_L(8); PG8_BAR; PG8_WAIT_L(0); PG8_MMA(0, 0, At, B0); PG8_BAR; PG8_SCHED;
;       PG8_LDB(B1, 1, 1); PG8_STB(PG8_SB(1, 0), b3, xb2);
;       PG8_BAR; PG8_WAIT_L(0); PG8_MMA(0, 1, At, B1); PG8_BAR;
;       PG8_LDA(At, 1, 1); PG8_STA(PG8_SA(1, 0), a3, xa2);
;       PG8_BAR; PG8_WAIT_L(0); PG8_MMA(1, 0, At, B0); PG8_BAR; PG8_SCHED;
	s_add_u32 s56, s88, s56
	s_addc_u32 s57, s89, s57
	s_add_i32 s64, s65, s60
	s_mov_b32 m0, s64
	s_nop 0
	global_load_lds_dwordx4 v200, s[56:57]
	s_add_i32 m0, s64, 0x2000
	v_lshl_add_u64 v[200:201], s[56:57], 0, v[200:201]
	global_load_lds_dwordx4 v202, s[56:57]
	s_waitcnt vmcnt(6)
	v_lshl_add_u64 v[202:203], s[56:57], 0, v[202:203]
	s_barrier
	s_setprio 1
	v_mfma_f32_16x16x32_bf16 v[44:47], v[180:183], v[148:151], v[44:47]
	v_mfma_f32_16x16x32_bf16 v[40:43], v[188:191], v[148:151], v[40:43]
	v_mfma_f32_16x16x32_bf16 v[28:31], v[180:183], v[156:159], v[28:31]
	v_mfma_f32_16x16x32_bf16 v[24:27], v[188:191], v[156:159], v[24:27]
	v_mfma_f32_16x16x32_bf16 v[12:15], v[180:183], v[164:167], v[12:15]
	v_mfma_f32_16x16x32_bf16 v[8:11], v[188:191], v[164:167], v[8:11]
	v_mfma_f32_16x16x32_bf16 v[4:7], v[180:183], v[172:175], v[4:7]
	v_mfma_f32_16x16x32_bf16 v[0:3], v[188:191], v[172:175], v[0:3]
	v_mfma_f32_16x16x32_bf16 v[44:47], v[184:187], v[152:155], v[44:47]
	v_mfma_f32_16x16x32_bf16 v[40:43], v[210:213], v[152:155], v[40:43]
	v_mfma_f32_16x16x32_bf16 v[28:31], v[184:187], v[160:163], v[28:31]
	v_mfma_f32_16x16x32_bf16 v[24:27], v[210:213], v[160:163], v[24:27]
	v_mfma_f32_16x16x32_bf16 v[12:15], v[184:187], v[168:171], v[12:15]
	v_mfma_f32_16x16x32_bf16 v[8:11], v[210:213], v[168:171], v[8:11]
	v_mfma_f32_16x16x32_bf16 v[4:7], v[184:187], v[176:179], v[4:7]
	v_mfma_f32_16x16x32_bf16 v[0:3], v[210:213], v[176:179], v[0:3]
	s_setprio 0
	s_add_i32 s56, 0, 0x18000
	v_add_u32_e32 v144, s56, v239
	s_barrier
	ds_read_b128 v[132:135], v144
	ds_read_b128 v[136:139], v144 offset:1024
	ds_read_b128 v[140:143], v144 offset:2048
	ds_read_b128 v[144:147], v144 offset:3072
	s_add_u32 s46, s46, s50
	s_addc_u32 s47, s47, s51
	s_mov_b32 m0, s9
	ds_read_b128 v[148:151], v241 offset:32768
	ds_read_b128 v[152:155], v241 offset:33792
	ds_read_b128 v[156:159], v241 offset:34816
	ds_read_b128 v[160:163], v241 offset:35840
	ds_read_b128 v[164:167], v241 offset:36864
	ds_read_b128 v[168:171], v241 offset:37888
	ds_read_b128 v[172:175], v241 offset:38912
	ds_read_b128 v[176:179], v241 offset:39936
	global_load_lds_dwordx4 v218, s[46:47]
	s_mov_b32 m0, s26
	s_nop 0
	global_load_lds_dwordx4 v222, s[46:47]
	s_waitcnt lgkmcnt(8)
	s_barrier
	s_waitcnt lgkmcnt(0)
	s_setprio 1
	v_mfma_f32_16x16x32_bf16 v[124:127], v[132:135], v[148:151], v[124:127]
	v_mfma_f32_16x16x32_bf16 v[120:123], v[140:143], v[148:151], v[120:123]
	v_mfma_f32_16x16x32_bf16 v[116:119], v[132:135], v[156:159], v[116:119]
	v_mfma_f32_16x16x32_bf16 v[112:115], v[140:143], v[156:159], v[112:115]
	v_mfma_f32_16x16x32_bf16 v[100:103], v[132:135], v[164:167], v[100:103]
	v_mfma_f32_16x16x32_bf16 v[96:99], v[140:143], v[164:167], v[96:99]
	v_mfma_f32_16x16x32_bf16 v[84:87], v[132:135], v[172:175], v[84:87]
	v_mfma_f32_16x16x32_bf16 v[80:83], v[140:143], v[172:175], v[80:83]
	v_mfma_f32_16x16x32_bf16 v[124:127], v[136:139], v[152:155], v[124:127]
	v_mfma_f32_16x16x32_bf16 v[120:123], v[144:147], v[152:155], v[120:123]
	v_mfma_f32_16x16x32_bf16 v[116:119], v[136:139], v[160:163], v[116:119]
	v_mfma_f32_16x16x32_bf16 v[112:115], v[144:147], v[160:163], v[112:115]
	v_mfma_f32_16x16x32_bf16 v[100:103], v[136:139], v[168:171], v[100:103]
	v_mfma_f32_16x16x32_bf16 v[96:99], v[144:147], v[168:171], v[96:99]
	v_mfma_f32_16x16x32_bf16 v[84:87], v[136:139], v[176:179], v[84:87]
	v_mfma_f32_16x16x32_bf16 v[80:83], v[144:147], v[176:179], v[80:83]
	s_setprio 0
	s_barrier
	s_add_i32 s46, 0, 0x1c000
	s_add_i32 s47, s56, s60
	v_add_u32_e32 v195, s46, v239
	v_lshl_add_u64 v[214:215], v[214:215], 0, s[58:59]
	s_mov_b32 m0, s47
	ds_read_b128 v[180:183], v195
	ds_read_b128 v[184:187], v195 offset:1024
	ds_read_b128 v[188:191], v195 offset:2048
	ds_read_b128 v[210:213], v195 offset:3072
	global_load_lds_dwordx4 v[214:215], off
	v_lshl_add_u64 v[214:215], v[216:217], 0, s[58:59]
	s_add_i32 m0, s47, 0x2000
	s_nop 0
	global_load_lds_dwordx4 v[214:215], off
	s_barrier
	s_waitcnt lgkmcnt(0)
	s_setprio 1
	v_mfma_f32_16x16x32_bf16 v[108:111], v[180:183], v[148:151], v[108:111]
	v_mfma_f32_16x16x32_bf16 v[104:107], v[188:191], v[148:151], v[104:107]
	v_mfma_f32_16x16x32_bf16 v[92:95], v[180:183], v[156:159], v[92:95]
	v_mfma_f32_16x16x32_bf16 v[88:91], v[188:191], v[156:159], v[88:91]
	v_mfma_f32_16x16x32_bf16 v[76:79], v[180:183], v[164:167], v[76:79]
	v_mfma_f32_16x16x32_bf16 v[72:75], v[188:191], v[164:167], v[72:75]
	v_mfma_f32_16x16x32_bf16 v[68:71], v[180:183], v[172:175], v[68:71]
	v_mfma_f32_16x16x32_bf16 v[64:67], v[188:191], v[172:175], v[64:67]
	v_mfma_f32_16x16x32_bf16 v[108:111], v[184:187], v[152:155], v[108:111]
	v_mfma_f32_16x16x32_bf16 v[104:107], v[210:213], v[152:155], v[104:107]
	v_mfma_f32_16x16x32_bf16 v[92:95], v[184:187], v[160:163], v[92:95]
	v_mfma_f32_16x16x32_bf16 v[88:91], v[210:213], v[160:163], v[88:91]
	v_mfma_f32_16x16x32_bf16 v[76:79], v[184:187], v[168:171], v[76:79]
	v_mfma_f32_16x16x32_bf16 v[72:75], v[210:213], v[168:171], v[72:75]
	v_mfma_f32_16x16x32_bf16 v[68:71], v[184:187], v[176:179], v[68:71]
	v_mfma_f32_16x16x32_bf16 v[64:67], v[210:213], v[176:179], v[64:67]
	s_setprio 0
	s_mov_b32 m0, s27
	v_lshl_add_u64 v[214:215], v[242:243], 0, s[58:59]
	s_barrier
; DI int get_tid() { int t = threadIdx.x; asm volatile("" : "+v"(t)); return t; }
; #define MEMBAR() asm volatile("" ::: "memory")
; #define PG8_LDA(dst, b, h) do { _Pragma("unroll") for (int m = 0; m < 4; ++m) _Pragma("unroll") for (int k = 0; k < 2; ++k) dst[m][k] = *(const LAS bf16x8*)(lds + PG8_SA(b, h) + aoff + m * 2048 + k * 1024); } while (0)
; #define PG8_LDB(dst, b, h) do { _Pragma("unroll") for (int n = 0; n < 2; ++n) _Pragma("unroll") for (int k = 0; k < 2; ++k) dst[n][k] = *(const LAS bf16x8*)(lds + PG8_SB(b, h) + boff + n * 2048 + k * 1024); } while (0)
; #define PG8_BAR __builtin_amdgcn_s_barrier()
; template <class Sched, class Epi>
; DI void gemm_stream(char* smem, const Sched& S_, const Epi& E) {
;     ...
;       PG8_STB(PG8_SB(0, 1), b2 + xhB, xb2);
;       PG8_WAIT_V(6); PG8_BAR; PG8_MMA(1, 1, At, B1); PG8_BAR;
;       PG8_LDB(B0, 1, 0); PG8_SCHED; PG8_LDA(At, 1, 0); PG8_STA(PG8_SA(0, 1), a2 + xhA, xa2);
;       PG8_WAIT_L(8); PG8_BAR; PG8_WAIT_L(0); PG8_MMA(0, 0, At, B0); PG8_BAR; PG8_SCHED;
;       PG8_LDB(B1, 1, 1); PG8_STB(PG8_SB(1, 0), b3, xb2);
;       PG8_BAR; PG8_WAIT_L(0); PG8_MMA(0, 1, At, B1); PG8_BAR;
;       PG8_LDA(At, 1, 1); PG8_STA(PG8_SA(1, 0), a3, xa2);
;       PG8_BAR; PG8_WAIT_L(0); PG8_MMA(1, 0, At, B0); PG8_BAR; PG8_SCHED;
;       PG8_STB(PG8_SB(1, 1), b3 + xhB, xb2);
;       PG8_WAIT_V(6); PG8_BAR; PG8_MMA(1, 1, At, B1); PG8_BAR;
;   DI void operator()(const acc_t& acc, const Desc& u, int wr, int wc, int fr, int fq) const {
;     u32x4* sp = slab + get_tid(); asm volatile("" : "+v"(sp));
;     if (!(u.kind & 1)) {
; #pragma unroll
;       for (int ai = 0; ai < 2; ++ai)
; #pragma unroll
;         for (int m = 0; m < 4; ++m)
; #pragma unroll
;           for (int bj = 0; bj < 2; ++bj) sp[((ai * 4 + m) * 2 + bj) * 512] = pack8v(acc[ai][bj][m][0], acc[ai][bj][m][1]);
;     } else {
;       const int first = u.kind == 1, lastx = u.kind == 5;
;       const int row0 = u.pm * BM + wr * 64 + fr, col0 = u.pn * BM + wc * 32 + 8 * fq;
; #pragma unroll
;       for (int ai = 0; ai < 2; ++ai) {
;         MEMBAR();
;         u32x4 pv[4][2], mv[4][2];
; #pragma unroll
;         for (int m = 0; m < 4; ++m)
; #pragma unroll
;           for (int bj = 0; bj < 2; ++bj) {
;             pv[m][bj] = sp[((ai * 4 + m) * 2 + bj) * 512];
;             if (!first) mv[m][bj] = sp[(16 + (ai * 4 + m) * 2 + bj) * 512];
;           }
	ds_read_b128 v[148:151], v241 offset:49152
	ds_read_b128 v[152:155], v241 offset:50176
	ds_read_b128 v[156:159], v241 offset:51200
	ds_read_b128 v[160:163], v241 offset:52224
	ds_read_b128 v[164:167], v241 offset:53248
	ds_read_b128 v[168:171], v241 offset:54272
	ds_read_b128 v[172:175], v241 offset:55296
	ds_read_b128 v[176:179], v241 offset:56320
	global_load_lds_dwordx4 v[214:215], off
	v_lshl_add_u64 v[214:215], v[244:245], 0, s[58:59]
	s_mov_b32 m0, s33
	s_nop 0
	global_load_lds_dwordx4 v[214:215], off
	s_barrier
	s_waitcnt lgkmcnt(0)
	s_setprio 1
	v_mfma_f32_16x16x32_bf16 v[60:63], v[132:135], v[148:151], v[60:63]
	v_mfma_f32_16x16x32_bf16 v[56:59], v[140:143], v[148:151], v[56:59]
	v_mfma_f32_16x16x32_bf16 v[52:55], v[132:135], v[156:159], v[52:55]
	v_mfma_f32_16x16x32_bf16 v[48:51], v[140:143], v[156:159], v[48:51]
	v_mfma_f32_16x16x32_bf16 v[36:39], v[132:135], v[164:167], v[36:39]
	v_mfma_f32_16x16x32_bf16 v[32:35], v[140:143], v[164:167], v[32:35]
	v_mfma_f32_16x16x32_bf16 v[20:23], v[132:135], v[172:175], v[20:23]
	v_mfma_f32_16x16x32_bf16 v[16:19], v[140:143], v[172:175], v[16:19]
	v_mfma_f32_16x16x32_bf16 v[60:63], v[136:139], v[152:155], v[60:63]
	v_mfma_f32_16x16x32_bf16 v[56:59], v[144:147], v[152:155], v[56:59]
	v_mfma_f32_16x16x32_bf16 v[52:55], v[136:139], v[160:163], v[52:55]
	v_mfma_f32_16x16x32_bf16 v[48:51], v[144:147], v[160:163], v[48:51]
	v_mfma_f32_16x16x32_bf16 v[36:39], v[136:139], v[168:171], v[36:39]
	v_mfma_f32_16x16x32_bf16 v[32:35], v[144:147], v[168:171], v[32:35]
	v_mfma_f32_16x16x32_bf16 v[20:23], v[136:139], v[176:179], v[20:23]
	v_mfma_f32_16x16x32_bf16 v[16:19], v[144:147], v[176:179], v[16:19]
	s_setprio 0
	s_barrier
	s_add_i32 s46, s46, s60
	v_lshl_add_u64 v[132:133], v[200:201], 0, s[58:59]
	s_mov_b32 m0, s46
	s_nop 0
	global_load_lds_dwordx4 v[132:133], off
	v_lshl_add_u64 v[132:133], v[202:203], 0, s[58:59]
	s_add_i32 m0, s46, 0x2000
	s_nop 0
	global_load_lds_dwordx4 v[132:133], off
	s_waitcnt vmcnt(6)
	s_barrier
	s_setprio 1
	v_mfma_f32_16x16x32_bf16 v[44:47], v[180:183], v[148:151], v[44:47]
	v_mfma_f32_16x16x32_bf16 v[40:43], v[188:191], v[148:151], v[40:43]
	v_mfma_f32_16x16x32_bf16 v[28:31], v[180:183], v[156:159], v[28:31]
	v_mfma_f32_16x16x32_bf16 v[24:27], v[188:191], v[156:159], v[24:27]
	v_mfma_f32_16x16x32_bf16 v[12:15], v[180:183], v[164:167], v[12:15]
	v_mfma_f32_16x16x32_bf16 v[8:11], v[188:191], v[164:167], v[8:11]
	v_mfma_f32_16x16x32_bf16 v[4:7], v[180:183], v[172:175], v[4:7]
	v_mfma_f32_16x16x32_bf16 v[0:3], v[188:191], v[172:175], v[0:3]
	v_mfma_f32_16x16x32_bf16 v[44:47], v[184:187], v[152:155], v[44:47]
	v_mfma_f32_16x16x32_bf16 v[40:43], v[210:213], v[152:155], v[40:43]
	v_mfma_f32_16x16x32_bf16 v[28:31], v[184:187], v[160:163], v[28:31]
	v_mfma_f32_16x16x32_bf16 v[24:27], v[210:213], v[160:163], v[24:27]
	v_mfma_f32_16x16x32_bf16 v[12:15], v[184:187], v[168:171], v[12:15]
	v_mfma_f32_16x16x32_bf16 v[8:11], v[210:213], v[168:171], v[8:11]
	v_mfma_f32_16x16x32_bf16 v[4:7], v[184:187], v[176:179], v[4:7]
	v_mfma_f32_16x16x32_bf16 v[0:3], v[210:213], v[176:179], v[0:3]
	s_setprio 0
	s_add_u32 s44, s44, 0x100
	s_addc_u32 s45, s45, 0
	s_add_u32 s63, s63, 0x100
	s_addc_u32 s52, s52, 0
	s_cmp_ge_i32 s53, s5
	s_mov_b32 s46, s53
	s_barrier
	s_cbranch_scc0 .LBB0_1166
	v_mov_b32_e32 v128, v192
	v_readlane_b32 s44, v252, 45
	s_bitcmp1_b32 s4, 0
	v_readlane_b32 s45, v252, 46
	v_ashrrev_i32_e32 v129, 31, v128
	s_cselect_b64 s[46:47], -1, 0
	v_readlane_b32 s62, v254, 39
	v_readlane_b32 s88, v254, 43
	v_lshl_add_u64 v[210:211], v[128:129], 4, s[44:45]
	s_mov_b64 s[44:45], -1
	s_and_b64 vcc, exec, s[46:47]
	v_readlane_b32 s63, v254, 40
	v_readlane_b32 s89, v254, 44
	v_readlane_b32 s53, v253, 4
	s_movk_i32 s80, 0xef00
	s_cbranch_vccz .LBB0_1297
	flat_load_dwordx4 v[188:191], v[210:211]
	s_cmp_lg_u32 s4, 1
	s_cselect_b64 s[46:47], -1, 0
	s_cmp_eq_u32 s4, 1
	s_cbranch_scc1 .LBB0_1170
	v_add_co_u32_e32 v128, vcc, 0x20000, v210
	s_nop 1
	v_addc_co_u32_e32 v129, vcc, 0, v211, vcc
	flat_load_dwordx4 v[156:159], v[128:129]

; #define PG8_STAGE(bufoff, gbase, voff) do { _Pragma("unroll") for (int _i = 0; _i < 2; ++_i) \
;     __builtin_amdgcn_global_load_lds((const unsigned*)((const char*)(gbase) + (voff)[_i]), (LAS unsigned*)(lds + (bufoff) + ldsw + _i * 8192), 16, 0, 0); } while (0)
; #define PG8_LDA(dst, b, h) do { _Pragma("unroll") for (int m = 0; m < 4; ++m) _Pragma("unroll") for (int k = 0; k < 2; ++k) dst[m][k] = *(const LAS bf16x8*)(lds + PG8_SA(b, h) + aoff + m * 2048 + k * 1024); } while (0)
; #define PG8_LDB(dst, b, h) do { _Pragma("unroll") for (int n = 0; n < 2; ++n) _Pragma("unroll") for (int k = 0; k < 2; ++k) dst[n][k] = *(const LAS bf16x8*)(lds + PG8_SB(b, h) + boff + n * 2048 + k * 1024); } while (0)
; #define PG8_MMA(ai, bj, At, Bt_) do { __builtin_amdgcn_s_setprio(1); _Pragma("unroll") for (int m = 0; m < 4; ++m) _Pragma("unroll") for (int n = 0; n < 2; ++n) _Pragma("unroll") for (int k = 0; k < 2; ++k) \
;     acc[ai][bj][m][n] = __builtin_amdgcn_mfma_f32_16x16x32_bf16(Bt_[n][k], At[m][k], acc[ai][bj][m][n], 0, 0, 0); __builtin_amdgcn_s_setprio(0); } while (0)
; #define PG8_WAIT_L(n) asm volatile("s_waitcnt lgkmcnt(" #n ")" ::: "memory")
; #define PG8_BAR __builtin_amdgcn_s_barrier()
; #define PG8_SCHED __builtin_amdgcn_sched_barrier(0)
; #define PG8_LDA(dst, b, h) do { _Pragma("unroll") for (int m = 0; m < 4; ++m) _Pragma("unroll") for (int k = 0; k < 2; ++k) dst[m][k] = *(const LAS bf16x8*)(lds + PG8_SA(b, h) + aoff + m * 2048 + k * 1024); } while (0)
; #define PG8_LDB(dst, b, h) do { _Pragma("unroll") for (int n = 0; n < 2; ++n) _Pragma("unroll") for (int k = 0; k < 2; ++k) dst[n][k] = *(const LAS bf16x8*)(lds + PG8_SB(b, h) + boff + n * 2048 + k * 1024); } while (0)
; #define PG8_WAIT_L(n) asm volatile("s_waitcnt lgkmcnt(" #n ")" ::: "memory")
; template <class Epi>
; DI void gemm_phase(char* smem, const bf16_t* A, int lda, const bf16_t* Bt, int ldb, int K, const Order& S_, const Epi& E) {
;     ...
;       PG8_LDB(B0, 0, 0); PG8_SCHED; PG8_LDA(At, 0, 0); PG8_STAGE(PG8_SA(1, 1), a1 + hstepA, voffA);
;       PG8_WAIT_L(8); PG8_BAR; PG8_WAIT_L(0); PG8_MMA(0, 0, At, B0); PG8_BAR; PG8_SCHED;
;       PG8_LDB(B1, 0, 1); PG8_STAGE(PG8_SB(0, 0), b2, voffB);
;       PG8_BAR; PG8_WAIT_L(0); PG8_MMA(0, 1, At, B1); PG8_BAR;
;       PG8_LDA(At, 0, 1); PG8_STAGE(PG8_SA(0, 0), a2, voffA);
;       PG8_BAR; PG8_WAIT_L(0); PG8_MMA(1, 0, At, B0); PG8_BAR; PG8_SCHED;
.LBB0_1701:
	s_add_u32 s0, s90, 0x100
	s_addc_u32 s1, s91, 0
	s_add_i32 s41, 0, 0x10000
	v_add_u32_e32 v76, s41, v185
	ds_read_b128 v[64:67], v76
	ds_read_b128 v[68:71], v76 offset:1024
	ds_read_b128 v[72:75], v76 offset:2048
	ds_read_b128 v[76:79], v76 offset:3072
	s_cmp_eq_u32 s29, 12
	s_cselect_b32 s51, s45, s1
	s_cselect_b32 s50, s44, s0
	s_cselect_b32 s47, s5, s20
	s_cselect_b32 s46, s15, s16
	v_lshl_add_u64 v[182:183], s[90:91], 0, v[166:167]
	s_add_i32 m0, s27, 0xc000
	ds_read_b128 v[144:147], v187
	ds_read_b128 v[148:151], v187 offset:1024
	ds_read_b128 v[152:155], v187 offset:2048
	ds_read_b128 v[156:159], v187 offset:3072
	ds_read_b128 v[170:173], v187 offset:4096
	ds_read_b128 v[174:177], v187 offset:5120
	ds_read_b128 v[178:181], v187 offset:6144
	ds_read_b128 v[188:191], v187 offset:7168
	global_load_lds_dwordx4 v[182:183], off
	v_lshl_add_u64 v[182:183], s[90:91], 0, v[168:169]
	s_add_i32 m0, s27, 0xe000
	s_nop 0
	global_load_lds_dwordx4 v[182:183], off
	s_waitcnt lgkmcnt(8)
	s_barrier
	s_waitcnt lgkmcnt(0)
	s_setprio 1
	v_mfma_f32_16x16x32_bf16 v[140:143], v[64:67], v[144:147], v[140:143]
	v_mfma_f32_16x16x32_bf16 v[136:139], v[72:75], v[144:147], v[136:139]
	v_mfma_f32_16x16x32_bf16 v[132:135], v[64:67], v[152:155], v[132:135]
	v_mfma_f32_16x16x32_bf16 v[124:127], v[72:75], v[152:155], v[124:127]
	v_mfma_f32_16x16x32_bf16 v[108:111], v[64:67], v[170:173], v[108:111]
	v_mfma_f32_16x16x32_bf16 v[104:107], v[72:75], v[170:173], v[104:107]
	v_mfma_f32_16x16x32_bf16 v[100:103], v[64:67], v[178:181], v[100:103]
	v_mfma_f32_16x16x32_bf16 v[92:95], v[72:75], v[178:181], v[92:95]
	v_mfma_f32_16x16x32_bf16 v[140:143], v[68:71], v[148:151], v[140:143]
	v_mfma_f32_16x16x32_bf16 v[136:139], v[76:79], v[148:151], v[136:139]
	v_mfma_f32_16x16x32_bf16 v[132:135], v[68:71], v[156:159], v[132:135]
	v_mfma_f32_16x16x32_bf16 v[124:127], v[76:79], v[156:159], v[124:127]
	v_mfma_f32_16x16x32_bf16 v[108:111], v[68:71], v[174:177], v[108:111]
	v_mfma_f32_16x16x32_bf16 v[104:107], v[76:79], v[174:177], v[104:107]
	v_mfma_f32_16x16x32_bf16 v[100:103], v[68:71], v[188:191], v[100:103]
	v_mfma_f32_16x16x32_bf16 v[92:95], v[76:79], v[188:191], v[92:95]
	s_setprio 0
	s_barrier
	s_add_i32 s43, 0, 0x14000
	v_add_u32_e32 v182, s43, v185
	s_add_i32 s41, s41, s26
	ds_read_b128 v[210:213], v182
	ds_read_b128 v[214:217], v182 offset:1024
	ds_read_b128 v[234:237], v182 offset:2048
	ds_read_b128 v[238:241], v182 offset:3072
	v_lshl_add_u64 v[182:183], s[46:47], 0, v[220:221]
	s_mov_b32 m0, s41
	v_lshl_add_u64 v[194:195], s[46:47], 0, v[164:165]
	global_load_lds_dwordx4 v[182:183], off
	s_add_i32 m0, s41, 0x2000
	s_nop 0
	global_load_lds_dwordx4 v[194:195], off
	s_barrier
	s_waitcnt lgkmcnt(0)
	s_setprio 1
	v_mfma_f32_16x16x32_bf16 v[128:131], v[210:213], v[144:147], v[128:131]
	v_mfma_f32_16x16x32_bf16 v[120:123], v[234:237], v[144:147], v[120:123]
	v_mfma_f32_16x16x32_bf16 v[116:119], v[210:213], v[152:155], v[116:119]
	v_mfma_f32_16x16x32_bf16 v[112:115], v[234:237], v[152:155], v[112:115]
	v_mfma_f32_16x16x32_bf16 v[96:99], v[210:213], v[170:173], v[96:99]
	v_mfma_f32_16x16x32_bf16 v[88:91], v[234:237], v[170:173], v[88:91]
	v_mfma_f32_16x16x32_bf16 v[84:87], v[210:213], v[178:181], v[84:87]
	v_mfma_f32_16x16x32_bf16 v[80:83], v[234:237], v[178:181], v[80:83]
	v_mfma_f32_16x16x32_bf16 v[128:131], v[214:217], v[148:151], v[128:131]
	v_mfma_f32_16x16x32_bf16 v[120:123], v[238:241], v[148:151], v[120:123]
	v_mfma_f32_16x16x32_bf16 v[116:119], v[214:217], v[156:159], v[116:119]
	v_mfma_f32_16x16x32_bf16 v[112:115], v[238:241], v[156:159], v[112:115]
	v_mfma_f32_16x16x32_bf16 v[96:99], v[214:217], v[174:177], v[96:99]
	v_mfma_f32_16x16x32_bf16 v[88:91], v[238:241], v[174:177], v[88:91]
	v_mfma_f32_16x16x32_bf16 v[84:87], v[214:217], v[188:191], v[84:87]
	v_mfma_f32_16x16x32_bf16 v[80:83], v[238:241], v[188:191], v[80:83]
	s_setprio 0
	s_mov_b32 m0, s27
	v_lshl_add_u64 v[200:201], s[50:51], 0, v[160:161]
	s_barrier
	ds_read_b128 v[144:147], v187 offset:16384
	ds_read_b128 v[148:151], v187 offset:17408
	ds_read_b128 v[152:155], v187 offset:18432
	ds_read_b128 v[156:159], v187 offset:19456
	ds_read_b128 v[170:173], v187 offset:20480
	ds_read_b128 v[174:177], v187 offset:21504
	ds_read_b128 v[178:181], v187 offset:22528
	ds_read_b128 v[188:191], v187 offset:23552
	global_load_lds_dwordx4 v[200:201], off
	v_lshl_add_u64 v[202:203], s[50:51], 0, v[162:163]
	s_mov_b32 m0, s33
	s_nop 0
	global_load_lds_dwordx4 v[202:203], off
	s_barrier
	s_waitcnt lgkmcnt(0)
	s_setprio 1
	v_mfma_f32_16x16x32_bf16 v[60:63], v[64:67], v[144:147], v[60:63]
	v_mfma_f32_16x16x32_bf16 v[56:59], v[72:75], v[144:147], v[56:59]
	v_mfma_f32_16x16x32_bf16 v[52:55], v[64:67], v[152:155], v[52:55]
	v_mfma_f32_16x16x32_bf16 v[44:47], v[72:75], v[152:155], v[44:47]
	v_mfma_f32_16x16x32_bf16 v[28:31], v[64:67], v[170:173], v[28:31]
	v_mfma_f32_16x16x32_bf16 v[24:27], v[72:75], v[170:173], v[24:27]
	v_mfma_f32_16x16x32_bf16 v[20:23], v[64:67], v[178:181], v[20:23]
	v_mfma_f32_16x16x32_bf16 v[12:15], v[72:75], v[178:181], v[12:15]
	v_mfma_f32_16x16x32_bf16 v[60:63], v[68:71], v[148:151], v[60:63]
	v_mfma_f32_16x16x32_bf16 v[56:59], v[76:79], v[148:151], v[56:59]
	v_mfma_f32_16x16x32_bf16 v[52:55], v[68:71], v[156:159], v[52:55]
	v_mfma_f32_16x16x32_bf16 v[44:47], v[76:79], v[156:159], v[44:47]
	v_mfma_f32_16x16x32_bf16 v[28:31], v[68:71], v[174:177], v[28:31]
	v_mfma_f32_16x16x32_bf16 v[24:27], v[76:79], v[174:177], v[24:27]
	v_mfma_f32_16x16x32_bf16 v[20:23], v[68:71], v[188:191], v[20:23]
	v_mfma_f32_16x16x32_bf16 v[12:15], v[76:79], v[188:191], v[12:15]
	s_setprio 0
	s_barrier
; #define PG8_STAGE(bufoff, gbase, voff) do { _Pragma("unroll") for (int _i = 0; _i < 2; ++_i) \
;     __builtin_amdgcn_global_load_lds((const unsigned*)((const char*)(gbase) + (voff)[_i]), (LAS unsigned*)(lds + (bufoff) + ldsw + _i * 8192), 16, 0, 0); } while (0)
; #define PG8_LDA(dst, b, h) do { _Pragma("unroll") for (int m = 0; m < 4; ++m) _Pragma("unroll") for (int k = 0; k < 2; ++k) dst[m][k] = *(const LAS bf16x8*)(lds + PG8_SA(b, h) + aoff + m * 2048 + k * 1024); } while (0)
; #define PG8_LDB(dst, b, h) do { _Pragma("unroll") for (int n = 0; n < 2; ++n) _Pragma("unroll") for (int k = 0; k < 2; ++k) dst[n][k] = *(const LAS bf16x8*)(lds + PG8_SB(b, h) + boff + n * 2048 + k * 1024); } while (0)
; #define PG8_MMA(ai, bj, At, Bt_) do { __builtin_amdgcn_s_setprio(1); _Pragma("unroll") for (int m = 0; m < 4; ++m) _Pragma("unroll") for (int n = 0; n < 2; ++n) _Pragma("unroll") for (int k = 0; k < 2; ++k) \
;     acc[ai][bj][m][n] = __builtin_amdgcn_mfma_f32_16x16x32_bf16(Bt_[n][k], At[m][k], acc[ai][bj][m][n], 0, 0, 0); __builtin_amdgcn_s_setprio(0); } while (0)
; #define PG8_WAIT_V(n) asm volatile("s_waitcnt vmcnt(" #n ")" ::: "memory")
; #define PG8_WAIT_L(n) asm volatile("s_waitcnt lgkmcnt(" #n ")" ::: "memory")
; #define PG8_BAR __builtin_amdgcn_s_barrier()
; #define PG8_SCHED __builtin_amdgcn_sched_barrier(0)
; #define PG8_LDA(dst, b, h) do { _Pragma("unroll") for (int m = 0; m < 4; ++m) _Pragma("unroll") for (int k = 0; k < 2; ++k) dst[m][k] = *(const LAS bf16x8*)(lds + PG8_SA(b, h) + aoff + m * 2048 + k * 1024); } while (0)
; #define PG8_WAIT_V(n) asm volatile("s_waitcnt vmcnt(" #n ")" ::: "memory")
; template <class Epi>
; DI void gemm_phase(char* smem, const bf16_t* A, int lda, const bf16_t* Bt, int ldb, int K, const Order& S_, const Epi& E) {
;     ...
;       PG8_STAGE(PG8_SB(0, 1), b2 + hstepB, voffB);
;       PG8_WAIT_V(6); PG8_BAR; PG8_MMA(1, 1, At, B1); PG8_BAR;
;       PG8_LDB(B0, 1, 0); PG8_SCHED; PG8_LDA(At, 1, 0); PG8_STAGE(PG8_SA(0, 1), a2 + hstepA, voffA);
;       PG8_WAIT_L(8); PG8_BAR; PG8_WAIT_L(0); PG8_MMA(0, 0, At, B0); PG8_BAR; PG8_SCHED;
;       PG8_LDB(B1, 1, 1); PG8_STAGE(PG8_SB(1, 0), b3, voffB);
;       PG8_BAR; PG8_WAIT_L(0); PG8_MMA(0, 1, At, B1); PG8_BAR;
;       PG8_LDA(At, 1, 1); PG8_STAGE(PG8_SA(1, 0), a3, voffA);
;       PG8_BAR; PG8_WAIT_L(0); PG8_MMA(1, 0, At, B0); PG8_BAR; PG8_SCHED;
	s_add_u32 s52, s46, 0x40000
	s_addc_u32 s53, s47, 0
	s_add_i32 s41, s43, s26
	v_lshl_add_u64 v[64:65], s[52:53], 0, v[220:221]
	s_mov_b32 m0, s41
	s_nop 0
	global_load_lds_dwordx4 v[64:65], off
	v_lshl_add_u64 v[64:65], s[52:53], 0, v[164:165]
	s_add_i32 m0, s41, 0x2000
	s_nop 0
	global_load_lds_dwordx4 v[64:65], off
	s_waitcnt vmcnt(6)
	s_barrier
	s_setprio 1
	v_mfma_f32_16x16x32_bf16 v[48:51], v[210:213], v[144:147], v[48:51]
	v_mfma_f32_16x16x32_bf16 v[40:43], v[234:237], v[144:147], v[40:43]
	v_mfma_f32_16x16x32_bf16 v[36:39], v[210:213], v[152:155], v[36:39]
	v_mfma_f32_16x16x32_bf16 v[32:35], v[234:237], v[152:155], v[32:35]
	v_mfma_f32_16x16x32_bf16 v[16:19], v[210:213], v[170:173], v[16:19]
	v_mfma_f32_16x16x32_bf16 v[8:11], v[234:237], v[170:173], v[8:11]
	v_mfma_f32_16x16x32_bf16 v[4:7], v[210:213], v[178:181], v[4:7]
	v_mfma_f32_16x16x32_bf16 v[0:3], v[234:237], v[178:181], v[0:3]
	v_mfma_f32_16x16x32_bf16 v[48:51], v[214:217], v[148:151], v[48:51]
	v_mfma_f32_16x16x32_bf16 v[40:43], v[238:241], v[148:151], v[40:43]
	v_mfma_f32_16x16x32_bf16 v[36:39], v[214:217], v[156:159], v[36:39]
	v_mfma_f32_16x16x32_bf16 v[32:35], v[238:241], v[156:159], v[32:35]
	v_mfma_f32_16x16x32_bf16 v[16:19], v[214:217], v[174:177], v[16:19]
	v_mfma_f32_16x16x32_bf16 v[8:11], v[238:241], v[174:177], v[8:11]
	v_mfma_f32_16x16x32_bf16 v[4:7], v[214:217], v[188:191], v[4:7]
	v_mfma_f32_16x16x32_bf16 v[0:3], v[238:241], v[188:191], v[0:3]
	s_setprio 0
	s_add_i32 s41, 0, 0x18000
	v_add_u32_e32 v76, s41, v185
	s_barrier
	ds_read_b128 v[64:67], v76
	ds_read_b128 v[68:71], v76 offset:1024
	ds_read_b128 v[72:75], v76 offset:2048
	ds_read_b128 v[76:79], v76 offset:3072
	s_add_u32 s50, s50, 0xb0000
	s_addc_u32 s51, s51, 0
	s_mov_b32 m0, s34
	v_lshl_add_u64 v[208:209], s[50:51], 0, v[160:161]
	ds_read_b128 v[144:147], v187 offset:32768
	ds_read_b128 v[148:151], v187 offset:33792
	ds_read_b128 v[152:155], v187 offset:34816
	ds_read_b128 v[156:159], v187 offset:35840
	ds_read_b128 v[170:173], v187 offset:36864
	ds_read_b128 v[174:177], v187 offset:37888
	ds_read_b128 v[178:181], v187 offset:38912
	ds_read_b128 v[188:191], v187 offset:39936
	global_load_lds_dwordx4 v[208:209], off
	v_lshl_add_u64 v[208:209], s[50:51], 0, v[162:163]
	s_mov_b32 m0, s38
	s_nop 0
	global_load_lds_dwordx4 v[208:209], off
	s_waitcnt lgkmcnt(8)
	s_barrier
	s_waitcnt lgkmcnt(0)
	s_setprio 1
	v_mfma_f32_16x16x32_bf16 v[140:143], v[64:67], v[144:147], v[140:143]
	v_mfma_f32_16x16x32_bf16 v[136:139], v[72:75], v[144:147], v[136:139]
	v_mfma_f32_16x16x32_bf16 v[132:135], v[64:67], v[152:155], v[132:135]
	v_mfma_f32_16x16x32_bf16 v[124:127], v[72:75], v[152:155], v[124:127]
	v_mfma_f32_16x16x32_bf16 v[108:111], v[64:67], v[170:173], v[108:111]
	v_mfma_f32_16x16x32_bf16 v[104:107], v[72:75], v[170:173], v[104:107]
	v_mfma_f32_16x16x32_bf16 v[100:103], v[64:67], v[178:181], v[100:103]
	v_mfma_f32_16x16x32_bf16 v[92:95], v[72:75], v[178:181], v[92:95]
	v_mfma_f32_16x16x32_bf16 v[140:143], v[68:71], v[148:151], v[140:143]
	v_mfma_f32_16x16x32_bf16 v[136:139], v[76:79], v[148:151], v[136:139]
	v_mfma_f32_16x16x32_bf16 v[132:135], v[68:71], v[156:159], v[132:135]
	v_mfma_f32_16x16x32_bf16 v[124:127], v[76:79], v[156:159], v[124:127]
	v_mfma_f32_16x16x32_bf16 v[108:111], v[68:71], v[174:177], v[108:111]
	v_mfma_f32_16x16x32_bf16 v[104:107], v[76:79], v[174:177], v[104:107]
	v_mfma_f32_16x16x32_bf16 v[100:103], v[68:71], v[188:191], v[100:103]
	v_mfma_f32_16x16x32_bf16 v[92:95], v[76:79], v[188:191], v[92:95]
	s_setprio 0
	s_barrier
	s_add_i32 s43, 0, 0x1c000
	s_add_i32 s41, s41, s26
	v_add_u32_e32 v204, s43, v185
	v_lshl_add_u64 v[182:183], v[182:183], 0, s[58:59]
	s_mov_b32 m0, s41
	ds_read_b128 v[210:213], v204
	ds_read_b128 v[214:217], v204 offset:1024
	ds_read_b128 v[234:237], v204 offset:2048
	ds_read_b128 v[238:241], v204 offset:3072
	global_load_lds_dwordx4 v[182:183], off
	v_lshl_add_u64 v[182:183], v[194:195], 0, s[58:59]
	s_add_i32 m0, s41, 0x2000
	s_nop 0
	global_load_lds_dwordx4 v[182:183], off
	s_barrier
	s_waitcnt lgkmcnt(0)
	s_setprio 1
	v_mfma_f32_16x16x32_bf16 v[128:131], v[210:213], v[144:147], v[128:131]
	v_mfma_f32_16x16x32_bf16 v[120:123], v[234:237], v[144:147], v[120:123]
	v_mfma_f32_16x16x32_bf16 v[116:119], v[210:213], v[152:155], v[116:119]
	v_mfma_f32_16x16x32_bf16 v[112:115], v[234:237], v[152:155], v[112:115]
	v_mfma_f32_16x16x32_bf16 v[96:99], v[210:213], v[170:173], v[96:99]
	v_mfma_f32_16x16x32_bf16 v[88:91], v[234:237], v[170:173], v[88:91]
	v_mfma_f32_16x16x32_bf16 v[84:87], v[210:213], v[178:181], v[84:87]
	v_mfma_f32_16x16x32_bf16 v[80:83], v[234:237], v[178:181], v[80:83]
	v_mfma_f32_16x16x32_bf16 v[128:131], v[214:217], v[148:151], v[128:131]
	v_mfma_f32_16x16x32_bf16 v[120:123], v[238:241], v[148:151], v[120:123]
	v_mfma_f32_16x16x32_bf16 v[116:119], v[214:217], v[156:159], v[116:119]
	v_mfma_f32_16x16x32_bf16 v[112:115], v[238:241], v[156:159], v[112:115]
	v_mfma_f32_16x16x32_bf16 v[96:99], v[214:217], v[174:177], v[96:99]
	v_mfma_f32_16x16x32_bf16 v[88:91], v[238:241], v[174:177], v[88:91]
	v_mfma_f32_16x16x32_bf16 v[84:87], v[214:217], v[188:191], v[84:87]
	v_mfma_f32_16x16x32_bf16 v[80:83], v[238:241], v[188:191], v[80:83]
	s_setprio 0
	s_mov_b32 m0, s39
	v_lshl_add_u64 v[182:183], v[200:201], 0, s[58:59]
	s_barrier
; #define MEMBAR() asm volatile("" ::: "memory")
; DI float* modp(const Params& p, int layer, int g, int chunk) { return (float*)(p.ws + OFF_MOD) + ((size_t)(layer * 9 + g) * 6 + chunk) * 1024; }
; #define PG8_STAGE(bufoff, gbase, voff) do { _Pragma("unroll") for (int _i = 0; _i < 2; ++_i) \
;     __builtin_amdgcn_global_load_lds((const unsigned*)((const char*)(gbase) + (voff)[_i]), (LAS unsigned*)(lds + (bufoff) + ldsw + _i * 8192), 16, 0, 0); } while (0)
; #define PG8_LDA(dst, b, h) do { _Pragma("unroll") for (int m = 0; m < 4; ++m) _Pragma("unroll") for (int k = 0; k < 2; ++k) dst[m][k] = *(const LAS bf16x8*)(lds + PG8_SA(b, h) + aoff + m * 2048 + k * 1024); } while (0)
; #define PG8_MMA(ai, bj, At, Bt_) do { __builtin_amdgcn_s_setprio(1); _Pragma("unroll") for (int m = 0; m < 4; ++m) _Pragma("unroll") for (int n = 0; n < 2; ++n) _Pragma("unroll") for (int k = 0; k < 2; ++k) \
;     acc[ai][bj][m][n] = __builtin_amdgcn_mfma_f32_16x16x32_bf16(Bt_[n][k], At[m][k], acc[ai][bj][m][n], 0, 0, 0); __builtin_amdgcn_s_setprio(0); } while (0)
; #define PG8_WAIT_V(n) asm volatile("s_waitcnt vmcnt(" #n ")" ::: "memory")
; #define PG8_BAR __builtin_amdgcn_s_barrier()
; template <class Epi>
; DI void gemm_phase(char* smem, const bf16_t* A, int lda, const bf16_t* Bt, int ldb, int K, const Order& S_, const Epi& E) {
;     ...
;       PG8_LDA(At, 1, 1); PG8_STAGE(PG8_SA(1, 0), a3, voffA);
;       PG8_BAR; PG8_WAIT_L(0); PG8_MMA(1, 0, At, B0); PG8_BAR; PG8_SCHED;
;       PG8_STAGE(PG8_SB(1, 1), b3 + hstepB, voffB);
;       PG8_WAIT_V(6); PG8_BAR; PG8_MMA(1, 1, At, B1); PG8_BAR;
;   DI void operator()(const acc_t& acc, const Unit& u, int wr, int wc, int fr, int fq) const {
;     const int row0 = u.pm * BM + wr * 64 + fr, col0 = u.pn * BM + wc * 32 + 4 * fq;
;     const int b = u.pm / 17, g = (u.pm - b * 17) == 0 ? 8 : b;
;     const float* gate = modp(p, layer, g, chunk);
;     f32x4 gv[2][2];
; #pragma unroll
;     for (int bj = 0; bj < 2; ++bj)
; #pragma unroll
;       for (int n = 0; n < 2; ++n) gv[bj][n] = *(const f32x4*)(gate + col0 + bj * HALF + n * 16);
; #pragma unroll
;     for (int q = 0; q < 4; ++q) {
;       const int ai = q >> 1, mh = q & 1;
;       MEMBAR();
;       f32x4 xv[2][2][2];
; #pragma unroll
;       for (int mm = 0; mm < 2; ++mm) { const int t = row0 + ai * HALF + (2 * mh + mm) * 16;
;         const float* xi = from_input ? xrow_in(p, t) : xrow_ws(p, t);
	ds_read_b128 v[144:147], v187 offset:49152
	ds_read_b128 v[148:151], v187 offset:50176
	ds_read_b128 v[152:155], v187 offset:51200
	ds_read_b128 v[156:159], v187 offset:52224
	ds_read_b128 v[170:173], v187 offset:53248
	ds_read_b128 v[174:177], v187 offset:54272
	ds_read_b128 v[178:181], v187 offset:55296
	ds_read_b128 v[188:191], v187 offset:56320
	global_load_lds_dwordx4 v[182:183], off
	v_lshl_add_u64 v[182:183], v[202:203], 0, s[58:59]
	s_mov_b32 m0, s49
	s_nop 0
	global_load_lds_dwordx4 v[182:183], off
	s_barrier
	s_waitcnt lgkmcnt(0)
	s_setprio 1
	v_mfma_f32_16x16x32_bf16 v[60:63], v[64:67], v[144:147], v[60:63]
	v_mfma_f32_16x16x32_bf16 v[56:59], v[72:75], v[144:147], v[56:59]
	v_mfma_f32_16x16x32_bf16 v[52:55], v[64:67], v[152:155], v[52:55]
	v_mfma_f32_16x16x32_bf16 v[44:47], v[72:75], v[152:155], v[44:47]
	v_mfma_f32_16x16x32_bf16 v[28:31], v[64:67], v[170:173], v[28:31]
	v_mfma_f32_16x16x32_bf16 v[24:27], v[72:75], v[170:173], v[24:27]
	v_mfma_f32_16x16x32_bf16 v[20:23], v[64:67], v[178:181], v[20:23]
	v_mfma_f32_16x16x32_bf16 v[12:15], v[72:75], v[178:181], v[12:15]
	v_mfma_f32_16x16x32_bf16 v[60:63], v[68:71], v[148:151], v[60:63]
	v_mfma_f32_16x16x32_bf16 v[56:59], v[76:79], v[148:151], v[56:59]
	v_mfma_f32_16x16x32_bf16 v[52:55], v[68:71], v[156:159], v[52:55]
	v_mfma_f32_16x16x32_bf16 v[44:47], v[76:79], v[156:159], v[44:47]
	v_mfma_f32_16x16x32_bf16 v[28:31], v[68:71], v[174:177], v[28:31]
	v_mfma_f32_16x16x32_bf16 v[24:27], v[76:79], v[174:177], v[24:27]
	v_mfma_f32_16x16x32_bf16 v[20:23], v[68:71], v[188:191], v[20:23]
	v_mfma_f32_16x16x32_bf16 v[12:15], v[76:79], v[188:191], v[12:15]
	s_setprio 0
	s_barrier
	s_add_u32 s46, s46, 0x40080
	s_addc_u32 s47, s47, 0
	s_add_i32 s41, s43, s26
	v_lshl_add_u64 v[64:65], s[46:47], 0, v[220:221]
	s_mov_b32 m0, s41
	s_nop 0
	global_load_lds_dwordx4 v[64:65], off
	v_lshl_add_u64 v[64:65], s[46:47], 0, v[164:165]
	s_add_i32 m0, s41, 0x2000
	s_nop 0
	global_load_lds_dwordx4 v[64:65], off
	s_waitcnt vmcnt(6)
	s_barrier
	s_setprio 1
	v_mfma_f32_16x16x32_bf16 v[48:51], v[210:213], v[144:147], v[48:51]
	v_mfma_f32_16x16x32_bf16 v[40:43], v[234:237], v[144:147], v[40:43]
	v_mfma_f32_16x16x32_bf16 v[36:39], v[210:213], v[152:155], v[36:39]
	v_mfma_f32_16x16x32_bf16 v[32:35], v[234:237], v[152:155], v[32:35]
	v_mfma_f32_16x16x32_bf16 v[16:19], v[210:213], v[170:173], v[16:19]
	v_mfma_f32_16x16x32_bf16 v[8:11], v[234:237], v[170:173], v[8:11]
	v_mfma_f32_16x16x32_bf16 v[4:7], v[210:213], v[178:181], v[4:7]
	v_mfma_f32_16x16x32_bf16 v[0:3], v[234:237], v[178:181], v[0:3]
	v_mfma_f32_16x16x32_bf16 v[48:51], v[214:217], v[148:151], v[48:51]
	v_mfma_f32_16x16x32_bf16 v[40:43], v[238:241], v[148:151], v[40:43]
	v_mfma_f32_16x16x32_bf16 v[36:39], v[214:217], v[156:159], v[36:39]
	v_mfma_f32_16x16x32_bf16 v[32:35], v[238:241], v[156:159], v[32:35]
	v_mfma_f32_16x16x32_bf16 v[16:19], v[214:217], v[174:177], v[16:19]
	v_mfma_f32_16x16x32_bf16 v[8:11], v[238:241], v[174:177], v[8:11]
	v_mfma_f32_16x16x32_bf16 v[4:7], v[214:217], v[188:191], v[4:7]
	v_mfma_f32_16x16x32_bf16 v[0:3], v[238:241], v[188:191], v[0:3]
	s_setprio 0
	s_add_i32 s29, s29, 2
	s_add_u32 s16, s16, 0x100
	s_addc_u32 s20, s20, 0
	s_cmp_gt_u32 s29, 13
	s_mov_b64 s[90:91], s[0:1]
	s_barrier
	s_cbranch_scc0 .LBB0_1701
	s_mul_hi_i32 s0, s4, 0x78787879
	s_lshr_b32 s1, s0, 31
	s_ashr_i32 s0, s0, 3
	s_add_i32 s0, s0, s1
	s_mul_i32 s1, s0, 0xffffffef
	s_sub_i32 s5, 0, s4
	s_cmp_lg_u32 s1, s5
	s_cselect_b32 s0, s0, 8
	v_readlane_b32 s1, v254, 59
	s_add_i32 s0, s0, s1
	s_mul_i32 s0, s0, 6
	s_ashr_i32 s1, s0, 31
	s_lshl_b64 s[0:1], s[0:1], 12
	v_readlane_b32 s5, v253, 27
	v_lshl_or_b32 v172, s42, 8, v186
	s_add_u32 s0, s5, s0
	v_readlane_b32 s5, v253, 28
	s_addc_u32 s1, s5, s1
	v_ashrrev_i32_e32 v173, 31, v172
	v_lshl_add_u64 v[64:65], v[172:173], 2, s[0:1]
	global_load_dwordx4 v[76:79], v[64:65], off
	global_load_dwordx4 v[72:75], v[64:65], off offset:64
	global_load_dwordx4 v[68:71], v[64:65], off offset:512
	s_nop 0
	global_load_dwordx4 v[64:67], v[64:65], off offset:576
	v_lshl_add_u32 v188, s4, 8, v184
	s_mov_b32 s51, 0x78787879
	v_mul_hi_i32 v144, v188, s51
	v_lshrrev_b32_e32 v145, 31, v144
	v_ashrrev_i32_e32 v144, 11, v144
	v_add_u32_e32 v144, v144, v145
	s_movk_i32 s4, 0xef00
	v_mad_i32_i24 v145, v144, s4, v188
	v_readlane_b32 s90, v254, 51
	s_movk_i32 s50, 0x100
	v_readlane_b32 s91, v254, 52
	v_ashrrev_i32_e32 v146, 31, v145
	v_add_u32_e32 v147, 0xffffff00, v145
	v_cmp_gt_i32_e64 s[0:1], s50, v145
	s_mov_b64 s[42:43], -1
	s_and_b64 vcc, exec, s[90:91]
	v_cndmask_b32_e64 v175, 0, v146, s[0:1]
	v_cndmask_b32_e64 v174, v147, v145, s[0:1]
	v_readlane_b32 s29, v254, 42
	s_cbranch_vccz .LBB0_1704
	v_mov_b32_e32 v145, s93
	v_mov_b32_e32 v146, s83
	v_cndmask_b32_e64 v147, v145, v146, s[0:1]
	v_mov_b32_e32 v145, s92
	v_mov_b32_e32 v146, s29
	v_cndmask_b32_e64 v146, v145, v146, s[0:1]
	s_mov_b64 s[42:43], 0

; #define PG8_STAGE(bufoff, gbase, voff) do { _Pragma("unroll") for (int _i = 0; _i < 2; ++_i) \
;     __builtin_amdgcn_global_load_lds((const unsigned*)((const char*)(gbase) + (voff)[_i]), (LAS unsigned*)(lds + (bufoff) + ldsw + _i * 8192), 16, 0, 0); } while (0)
; #define PG8_LDA(dst, b, h) do { _Pragma("unroll") for (int m = 0; m < 4; ++m) _Pragma("unroll") for (int k = 0; k < 2; ++k) dst[m][k] = *(const LAS bf16x8*)(lds + PG8_SA(b, h) + aoff + m * 2048 + k * 1024); } while (0)
; #define PG8_LDB(dst, b, h) do { _Pragma("unroll") for (int n = 0; n < 2; ++n) _Pragma("unroll") for (int k = 0; k < 2; ++k) dst[n][k] = *(const LAS bf16x8*)(lds + PG8_SB(b, h) + boff + n * 2048 + k * 1024); } while (0)
; #define PG8_MMA(ai, bj, At, Bt_) do { __builtin_amdgcn_s_setprio(1); _Pragma("unroll") for (int m = 0; m < 4; ++m) _Pragma("unroll") for (int n = 0; n < 2; ++n) _Pragma("unroll") for (int k = 0; k < 2; ++k) \
;     acc[ai][bj][m][n] = __builtin_amdgcn_mfma_f32_16x16x32_bf16(Bt_[n][k], At[m][k], acc[ai][bj][m][n], 0, 0, 0); __builtin_amdgcn_s_setprio(0); } while (0)
; #define PG8_WAIT_L(n) asm volatile("s_waitcnt lgkmcnt(" #n ")" ::: "memory")
; #define PG8_BAR __builtin_amdgcn_s_barrier()
; #define PG8_SCHED __builtin_amdgcn_sched_barrier(0)
; #define PG8_LDA(dst, b, h) do { _Pragma("unroll") for (int m = 0; m < 4; ++m) _Pragma("unroll") for (int k = 0; k < 2; ++k) dst[m][k] = *(const LAS bf16x8*)(lds + PG8_SA(b, h) + aoff + m * 2048 + k * 1024); } while (0)
; #define PG8_LDB(dst, b, h) do { _Pragma("unroll") for (int n = 0; n < 2; ++n) _Pragma("unroll") for (int k = 0; k < 2; ++k) dst[n][k] = *(const LAS bf16x8*)(lds + PG8_SB(b, h) + boff + n * 2048 + k * 1024); } while (0)
; #define PG8_WAIT_L(n) asm volatile("s_waitcnt lgkmcnt(" #n ")" ::: "memory")
; template <class Epi>
; DI void gemm_phase(char* smem, const bf16_t* A, int lda, const bf16_t* Bt, int ldb, int K, const Order& S_, const Epi& E) {
;     ...
;       PG8_LDB(B0, 0, 0); PG8_SCHED; PG8_LDA(At, 0, 0); PG8_STAGE(PG8_SA(1, 1), a1 + hstepA, voffA);
;       PG8_WAIT_L(8); PG8_BAR; PG8_WAIT_L(0); PG8_MMA(0, 0, At, B0); PG8_BAR; PG8_SCHED;
;       PG8_LDB(B1, 0, 1); PG8_STAGE(PG8_SB(0, 0), b2, voffB);
;       PG8_BAR; PG8_WAIT_L(0); PG8_MMA(0, 1, At, B1); PG8_BAR;
;       PG8_LDA(At, 0, 1); PG8_STAGE(PG8_SA(0, 0), a2, voffA);
;       PG8_BAR; PG8_WAIT_L(0); PG8_MMA(1, 0, At, B0); PG8_BAR; PG8_SCHED;
.LBB0_1858:
	s_add_u32 s42, vcc_lo, 0xfffc0080
	s_addc_u32 s43, vcc_hi, -1
	s_add_i32 s52, 0, 0x10000
	v_add_u32_e32 v154, s52, v139
	ds_read_b128 v[142:145], v154
	ds_read_b128 v[146:149], v154 offset:1024
	ds_read_b128 v[150:153], v154 offset:2048
	ds_read_b128 v[154:157], v154 offset:3072
	s_cmp_eq_u32 s41, 12
	s_cselect_b32 s89, s4, s43
	s_cselect_b32 s88, s5, s42
	s_cselect_b32 s43, s15, s29
	s_cselect_b32 s42, s16, s20
	v_lshl_add_u64 v[190:191], vcc, 0, v[134:135]
	s_add_i32 m0, s1, 0xc000
	ds_read_b128 v[158:161], v141
	ds_read_b128 v[162:165], v141 offset:1024
	ds_read_b128 v[166:169], v141 offset:2048
	ds_read_b128 v[170:173], v141 offset:3072
	ds_read_b128 v[174:177], v141 offset:4096
	ds_read_b128 v[178:181], v141 offset:5120
	ds_read_b128 v[182:185], v141 offset:6144
	ds_read_b128 v[186:189], v141 offset:7168
	global_load_lds_dwordx4 v[190:191], off
	v_lshl_add_u64 v[190:191], vcc, 0, v[136:137]
	s_add_i32 m0, s1, 0xe000
	s_nop 0
	global_load_lds_dwordx4 v[190:191], off
	s_waitcnt lgkmcnt(8)
	s_barrier
	s_waitcnt lgkmcnt(0)
	s_setprio 1
	v_mfma_f32_16x16x32_bf16 v[124:127], v[142:145], v[158:161], v[124:127]
	v_mfma_f32_16x16x32_bf16 v[116:119], v[150:153], v[158:161], v[116:119]
	v_mfma_f32_16x16x32_bf16 v[108:111], v[142:145], v[166:169], v[108:111]
	v_mfma_f32_16x16x32_bf16 v[100:103], v[150:153], v[166:169], v[100:103]
	v_mfma_f32_16x16x32_bf16 v[92:95], v[142:145], v[174:177], v[92:95]
	v_mfma_f32_16x16x32_bf16 v[84:87], v[150:153], v[174:177], v[84:87]
	v_mfma_f32_16x16x32_bf16 v[76:79], v[142:145], v[182:185], v[76:79]
	v_mfma_f32_16x16x32_bf16 v[68:71], v[150:153], v[182:185], v[68:71]
	v_mfma_f32_16x16x32_bf16 v[124:127], v[146:149], v[162:165], v[124:127]
	v_mfma_f32_16x16x32_bf16 v[116:119], v[154:157], v[162:165], v[116:119]
	v_mfma_f32_16x16x32_bf16 v[108:111], v[146:149], v[170:173], v[108:111]
	v_mfma_f32_16x16x32_bf16 v[100:103], v[154:157], v[170:173], v[100:103]
	v_mfma_f32_16x16x32_bf16 v[92:95], v[146:149], v[178:181], v[92:95]
	v_mfma_f32_16x16x32_bf16 v[84:87], v[154:157], v[178:181], v[84:87]
	v_mfma_f32_16x16x32_bf16 v[76:79], v[146:149], v[186:189], v[76:79]
	v_mfma_f32_16x16x32_bf16 v[68:71], v[154:157], v[186:189], v[68:71]
	s_setprio 0
	s_barrier
	s_add_i32 s56, 0, 0x14000
	v_add_u32_e32 v190, s56, v139
	s_add_i32 s52, s52, s33
	ds_read_b128 v[210:213], v190
	ds_read_b128 v[214:217], v190 offset:1024
	ds_read_b128 v[234:237], v190 offset:2048
	ds_read_b128 v[238:241], v190 offset:3072
	v_lshl_add_u64 v[190:191], s[42:43], 0, v[220:221]
	s_mov_b32 m0, s52
	v_lshl_add_u64 v[194:195], s[42:43], 0, v[132:133]
	global_load_lds_dwordx4 v[190:191], off
	s_add_i32 m0, s52, 0x2000
	s_nop 0
	global_load_lds_dwordx4 v[194:195], off
	s_barrier
	s_waitcnt lgkmcnt(0)
	s_setprio 1
	v_mfma_f32_16x16x32_bf16 v[120:123], v[210:213], v[158:161], v[120:123]
	v_mfma_f32_16x16x32_bf16 v[112:115], v[234:237], v[158:161], v[112:115]
	v_mfma_f32_16x16x32_bf16 v[104:107], v[210:213], v[166:169], v[104:107]
	v_mfma_f32_16x16x32_bf16 v[96:99], v[234:237], v[166:169], v[96:99]
	v_mfma_f32_16x16x32_bf16 v[88:91], v[210:213], v[174:177], v[88:91]
	v_mfma_f32_16x16x32_bf16 v[80:83], v[234:237], v[174:177], v[80:83]
	v_mfma_f32_16x16x32_bf16 v[72:75], v[210:213], v[182:185], v[72:75]
	v_mfma_f32_16x16x32_bf16 v[64:67], v[234:237], v[182:185], v[64:67]
	v_mfma_f32_16x16x32_bf16 v[120:123], v[214:217], v[162:165], v[120:123]
	v_mfma_f32_16x16x32_bf16 v[112:115], v[238:241], v[162:165], v[112:115]
	v_mfma_f32_16x16x32_bf16 v[104:107], v[214:217], v[170:173], v[104:107]
	v_mfma_f32_16x16x32_bf16 v[96:99], v[238:241], v[170:173], v[96:99]
	v_mfma_f32_16x16x32_bf16 v[88:91], v[214:217], v[178:181], v[88:91]
	v_mfma_f32_16x16x32_bf16 v[80:83], v[238:241], v[178:181], v[80:83]
	v_mfma_f32_16x16x32_bf16 v[72:75], v[214:217], v[186:189], v[72:75]
	v_mfma_f32_16x16x32_bf16 v[64:67], v[238:241], v[186:189], v[64:67]
	s_setprio 0
	s_mov_b32 m0, s1
	v_lshl_add_u64 v[200:201], s[88:89], 0, v[128:129]
	s_barrier
	ds_read_b128 v[158:161], v141 offset:16384
	ds_read_b128 v[162:165], v141 offset:17408
	ds_read_b128 v[166:169], v141 offset:18432
	ds_read_b128 v[170:173], v141 offset:19456
	ds_read_b128 v[174:177], v141 offset:20480
	ds_read_b128 v[178:181], v141 offset:21504
	ds_read_b128 v[182:185], v141 offset:22528
	ds_read_b128 v[186:189], v141 offset:23552
	global_load_lds_dwordx4 v[200:201], off
	v_lshl_add_u64 v[202:203], s[88:89], 0, v[130:131]
	s_mov_b32 m0, s34
	s_nop 0
	global_load_lds_dwordx4 v[202:203], off
	s_barrier
	s_waitcnt lgkmcnt(0)
	s_setprio 1
	v_mfma_f32_16x16x32_bf16 v[60:63], v[142:145], v[158:161], v[60:63]
	v_mfma_f32_16x16x32_bf16 v[52:55], v[150:153], v[158:161], v[52:55]
	v_mfma_f32_16x16x32_bf16 v[44:47], v[142:145], v[166:169], v[44:47]
	v_mfma_f32_16x16x32_bf16 v[36:39], v[150:153], v[166:169], v[36:39]
	v_mfma_f32_16x16x32_bf16 v[28:31], v[142:145], v[174:177], v[28:31]
	v_mfma_f32_16x16x32_bf16 v[20:23], v[150:153], v[174:177], v[20:23]
	v_mfma_f32_16x16x32_bf16 v[12:15], v[142:145], v[182:185], v[12:15]
	v_mfma_f32_16x16x32_bf16 v[4:7], v[150:153], v[182:185], v[4:7]
	v_mfma_f32_16x16x32_bf16 v[60:63], v[146:149], v[162:165], v[60:63]
	v_mfma_f32_16x16x32_bf16 v[52:55], v[154:157], v[162:165], v[52:55]
	v_mfma_f32_16x16x32_bf16 v[44:47], v[146:149], v[170:173], v[44:47]
	v_mfma_f32_16x16x32_bf16 v[36:39], v[154:157], v[170:173], v[36:39]
	v_mfma_f32_16x16x32_bf16 v[28:31], v[146:149], v[178:181], v[28:31]
	v_mfma_f32_16x16x32_bf16 v[20:23], v[154:157], v[178:181], v[20:23]
	v_mfma_f32_16x16x32_bf16 v[12:15], v[146:149], v[186:189], v[12:15]
	v_mfma_f32_16x16x32_bf16 v[4:7], v[154:157], v[186:189], v[4:7]
	s_setprio 0
	s_barrier
; #define PG8_STAGE(bufoff, gbase, voff) do { _Pragma("unroll") for (int _i = 0; _i < 2; ++_i) \
;     __builtin_amdgcn_global_load_lds((const unsigned*)((const char*)(gbase) + (voff)[_i]), (LAS unsigned*)(lds + (bufoff) + ldsw + _i * 8192), 16, 0, 0); } while (0)
; #define PG8_LDA(dst, b, h) do { _Pragma("unroll") for (int m = 0; m < 4; ++m) _Pragma("unroll") for (int k = 0; k < 2; ++k) dst[m][k] = *(const LAS bf16x8*)(lds + PG8_SA(b, h) + aoff + m * 2048 + k * 1024); } while (0)
; #define PG8_LDB(dst, b, h) do { _Pragma("unroll") for (int n = 0; n < 2; ++n) _Pragma("unroll") for (int k = 0; k < 2; ++k) dst[n][k] = *(const LAS bf16x8*)(lds + PG8_SB(b, h) + boff + n * 2048 + k * 1024); } while (0)
; #define PG8_MMA(ai, bj, At, Bt_) do { __builtin_amdgcn_s_setprio(1); _Pragma("unroll") for (int m = 0; m < 4; ++m) _Pragma("unroll") for (int n = 0; n < 2; ++n) _Pragma("unroll") for (int k = 0; k < 2; ++k) \
;     acc[ai][bj][m][n] = __builtin_amdgcn_mfma_f32_16x16x32_bf16(Bt_[n][k], At[m][k], acc[ai][bj][m][n], 0, 0, 0); __builtin_amdgcn_s_setprio(0); } while (0)
; #define PG8_WAIT_V(n) asm volatile("s_waitcnt vmcnt(" #n ")" ::: "memory")
; #define PG8_WAIT_L(n) asm volatile("s_waitcnt lgkmcnt(" #n ")" ::: "memory")
; #define PG8_BAR __builtin_amdgcn_s_barrier()
; #define PG8_SCHED __builtin_amdgcn_sched_barrier(0)
; #define PG8_LDA(dst, b, h) do { _Pragma("unroll") for (int m = 0; m < 4; ++m) _Pragma("unroll") for (int k = 0; k < 2; ++k) dst[m][k] = *(const LAS bf16x8*)(lds + PG8_SA(b, h) + aoff + m * 2048 + k * 1024); } while (0)
; #define PG8_WAIT_V(n) asm volatile("s_waitcnt vmcnt(" #n ")" ::: "memory")
; template <class Epi>
; DI void gemm_phase(char* smem, const bf16_t* A, int lda, const bf16_t* Bt, int ldb, int K, const Order& S_, const Epi& E) {
;     ...
;       PG8_STAGE(PG8_SB(0, 1), b2 + hstepB, voffB);
;       PG8_WAIT_V(6); PG8_BAR; PG8_MMA(1, 1, At, B1); PG8_BAR;
;       PG8_LDB(B0, 1, 0); PG8_SCHED; PG8_LDA(At, 1, 0); PG8_STAGE(PG8_SA(0, 1), a2 + hstepA, voffA);
;       PG8_WAIT_L(8); PG8_BAR; PG8_WAIT_L(0); PG8_MMA(0, 0, At, B0); PG8_BAR; PG8_SCHED;
;       PG8_LDB(B1, 1, 1); PG8_STAGE(PG8_SB(1, 0), b3, voffB);
;       PG8_BAR; PG8_WAIT_L(0); PG8_MMA(0, 1, At, B1); PG8_BAR;
;       PG8_LDA(At, 1, 1); PG8_STAGE(PG8_SA(1, 0), a3, voffA);
;       PG8_BAR; PG8_WAIT_L(0); PG8_MMA(1, 0, At, B0); PG8_BAR; PG8_SCHED;
	s_add_u32 s52, s42, 0x40000
	s_addc_u32 s53, s43, 0
	s_add_i32 s56, s56, s33
	v_lshl_add_u64 v[142:143], s[52:53], 0, v[220:221]
	s_mov_b32 m0, s56
	s_nop 0
	global_load_lds_dwordx4 v[142:143], off
	v_lshl_add_u64 v[142:143], s[52:53], 0, v[132:133]
	s_add_i32 m0, s56, 0x2000
	s_nop 0
	global_load_lds_dwordx4 v[142:143], off
	s_waitcnt vmcnt(6)
	s_barrier
	s_setprio 1
	v_mfma_f32_16x16x32_bf16 v[56:59], v[210:213], v[158:161], v[56:59]
	v_mfma_f32_16x16x32_bf16 v[48:51], v[234:237], v[158:161], v[48:51]
	v_mfma_f32_16x16x32_bf16 v[40:43], v[210:213], v[166:169], v[40:43]
	v_mfma_f32_16x16x32_bf16 v[32:35], v[234:237], v[166:169], v[32:35]
	v_mfma_f32_16x16x32_bf16 v[24:27], v[210:213], v[174:177], v[24:27]
	v_mfma_f32_16x16x32_bf16 v[16:19], v[234:237], v[174:177], v[16:19]
	v_mfma_f32_16x16x32_bf16 v[8:11], v[210:213], v[182:185], v[8:11]
	v_mfma_f32_16x16x32_bf16 v[0:3], v[234:237], v[182:185], v[0:3]
	v_mfma_f32_16x16x32_bf16 v[56:59], v[214:217], v[162:165], v[56:59]
	v_mfma_f32_16x16x32_bf16 v[48:51], v[238:241], v[162:165], v[48:51]
	v_mfma_f32_16x16x32_bf16 v[40:43], v[214:217], v[170:173], v[40:43]
	v_mfma_f32_16x16x32_bf16 v[32:35], v[238:241], v[170:173], v[32:35]
	v_mfma_f32_16x16x32_bf16 v[24:27], v[214:217], v[178:181], v[24:27]
	v_mfma_f32_16x16x32_bf16 v[16:19], v[238:241], v[178:181], v[16:19]
	v_mfma_f32_16x16x32_bf16 v[8:11], v[214:217], v[186:189], v[8:11]
	v_mfma_f32_16x16x32_bf16 v[0:3], v[238:241], v[186:189], v[0:3]
	s_setprio 0
	s_add_i32 s56, 0, 0x18000
	v_add_u32_e32 v154, s56, v139
	s_barrier
	ds_read_b128 v[142:145], v154
	ds_read_b128 v[146:149], v154 offset:1024
	ds_read_b128 v[150:153], v154 offset:2048
	ds_read_b128 v[154:157], v154 offset:3072
	s_add_u32 s52, s88, 0x40000
	s_addc_u32 s53, s89, 0
	s_mov_b32 m0, s38
	v_lshl_add_u64 v[208:209], s[52:53], 0, v[128:129]
	ds_read_b128 v[158:161], v141 offset:32768
	ds_read_b128 v[162:165], v141 offset:33792
	ds_read_b128 v[166:169], v141 offset:34816
	ds_read_b128 v[170:173], v141 offset:35840
	ds_read_b128 v[174:177], v141 offset:36864
	ds_read_b128 v[178:181], v141 offset:37888
	ds_read_b128 v[182:185], v141 offset:38912
	ds_read_b128 v[186:189], v141 offset:39936
	global_load_lds_dwordx4 v[208:209], off
	v_lshl_add_u64 v[208:209], s[52:53], 0, v[130:131]
	s_mov_b32 m0, s39
	s_nop 0
	global_load_lds_dwordx4 v[208:209], off
	s_waitcnt lgkmcnt(8)
	s_barrier
	s_waitcnt lgkmcnt(0)
	s_setprio 1
	v_mfma_f32_16x16x32_bf16 v[124:127], v[142:145], v[158:161], v[124:127]
	v_mfma_f32_16x16x32_bf16 v[116:119], v[150:153], v[158:161], v[116:119]
	v_mfma_f32_16x16x32_bf16 v[108:111], v[142:145], v[166:169], v[108:111]
	v_mfma_f32_16x16x32_bf16 v[100:103], v[150:153], v[166:169], v[100:103]
	v_mfma_f32_16x16x32_bf16 v[92:95], v[142:145], v[174:177], v[92:95]
	v_mfma_f32_16x16x32_bf16 v[84:87], v[150:153], v[174:177], v[84:87]
	v_mfma_f32_16x16x32_bf16 v[76:79], v[142:145], v[182:185], v[76:79]
	v_mfma_f32_16x16x32_bf16 v[68:71], v[150:153], v[182:185], v[68:71]
	v_mfma_f32_16x16x32_bf16 v[124:127], v[146:149], v[162:165], v[124:127]
	v_mfma_f32_16x16x32_bf16 v[116:119], v[154:157], v[162:165], v[116:119]
	v_mfma_f32_16x16x32_bf16 v[108:111], v[146:149], v[170:173], v[108:111]
	v_mfma_f32_16x16x32_bf16 v[100:103], v[154:157], v[170:173], v[100:103]
	v_mfma_f32_16x16x32_bf16 v[92:95], v[146:149], v[178:181], v[92:95]
	v_mfma_f32_16x16x32_bf16 v[84:87], v[154:157], v[178:181], v[84:87]
	v_mfma_f32_16x16x32_bf16 v[76:79], v[146:149], v[186:189], v[76:79]
	v_mfma_f32_16x16x32_bf16 v[68:71], v[154:157], v[186:189], v[68:71]
	s_setprio 0
	s_barrier
	s_add_i32 s52, 0, 0x1c000
	s_add_i32 s53, s56, s33
	v_add_u32_e32 v204, s52, v139
	v_lshl_add_u64 v[190:191], v[190:191], 0, s[58:59]
	s_mov_b32 m0, s53
	ds_read_b128 v[210:213], v204
	ds_read_b128 v[214:217], v204 offset:1024
	ds_read_b128 v[234:237], v204 offset:2048
	ds_read_b128 v[238:241], v204 offset:3072
	global_load_lds_dwordx4 v[190:191], off
	v_lshl_add_u64 v[190:191], v[194:195], 0, s[58:59]
	s_add_i32 m0, s53, 0x2000
	s_nop 0
	global_load_lds_dwordx4 v[190:191], off
	s_barrier
	s_waitcnt lgkmcnt(0)
	s_setprio 1
	v_mfma_f32_16x16x32_bf16 v[120:123], v[210:213], v[158:161], v[120:123]
	v_mfma_f32_16x16x32_bf16 v[112:115], v[234:237], v[158:161], v[112:115]
	v_mfma_f32_16x16x32_bf16 v[104:107], v[210:213], v[166:169], v[104:107]
	v_mfma_f32_16x16x32_bf16 v[96:99], v[234:237], v[166:169], v[96:99]
	v_mfma_f32_16x16x32_bf16 v[88:91], v[210:213], v[174:177], v[88:91]
	v_mfma_f32_16x16x32_bf16 v[80:83], v[234:237], v[174:177], v[80:83]
	v_mfma_f32_16x16x32_bf16 v[72:75], v[210:213], v[182:185], v[72:75]
	v_mfma_f32_16x16x32_bf16 v[64:67], v[234:237], v[182:185], v[64:67]
	v_mfma_f32_16x16x32_bf16 v[120:123], v[214:217], v[162:165], v[120:123]
	v_mfma_f32_16x16x32_bf16 v[112:115], v[238:241], v[162:165], v[112:115]
	v_mfma_f32_16x16x32_bf16 v[104:107], v[214:217], v[170:173], v[104:107]
	v_mfma_f32_16x16x32_bf16 v[96:99], v[238:241], v[170:173], v[96:99]
	v_mfma_f32_16x16x32_bf16 v[88:91], v[214:217], v[178:181], v[88:91]
	v_mfma_f32_16x16x32_bf16 v[80:83], v[238:241], v[178:181], v[80:83]
	v_mfma_f32_16x16x32_bf16 v[72:75], v[214:217], v[186:189], v[72:75]
	v_mfma_f32_16x16x32_bf16 v[64:67], v[238:241], v[186:189], v[64:67]
	s_setprio 0
	s_mov_b32 m0, s47
	v_lshl_add_u64 v[190:191], v[200:201], 0, s[58:59]
	s_barrier
	ds_read_b128 v[158:161], v141 offset:49152
	ds_read_b128 v[162:165], v141 offset:50176
	ds_read_b128 v[166:169], v141 offset:51200
	ds_read_b128 v[170:173], v141 offset:52224
	ds_read_b128 v[174:177], v141 offset:53248
	ds_read_b128 v[178:181], v141 offset:54272
	ds_read_b128 v[182:185], v141 offset:55296
	ds_read_b128 v[186:189], v141 offset:56320
	global_load_lds_dwordx4 v[190:191], off
	v_lshl_add_u64 v[190:191], v[202:203], 0, s[58:59]
	s_mov_b32 m0, s49
	s_nop 0
	global_load_lds_dwordx4 v[190:191], off
	s_barrier
; DI float siluf_(float x) { return x * sigmoidf_(x); }
; #define PG8_STAGE(bufoff, gbase, voff) do { _Pragma("unroll") for (int _i = 0; _i < 2; ++_i) \
;     __builtin_amdgcn_global_load_lds((const unsigned*)((const char*)(gbase) + (voff)[_i]), (LAS unsigned*)(lds + (bufoff) + ldsw + _i * 8192), 16, 0, 0); } while (0)
; #define PG8_MMA(ai, bj, At, Bt_) do { __builtin_amdgcn_s_setprio(1); _Pragma("unroll") for (int m = 0; m < 4; ++m) _Pragma("unroll") for (int n = 0; n < 2; ++n) _Pragma("unroll") for (int k = 0; k < 2; ++k) \
;     acc[ai][bj][m][n] = __builtin_amdgcn_mfma_f32_16x16x32_bf16(Bt_[n][k], At[m][k], acc[ai][bj][m][n], 0, 0, 0); __builtin_amdgcn_s_setprio(0); } while (0)
; #define PG8_WAIT_V(n) asm volatile("s_waitcnt vmcnt(" #n ")" ::: "memory")
; #define PG8_WAIT_L(n) asm volatile("s_waitcnt lgkmcnt(" #n ")" ::: "memory")
; #define PG8_BAR __builtin_amdgcn_s_barrier()
; #define PG8_SCHED __builtin_amdgcn_sched_barrier(0)
; DI u32x4 pack8v(const f32x4& a, const f32x4& b) { u32x4 w; w.x = pk2(a[0], a[1]); w.y = pk2(a[2], a[3]); w.z = pk2(b[0], b[1]); w.w = pk2(b[2], b[3]); return w; }
; #define PG8_WAIT_V(n) asm volatile("s_waitcnt vmcnt(" #n ")" ::: "memory")
; #define PG8_WAIT_L(n) asm volatile("s_waitcnt lgkmcnt(" #n ")" ::: "memory")
; #define PG8_BAR __builtin_amdgcn_s_barrier()
; #define PG8_SCHED __builtin_amdgcn_sched_barrier(0)
; template <class Epi>
; DI void gemm_phase(char* smem, const bf16_t* A, int lda, const bf16_t* Bt, int ldb, int K, const Order& S_, const Epi& E) {
;     ...
;       PG8_BAR; PG8_WAIT_L(0); PG8_MMA(1, 0, At, B0); PG8_BAR; PG8_SCHED;
;       PG8_STAGE(PG8_SB(1, 1), b3 + hstepB, voffB);
;       PG8_WAIT_V(6); PG8_BAR; PG8_MMA(1, 1, At, B1); PG8_BAR;
;   DI void operator()(const acc_t& acc, const Unit& u, int wr, int wc, int fr, int fq) const {
;     const int row0 = u.pm * BM + wr * 64 + fr, col0 = u.pn * HALF + wc * 32 + 8 * fq;
; #pragma unroll
;     for (int ai = 0; ai < 2; ++ai)
; #pragma unroll
;       for (int m = 0; m < 4; ++m) {
;         f32x4 r0, r1;
; #pragma unroll
;         for (int e = 0; e < 4; ++e) { r0[e] = siluf_(acc[ai][0][m][0][e]) * acc[ai][1][m][0][e]; r1[e] = siluf_(acc[ai][0][m][1][e]) * acc[ai][1][m][1][e]; }
;         *(u32x4*)(G + (size_t)(row0 + ai * HALF + m * 16) * DFF + col0) = pack8v(r0, r1); }
	s_waitcnt lgkmcnt(0)
	s_setprio 1
	v_mfma_f32_16x16x32_bf16 v[60:63], v[142:145], v[158:161], v[60:63]
	v_mfma_f32_16x16x32_bf16 v[52:55], v[150:153], v[158:161], v[52:55]
	v_mfma_f32_16x16x32_bf16 v[44:47], v[142:145], v[166:169], v[44:47]
	v_mfma_f32_16x16x32_bf16 v[36:39], v[150:153], v[166:169], v[36:39]
	v_mfma_f32_16x16x32_bf16 v[28:31], v[142:145], v[174:177], v[28:31]
	v_mfma_f32_16x16x32_bf16 v[20:23], v[150:153], v[174:177], v[20:23]
	v_mfma_f32_16x16x32_bf16 v[12:15], v[142:145], v[182:185], v[12:15]
	v_mfma_f32_16x16x32_bf16 v[4:7], v[150:153], v[182:185], v[4:7]
	v_mfma_f32_16x16x32_bf16 v[60:63], v[146:149], v[162:165], v[60:63]
	v_mfma_f32_16x16x32_bf16 v[52:55], v[154:157], v[162:165], v[52:55]
	v_mfma_f32_16x16x32_bf16 v[44:47], v[146:149], v[170:173], v[44:47]
	v_mfma_f32_16x16x32_bf16 v[36:39], v[154:157], v[170:173], v[36:39]
	v_mfma_f32_16x16x32_bf16 v[28:31], v[146:149], v[178:181], v[28:31]
	v_mfma_f32_16x16x32_bf16 v[20:23], v[154:157], v[178:181], v[20:23]
	v_mfma_f32_16x16x32_bf16 v[12:15], v[146:149], v[186:189], v[12:15]
	v_mfma_f32_16x16x32_bf16 v[4:7], v[154:157], v[186:189], v[4:7]
	s_setprio 0
	s_barrier
	s_add_u32 s42, s42, 0x40080
	s_addc_u32 s43, s43, 0
	s_add_i32 s52, s52, s33
	v_lshl_add_u64 v[142:143], s[42:43], 0, v[220:221]
	s_mov_b32 m0, s52
	s_nop 0
	global_load_lds_dwordx4 v[142:143], off
	v_lshl_add_u64 v[142:143], s[42:43], 0, v[132:133]
	s_add_i32 m0, s52, 0x2000
	s_nop 0
	global_load_lds_dwordx4 v[142:143], off
	s_waitcnt vmcnt(6)
	s_barrier
	s_setprio 1
	v_mfma_f32_16x16x32_bf16 v[56:59], v[210:213], v[158:161], v[56:59]
	v_mfma_f32_16x16x32_bf16 v[48:51], v[234:237], v[158:161], v[48:51]
	v_mfma_f32_16x16x32_bf16 v[40:43], v[210:213], v[166:169], v[40:43]
	v_mfma_f32_16x16x32_bf16 v[32:35], v[234:237], v[166:169], v[32:35]
	v_mfma_f32_16x16x32_bf16 v[24:27], v[210:213], v[174:177], v[24:27]
	v_mfma_f32_16x16x32_bf16 v[16:19], v[234:237], v[174:177], v[16:19]
	v_mfma_f32_16x16x32_bf16 v[8:11], v[210:213], v[182:185], v[8:11]
	v_mfma_f32_16x16x32_bf16 v[0:3], v[234:237], v[182:185], v[0:3]
	v_mfma_f32_16x16x32_bf16 v[56:59], v[214:217], v[162:165], v[56:59]
	v_mfma_f32_16x16x32_bf16 v[48:51], v[238:241], v[162:165], v[48:51]
	v_mfma_f32_16x16x32_bf16 v[40:43], v[214:217], v[170:173], v[40:43]
	v_mfma_f32_16x16x32_bf16 v[32:35], v[238:241], v[170:173], v[32:35]
	v_mfma_f32_16x16x32_bf16 v[24:27], v[214:217], v[178:181], v[24:27]
	v_mfma_f32_16x16x32_bf16 v[16:19], v[238:241], v[178:181], v[16:19]
	v_mfma_f32_16x16x32_bf16 v[8:11], v[214:217], v[186:189], v[8:11]
	v_mfma_f32_16x16x32_bf16 v[0:3], v[238:241], v[186:189], v[0:3]
	s_setprio 0
	s_add_i32 s41, s41, 2
	s_add_u32 vcc_lo, vcc_lo, 0x100
	s_addc_u32 vcc_hi, vcc_hi, 0
	s_add_u32 s20, s20, 0x100
	s_addc_u32 s29, s29, 0
	s_cmp_gt_u32 s41, 13
	s_barrier
	s_cbranch_scc0 .LBB0_1858
	v_mul_f32_e32 v143, 0xbfb8aa3b, v124
	v_exp_f32_e32 v143, v143
	v_readlane_b32 s4, v254, 43
	v_lshl_or_b32 v144, s0, 7, v140
	v_readlane_b32 s5, v254, 44
	v_add_f32_e32 v143, 1.0, v143
	v_rcp_f32_e32 v146, v143
	v_mul_f32_e32 v143, 0xbfb8aa3b, v116
	v_exp_f32_e32 v143, v143
	v_lshl_add_u32 v142, s46, 8, v138
	v_ashrrev_i32_e32 v145, 31, v144
	s_and_b64 vcc, exec, s[36:37]
	v_add_f32_e32 v143, 1.0, v143
	v_rcp_f32_e32 v148, v143
	v_mul_f32_e32 v143, 0xbfb8aa3b, v125
	v_exp_f32_e32 v143, v143
	s_mov_b32 s0, s90
	s_mov_b32 s46, s40
	s_mov_b64 s[88:89], s[44:45]
	v_add_f32_e32 v143, 1.0, v143
	v_rcp_f32_e32 v147, v143
	s_mov_b64 s[42:43], s[50:51]
	s_mov_b32 s51, 0x78787879
	v_pk_mul_f32 v[124:125], v[124:125], v[146:147]
	s_nop 0
	v_pk_mul_f32 v[120:121], v[124:125], v[120:121]
	v_mul_f32_e32 v124, 0xbfb8aa3b, v117
	v_exp_f32_e32 v124, v124
	s_nop 0
	v_add_f32_e32 v124, 1.0, v124
	v_rcp_f32_e32 v149, v124
	s_nop 0
	v_pk_mul_f32 v[116:117], v[116:117], v[148:149]
	s_nop 0
	v_pk_mul_f32 v[112:113], v[116:117], v[112:113]
	v_mul_f32_e32 v117, 0xbfb8aa3b, v118
	v_exp_f32_e32 v117, v117
	v_mul_f32_e32 v116, 0xbfb8aa3b, v126
	v_exp_f32_e32 v116, v116
	v_add_f32_e32 v117, 1.0, v117
	v_rcp_f32_e32 v124, v117
	v_mul_f32_e32 v117, 0xbfb8aa3b, v127
	v_exp_f32_e32 v117, v117
	v_add_f32_e32 v116, 1.0, v116
	v_rcp_f32_e32 v116, v116
	v_add_f32_e32 v117, 1.0, v117
	v_rcp_f32_e32 v117, v117
	s_nop 0
	v_pk_mul_f32 v[116:117], v[126:127], v[116:117]
	s_nop 0
	v_pk_mul_f32 v[122:123], v[116:117], v[122:123]
	v_mul_f32_e32 v116, 0xbfb8aa3b, v119
	v_exp_f32_e32 v116, v116
	s_nop 0
	v_add_f32_e32 v116, 1.0, v116
	v_rcp_f32_e32 v125, v116
	s_nop 0
	v_pk_mul_f32 v[116:117], v[118:119], v[124:125]
	s_nop 0
	v_pk_mul_f32 v[114:115], v[116:117], v[114:115]
	v_cvt_pk_bf16_f32 v118, v112, v113
	v_mov_b64_e32 v[112:113], s[4:5]
	v_cvt_pk_bf16_f32 v116, v120, v121
	v_cvt_pk_bf16_f32 v119, v114, v115
	v_mad_i64_i32 v[120:121], s[4:5], v142, s18, v[112:113]
	v_lshlrev_b64 v[114:115], 1, v[144:145]
	v_cvt_pk_bf16_f32 v117, v122, v123
	v_lshl_add_u64 v[120:121], v[120:121], 0, v[114:115]
	global_store_dwordx4 v[120:121], v[116:119], off
	s_nop 1
	v_mul_f32_e32 v117, 0xbfb8aa3b, v100
	v_exp_f32_e32 v117, v117
	v_mul_f32_e32 v116, 0xbfb8aa3b, v108
	v_exp_f32_e32 v116, v116
	v_add_f32_e32 v117, 1.0, v117
	v_rcp_f32_e32 v118, v117
	v_mul_f32_e32 v117, 0xbfb8aa3b, v109
	v_exp_f32_e32 v117, v117
	v_add_f32_e32 v116, 1.0, v116
	v_rcp_f32_e32 v116, v116
	v_add_f32_e32 v117, 1.0, v117
	v_rcp_f32_e32 v117, v117
	s_nop 0
	v_pk_mul_f32 v[108:109], v[108:109], v[116:117]
	s_nop 0
	v_pk_mul_f32 v[104:105], v[108:109], v[104:105]
	v_mul_f32_e32 v108, 0xbfb8aa3b, v101
	v_exp_f32_e32 v108, v108
	s_nop 0
	v_add_f32_e32 v108, 1.0, v108
	v_rcp_f32_e32 v119, v108
	s_nop 0
	v_pk_mul_f32 v[100:101], v[100:101], v[118:119]
; DI float siluf_(float x) { return x * sigmoidf_(x); }
; DI u32x4 pack8v(const f32x4& a, const f32x4& b) { u32x4 w; w.x = pk2(a[0], a[1]); w.y = pk2(a[2], a[3]); w.z = pk2(b[0], b[1]); w.w = pk2(b[2], b[3]); return w; }
;   DI void operator()(const acc_t& acc, const Unit& u, int wr, int wc, int fr, int fq) const {
;     const int row0 = u.pm * BM + wr * 64 + fr, col0 = u.pn * HALF + wc * 32 + 8 * fq;
; #pragma unroll
;     for (int ai = 0; ai < 2; ++ai)
; #pragma unroll
;       for (int m = 0; m < 4; ++m) {
;         f32x4 r0, r1;
; #pragma unroll
;         for (int e = 0; e < 4; ++e) { r0[e] = siluf_(acc[ai][0][m][0][e]) * acc[ai][1][m][0][e]; r1[e] = siluf_(acc[ai][0][m][1][e]) * acc[ai][1][m][1][e]; }
;         *(u32x4*)(G + (size_t)(row0 + ai * HALF + m * 16) * DFF + col0) = pack8v(r0, r1); }
	s_nop 0
	v_pk_mul_f32 v[100:101], v[100:101], v[96:97]
	v_mul_f32_e32 v97, 0xbfb8aa3b, v102
	v_exp_f32_e32 v97, v97
	v_mul_f32_e32 v96, 0xbfb8aa3b, v110
	v_exp_f32_e32 v96, v96
	v_add_f32_e32 v97, 1.0, v97
	v_rcp_f32_e32 v108, v97
	v_mul_f32_e32 v97, 0xbfb8aa3b, v111
	v_exp_f32_e32 v97, v97
	v_add_f32_e32 v96, 1.0, v96
	v_rcp_f32_e32 v96, v96
	v_add_f32_e32 v97, 1.0, v97
	v_rcp_f32_e32 v97, v97
	s_nop 0
	v_pk_mul_f32 v[96:97], v[110:111], v[96:97]
	s_nop 0
	v_pk_mul_f32 v[106:107], v[96:97], v[106:107]
	v_mul_f32_e32 v96, 0xbfb8aa3b, v103
	v_exp_f32_e32 v96, v96
	s_nop 0
	v_add_f32_e32 v96, 1.0, v96
	v_rcp_f32_e32 v109, v96
	s_nop 0
	v_pk_mul_f32 v[96:97], v[102:103], v[108:109]
	s_nop 0
	v_pk_mul_f32 v[102:103], v[96:97], v[98:99]
	v_cvt_pk_bf16_f32 v98, v100, v101
	v_or_b32_e32 v100, 16, v142
	v_mad_i64_i32 v[100:101], s[4:5], v100, s18, v[112:113]
	v_cvt_pk_bf16_f32 v96, v104, v105
	v_cvt_pk_bf16_f32 v97, v106, v107
	v_cvt_pk_bf16_f32 v99, v102, v103
	v_lshl_add_u64 v[100:101], v[100:101], 0, v[114:115]
	global_store_dwordx4 v[100:101], v[96:99], off
	s_nop 1
	v_mul_f32_e32 v97, 0xbfb8aa3b, v84
	v_exp_f32_e32 v97, v97
	v_mul_f32_e32 v96, 0xbfb8aa3b, v92
	v_exp_f32_e32 v96, v96
	v_add_f32_e32 v97, 1.0, v97
	v_rcp_f32_e32 v98, v97
	v_mul_f32_e32 v97, 0xbfb8aa3b, v93
	v_exp_f32_e32 v97, v97
	v_add_f32_e32 v96, 1.0, v96
	v_rcp_f32_e32 v96, v96
	v_add_f32_e32 v97, 1.0, v97
	v_rcp_f32_e32 v97, v97
	s_nop 0
	v_pk_mul_f32 v[92:93], v[92:93], v[96:97]
	s_nop 0
	v_pk_mul_f32 v[88:89], v[92:93], v[88:89]
	v_mul_f32_e32 v92, 0xbfb8aa3b, v85
	v_exp_f32_e32 v92, v92
	s_nop 0
	v_add_f32_e32 v92, 1.0, v92
	v_rcp_f32_e32 v99, v92
	s_nop 0
	v_pk_mul_f32 v[84:85], v[84:85], v[98:99]
	s_nop 0
	v_pk_mul_f32 v[84:85], v[84:85], v[80:81]
	v_mul_f32_e32 v81, 0xbfb8aa3b, v86
	v_exp_f32_e32 v81, v81
	v_mul_f32_e32 v80, 0xbfb8aa3b, v94
	v_exp_f32_e32 v80, v80
	v_add_f32_e32 v81, 1.0, v81
	v_rcp_f32_e32 v92, v81
	v_mul_f32_e32 v81, 0xbfb8aa3b, v95
	v_exp_f32_e32 v81, v81
	v_add_f32_e32 v80, 1.0, v80
	v_rcp_f32_e32 v80, v80
	v_add_f32_e32 v81, 1.0, v81
	v_rcp_f32_e32 v81, v81
	s_nop 0
	v_pk_mul_f32 v[80:81], v[94:95], v[80:81]
	s_nop 0
	v_pk_mul_f32 v[90:91], v[80:81], v[90:91]
	v_mul_f32_e32 v80, 0xbfb8aa3b, v87
	v_exp_f32_e32 v80, v80
	s_nop 0
	v_add_f32_e32 v80, 1.0, v80
	v_rcp_f32_e32 v93, v80
	s_nop 0
	v_pk_mul_f32 v[80:81], v[86:87], v[92:93]
	s_nop 0
	v_pk_mul_f32 v[86:87], v[80:81], v[82:83]
	v_cvt_pk_bf16_f32 v82, v84, v85
	v_or_b32_e32 v84, 32, v142
	v_mad_i64_i32 v[84:85], s[4:5], v84, s18, v[112:113]
	v_cvt_pk_bf16_f32 v80, v88, v89
	v_cvt_pk_bf16_f32 v81, v90, v91
	v_cvt_pk_bf16_f32 v83, v86, v87
	v_lshl_add_u64 v[84:85], v[84:85], 0, v[114:115]
	global_store_dwordx4 v[84:85], v[80:83], off
	s_nop 1
	v_mul_f32_e32 v81, 0xbfb8aa3b, v68
	v_exp_f32_e32 v81, v81
	v_mul_f32_e32 v80, 0xbfb8aa3b, v76
	v_exp_f32_e32 v80, v80
	v_add_f32_e32 v81, 1.0, v81
	v_rcp_f32_e32 v82, v81
	v_mul_f32_e32 v81, 0xbfb8aa3b, v77
	v_exp_f32_e32 v81, v81
	v_add_f32_e32 v80, 1.0, v80
	v_rcp_f32_e32 v80, v80
	v_add_f32_e32 v81, 1.0, v81
	v_rcp_f32_e32 v81, v81
	s_nop 0
	v_pk_mul_f32 v[76:77], v[76:77], v[80:81]
	s_nop 0
	v_pk_mul_f32 v[72:73], v[76:77], v[72:73]
	v_mul_f32_e32 v76, 0xbfb8aa3b, v69
	v_exp_f32_e32 v76, v76
	s_nop 0
	v_add_f32_e32 v76, 1.0, v76
	v_rcp_f32_e32 v83, v76
	s_nop 0
	v_pk_mul_f32 v[68:69], v[68:69], v[82:83]
	s_nop 0
	v_pk_mul_f32 v[68:69], v[68:69], v[64:65]
	v_mul_f32_e32 v65, 0xbfb8aa3b, v70
	v_exp_f32_e32 v65, v65
	v_mul_f32_e32 v64, 0xbfb8aa3b, v78
	v_exp_f32_e32 v64, v64
	v_add_f32_e32 v65, 1.0, v65
	v_rcp_f32_e32 v76, v65
	v_mul_f32_e32 v65, 0xbfb8aa3b, v79
	v_exp_f32_e32 v65, v65
	v_add_f32_e32 v64, 1.0, v64
	v_rcp_f32_e32 v64, v64
	v_add_f32_e32 v65, 1.0, v65
	v_rcp_f32_e32 v65, v65
	s_nop 0
	v_pk_mul_f32 v[64:65], v[78:79], v[64:65]
	s_nop 0
	v_pk_mul_f32 v[74:75], v[64:65], v[74:75]
	v_mul_f32_e32 v64, 0xbfb8aa3b, v71
	v_exp_f32_e32 v64, v64
	s_nop 0
	v_add_f32_e32 v64, 1.0, v64
	v_rcp_f32_e32 v77, v64
	s_nop 0
	v_pk_mul_f32 v[64:65], v[70:71], v[76:77]
	s_nop 0
	v_pk_mul_f32 v[70:71], v[64:65], v[66:67]
	v_cvt_pk_bf16_f32 v66, v68, v69
	v_or_b32_e32 v68, 48, v142
	v_mad_i64_i32 v[68:69], s[4:5], v68, s18, v[112:113]
	v_cvt_pk_bf16_f32 v64, v72, v73
	v_cvt_pk_bf16_f32 v65, v74, v75
	v_cvt_pk_bf16_f32 v67, v70, v71
	v_lshl_add_u64 v[68:69], v[68:69], 0, v[114:115]
	global_store_dwordx4 v[68:69], v[64:67], off
	v_add_u32_e32 v68, 0x80, v142
	s_nop 0
	v_mul_f32_e32 v65, 0xbfb8aa3b, v52
	v_exp_f32_e32 v65, v65
	v_mul_f32_e32 v64, 0xbfb8aa3b, v60
	v_exp_f32_e32 v64, v64
	v_add_f32_e32 v65, 1.0, v65
	v_rcp_f32_e32 v66, v65
	v_mul_f32_e32 v65, 0xbfb8aa3b, v61
	v_exp_f32_e32 v65, v65
	v_add_f32_e32 v64, 1.0, v64
	v_rcp_f32_e32 v64, v64
	v_add_f32_e32 v65, 1.0, v65
	v_rcp_f32_e32 v65, v65
	s_nop 0
	v_pk_mul_f32 v[60:61], v[60:61], v[64:65]
	s_nop 0
	v_pk_mul_f32 v[56:57], v[60:61], v[56:57]
	v_mul_f32_e32 v60, 0xbfb8aa3b, v53
	v_exp_f32_e32 v60, v60
	s_nop 0
	v_add_f32_e32 v60, 1.0, v60
	v_rcp_f32_e32 v67, v60
	s_nop 0
	v_pk_mul_f32 v[52:53], v[52:53], v[66:67]
	s_nop 0
	v_pk_mul_f32 v[52:53], v[52:53], v[48:49]
	v_mul_f32_e32 v49, 0xbfb8aa3b, v54
	v_exp_f32_e32 v49, v49
	v_mul_f32_e32 v48, 0xbfb8aa3b, v62
	v_exp_f32_e32 v48, v48
	v_add_f32_e32 v49, 1.0, v49
	v_rcp_f32_e32 v60, v49
	v_mul_f32_e32 v49, 0xbfb8aa3b, v63
	v_exp_f32_e32 v49, v49
	v_add_f32_e32 v48, 1.0, v48
	v_rcp_f32_e32 v48, v48
	v_add_f32_e32 v49, 1.0, v49
	v_rcp_f32_e32 v49, v49
	s_nop 0
	v_pk_mul_f32 v[48:49], v[62:63], v[48:49]
	s_nop 0
	v_pk_mul_f32 v[58:59], v[48:49], v[58:59]
; DI float siluf_(float x) { return x * sigmoidf_(x); }
; #define PG8_WAIT_V(n) asm volatile("s_waitcnt vmcnt(" #n ")" ::: "memory")
; #define PG8_BAR __builtin_amdgcn_s_barrier()
; DI u32x4 pack8v(const f32x4& a, const f32x4& b) { u32x4 w; w.x = pk2(a[0], a[1]); w.y = pk2(a[2], a[3]); w.z = pk2(b[0], b[1]); w.w = pk2(b[2], b[3]); return w; }
; #define PG8_WAIT_V(n) asm volatile("s_waitcnt vmcnt(" #n ")" ::: "memory")
; #define PG8_BAR __builtin_amdgcn_s_barrier()
; template <class Epi>
; DI void gemm_phase(char* smem, const bf16_t* A, int lda, const bf16_t* Bt, int ldb, int K, const Order& S_, const Epi& E) {
;     ...
;     E(acc, cur, wr, wc, fr, fq);
;     if (!has_next) break;
; #pragma unroll
;     for (int a = 0; a < 2; ++a)
; #pragma unroll
;       for (int b = 0; b < 2; ++b)
; #pragma unroll
;         for (int m = 0; m < 4; ++m)
; #pragma unroll
;           for (int n = 0; n < 2; ++n) acc[a][b][m][n] = (f32x4){0.f, 0.f, 0.f, 0.f};
;     cur = nxt; cA = nA; cB = nB; ++ui;
;   }
;   PG8_WAIT_V(0);
;   if (wr == 0) PG8_BAR;
;   PG8_BAR;
;   DI void operator()(const acc_t& acc, const Unit& u, int wr, int wc, int fr, int fq) const {
;     const int row0 = u.pm * BM + wr * 64 + fr, col0 = u.pn * HALF + wc * 32 + 8 * fq;
; #pragma unroll
;     for (int ai = 0; ai < 2; ++ai)
; #pragma unroll
;       for (int m = 0; m < 4; ++m) {
;         f32x4 r0, r1;
; #pragma unroll
;         for (int e = 0; e < 4; ++e) { r0[e] = siluf_(acc[ai][0][m][0][e]) * acc[ai][1][m][0][e]; r1[e] = siluf_(acc[ai][0][m][1][e]) * acc[ai][1][m][1][e]; }
;         *(u32x4*)(G + (size_t)(row0 + ai * HALF + m * 16) * DFF + col0) = pack8v(r0, r1); }
	v_mul_f32_e32 v48, 0xbfb8aa3b, v55
	v_exp_f32_e32 v48, v48
	s_nop 0
	v_add_f32_e32 v48, 1.0, v48
	v_rcp_f32_e32 v61, v48
	s_nop 0
	v_pk_mul_f32 v[48:49], v[54:55], v[60:61]
	s_nop 0
	v_pk_mul_f32 v[54:55], v[48:49], v[50:51]
	v_cvt_pk_bf16_f32 v50, v52, v53
	v_mad_i64_i32 v[52:53], s[4:5], v68, s18, v[112:113]
	v_cvt_pk_bf16_f32 v48, v56, v57
	v_cvt_pk_bf16_f32 v49, v58, v59
	v_cvt_pk_bf16_f32 v51, v54, v55
	v_lshl_add_u64 v[52:53], v[52:53], 0, v[114:115]
	global_store_dwordx4 v[52:53], v[48:51], off
	s_nop 1
	v_mul_f32_e32 v49, 0xbfb8aa3b, v36
	v_exp_f32_e32 v49, v49
	v_mul_f32_e32 v48, 0xbfb8aa3b, v44
	v_exp_f32_e32 v48, v48
	v_add_f32_e32 v49, 1.0, v49
	v_rcp_f32_e32 v50, v49
	v_mul_f32_e32 v49, 0xbfb8aa3b, v45
	v_exp_f32_e32 v49, v49
	v_add_f32_e32 v48, 1.0, v48
	v_rcp_f32_e32 v48, v48
	v_add_f32_e32 v49, 1.0, v49
	v_rcp_f32_e32 v49, v49
	s_nop 0
	v_pk_mul_f32 v[44:45], v[44:45], v[48:49]
	s_nop 0
	v_pk_mul_f32 v[40:41], v[44:45], v[40:41]
	v_mul_f32_e32 v44, 0xbfb8aa3b, v37
	v_exp_f32_e32 v44, v44
	s_nop 0
	v_add_f32_e32 v44, 1.0, v44
	v_rcp_f32_e32 v51, v44
	s_nop 0
	v_pk_mul_f32 v[36:37], v[36:37], v[50:51]
	s_nop 0
	v_pk_mul_f32 v[36:37], v[36:37], v[32:33]
	v_mul_f32_e32 v33, 0xbfb8aa3b, v38
	v_exp_f32_e32 v33, v33
	v_mul_f32_e32 v32, 0xbfb8aa3b, v46
	v_exp_f32_e32 v32, v32
	v_add_f32_e32 v33, 1.0, v33
	v_rcp_f32_e32 v44, v33
	v_mul_f32_e32 v33, 0xbfb8aa3b, v47
	v_exp_f32_e32 v33, v33
	v_add_f32_e32 v32, 1.0, v32
	v_rcp_f32_e32 v32, v32
	v_add_f32_e32 v33, 1.0, v33
	v_rcp_f32_e32 v33, v33
	s_nop 0
	v_pk_mul_f32 v[32:33], v[46:47], v[32:33]
	s_nop 0
	v_pk_mul_f32 v[42:43], v[32:33], v[42:43]
	v_mul_f32_e32 v32, 0xbfb8aa3b, v39
	v_exp_f32_e32 v32, v32
	s_nop 0
	v_add_f32_e32 v32, 1.0, v32
	v_rcp_f32_e32 v45, v32
	s_nop 0
	v_pk_mul_f32 v[32:33], v[38:39], v[44:45]
	s_nop 0
	v_pk_mul_f32 v[38:39], v[32:33], v[34:35]
	v_cvt_pk_bf16_f32 v34, v36, v37
	v_add_u32_e32 v36, 0x90, v142
	v_mad_i64_i32 v[36:37], s[4:5], v36, s18, v[112:113]
	v_cvt_pk_bf16_f32 v32, v40, v41
	v_cvt_pk_bf16_f32 v33, v42, v43
	v_cvt_pk_bf16_f32 v35, v38, v39
	v_lshl_add_u64 v[36:37], v[36:37], 0, v[114:115]
	global_store_dwordx4 v[36:37], v[32:35], off
	s_nop 1
	v_mul_f32_e32 v33, 0xbfb8aa3b, v20
	v_exp_f32_e32 v33, v33
	v_mul_f32_e32 v32, 0xbfb8aa3b, v28
	v_exp_f32_e32 v32, v32
	v_add_f32_e32 v33, 1.0, v33
	v_rcp_f32_e32 v34, v33
	v_mul_f32_e32 v33, 0xbfb8aa3b, v29
	v_exp_f32_e32 v33, v33
	v_add_f32_e32 v32, 1.0, v32
	v_rcp_f32_e32 v32, v32
	v_add_f32_e32 v33, 1.0, v33
	v_rcp_f32_e32 v33, v33
	s_nop 0
	v_pk_mul_f32 v[28:29], v[28:29], v[32:33]
	s_nop 0
	v_pk_mul_f32 v[24:25], v[28:29], v[24:25]
	v_mul_f32_e32 v28, 0xbfb8aa3b, v21
	v_exp_f32_e32 v28, v28
	s_nop 0
	v_add_f32_e32 v28, 1.0, v28
	v_rcp_f32_e32 v35, v28
	s_nop 0
	v_pk_mul_f32 v[20:21], v[20:21], v[34:35]
	s_nop 0
	v_pk_mul_f32 v[20:21], v[20:21], v[16:17]
	v_mul_f32_e32 v17, 0xbfb8aa3b, v22
	v_exp_f32_e32 v17, v17
	v_mul_f32_e32 v16, 0xbfb8aa3b, v30
	v_exp_f32_e32 v16, v16
	v_add_f32_e32 v17, 1.0, v17
	v_rcp_f32_e32 v28, v17
	v_mul_f32_e32 v17, 0xbfb8aa3b, v31
	v_exp_f32_e32 v17, v17
	v_add_f32_e32 v16, 1.0, v16
	v_rcp_f32_e32 v16, v16
	v_add_f32_e32 v17, 1.0, v17
	v_rcp_f32_e32 v17, v17
	s_nop 0
	v_pk_mul_f32 v[16:17], v[30:31], v[16:17]
	s_nop 0
	v_pk_mul_f32 v[26:27], v[16:17], v[26:27]
	v_mul_f32_e32 v16, 0xbfb8aa3b, v23
	v_exp_f32_e32 v16, v16
	s_nop 0
	v_add_f32_e32 v16, 1.0, v16
	v_rcp_f32_e32 v29, v16
	s_nop 0
	v_pk_mul_f32 v[16:17], v[22:23], v[28:29]
	s_nop 0
	v_pk_mul_f32 v[22:23], v[16:17], v[18:19]
	v_cvt_pk_bf16_f32 v18, v20, v21
	v_add_u32_e32 v20, 0xa0, v142
	v_mad_i64_i32 v[20:21], s[4:5], v20, s18, v[112:113]
	v_cvt_pk_bf16_f32 v16, v24, v25
	v_cvt_pk_bf16_f32 v17, v26, v27
	v_cvt_pk_bf16_f32 v19, v22, v23
	v_lshl_add_u64 v[20:21], v[20:21], 0, v[114:115]
	global_store_dwordx4 v[20:21], v[16:19], off
	s_nop 1
	v_mul_f32_e32 v17, 0xbfb8aa3b, v4
	v_exp_f32_e32 v17, v17
	v_mul_f32_e32 v16, 0xbfb8aa3b, v12
	v_exp_f32_e32 v16, v16
	v_add_f32_e32 v17, 1.0, v17
	v_rcp_f32_e32 v18, v17
	v_mul_f32_e32 v17, 0xbfb8aa3b, v13
	v_exp_f32_e32 v17, v17
	v_add_f32_e32 v16, 1.0, v16
	v_rcp_f32_e32 v16, v16
	v_add_f32_e32 v17, 1.0, v17
	v_rcp_f32_e32 v17, v17
	s_nop 0
	v_pk_mul_f32 v[12:13], v[12:13], v[16:17]
	s_nop 0
	v_pk_mul_f32 v[8:9], v[12:13], v[8:9]
	v_mul_f32_e32 v12, 0xbfb8aa3b, v5
	v_exp_f32_e32 v12, v12
	s_nop 0
	v_add_f32_e32 v12, 1.0, v12
	v_rcp_f32_e32 v19, v12
	s_nop 0
	v_pk_mul_f32 v[4:5], v[4:5], v[18:19]
	s_nop 0
	v_pk_mul_f32 v[4:5], v[4:5], v[0:1]
	v_mul_f32_e32 v1, 0xbfb8aa3b, v6
	v_exp_f32_e32 v1, v1
	v_mul_f32_e32 v0, 0xbfb8aa3b, v14
	v_exp_f32_e32 v0, v0
	v_add_f32_e32 v1, 1.0, v1
	v_rcp_f32_e32 v12, v1
	v_mul_f32_e32 v1, 0xbfb8aa3b, v15
	v_exp_f32_e32 v1, v1
	v_add_f32_e32 v0, 1.0, v0
	v_rcp_f32_e32 v0, v0
	v_add_f32_e32 v1, 1.0, v1
	v_rcp_f32_e32 v1, v1
	s_nop 0
	v_pk_mul_f32 v[0:1], v[14:15], v[0:1]
	s_nop 0
	v_pk_mul_f32 v[10:11], v[0:1], v[10:11]
	v_mul_f32_e32 v0, 0xbfb8aa3b, v7
	v_exp_f32_e32 v0, v0
	s_nop 0
	v_add_f32_e32 v0, 1.0, v0
	v_rcp_f32_e32 v13, v0
	s_nop 0
	v_pk_mul_f32 v[0:1], v[6:7], v[12:13]
	s_nop 0
	v_pk_mul_f32 v[6:7], v[0:1], v[2:3]
	v_cvt_pk_bf16_f32 v2, v4, v5
	v_add_u32_e32 v4, 0xb0, v142
	v_mad_i64_i32 v[4:5], s[4:5], v4, s18, v[112:113]
	v_cvt_pk_bf16_f32 v0, v8, v9
	v_cvt_pk_bf16_f32 v1, v10, v11
	v_cvt_pk_bf16_f32 v3, v6, v7
	v_lshl_add_u64 v[4:5], v[4:5], 0, v[114:115]
	global_store_dwordx4 v[4:5], v[0:3], off
	s_cbranch_vccz .LBB0_1854
	s_waitcnt vmcnt(0)
	s_cmpk_gt_u32 s3, 0xff
	s_cbranch_scc1 .LBB0_1862
	s_barrier

; #define PG8_STAGE(bufoff, gbase, voff) do { _Pragma("unroll") for (int _i = 0; _i < 2; ++_i) \
;     __builtin_amdgcn_global_load_lds((const unsigned*)((const char*)(gbase) + (voff)[_i]), (LAS unsigned*)(lds + (bufoff) + ldsw + _i * 8192), 16, 0, 0); } while (0)
; #define PG8_LDA(dst, b, h) do { _Pragma("unroll") for (int m = 0; m < 4; ++m) _Pragma("unroll") for (int k = 0; k < 2; ++k) dst[m][k] = *(const LAS bf16x8*)(lds + PG8_SA(b, h) + aoff + m * 2048 + k * 1024); } while (0)
; #define PG8_LDB(dst, b, h) do { _Pragma("unroll") for (int n = 0; n < 2; ++n) _Pragma("unroll") for (int k = 0; k < 2; ++k) dst[n][k] = *(const LAS bf16x8*)(lds + PG8_SB(b, h) + boff + n * 2048 + k * 1024); } while (0)
; #define PG8_MMA(ai, bj, At, Bt_) do { __builtin_amdgcn_s_setprio(1); _Pragma("unroll") for (int m = 0; m < 4; ++m) _Pragma("unroll") for (int n = 0; n < 2; ++n) _Pragma("unroll") for (int k = 0; k < 2; ++k) \
;     acc[ai][bj][m][n] = __builtin_amdgcn_mfma_f32_16x16x32_bf16(Bt_[n][k], At[m][k], acc[ai][bj][m][n], 0, 0, 0); __builtin_amdgcn_s_setprio(0); } while (0)
; #define PG8_WAIT_L(n) asm volatile("s_waitcnt lgkmcnt(" #n ")" ::: "memory")
; #define PG8_BAR __builtin_amdgcn_s_barrier()
; #define PG8_SCHED __builtin_amdgcn_sched_barrier(0)
; #define PG8_LDA(dst, b, h) do { _Pragma("unroll") for (int m = 0; m < 4; ++m) _Pragma("unroll") for (int k = 0; k < 2; ++k) dst[m][k] = *(const LAS bf16x8*)(lds + PG8_SA(b, h) + aoff + m * 2048 + k * 1024); } while (0)
; #define PG8_LDB(dst, b, h) do { _Pragma("unroll") for (int n = 0; n < 2; ++n) _Pragma("unroll") for (int k = 0; k < 2; ++k) dst[n][k] = *(const LAS bf16x8*)(lds + PG8_SB(b, h) + boff + n * 2048 + k * 1024); } while (0)
; #define PG8_WAIT_L(n) asm volatile("s_waitcnt lgkmcnt(" #n ")" ::: "memory")
; template <class Epi>
; DI void gemm_phase(char* smem, const bf16_t* A, int lda, const bf16_t* Bt, int ldb, int K, const Order& S_, const Epi& E) {
;     ...
;       PG8_LDB(B0, 0, 0); PG8_SCHED; PG8_LDA(At, 0, 0); PG8_STAGE(PG8_SA(1, 1), a1 + hstepA, voffA);
;       PG8_WAIT_L(8); PG8_BAR; PG8_WAIT_L(0); PG8_MMA(0, 0, At, B0); PG8_BAR; PG8_SCHED;
;       PG8_LDB(B1, 0, 1); PG8_STAGE(PG8_SB(0, 0), b2, voffB);
;       PG8_BAR; PG8_WAIT_L(0); PG8_MMA(0, 1, At, B1); PG8_BAR;
;       PG8_LDA(At, 0, 1); PG8_STAGE(PG8_SA(0, 0), a2, voffA);
;       PG8_BAR; PG8_WAIT_L(0); PG8_MMA(1, 0, At, B0); PG8_BAR; PG8_SCHED;
.LBB0_1929:
	s_add_u32 s44, s42, 0x100
	s_addc_u32 s45, s43, 0
	s_add_i32 s57, 0, 0x10000
	v_add_u32_e32 v140, s57, v153
	ds_read_b128 v[128:131], v140
	ds_read_b128 v[132:135], v140 offset:1024
	ds_read_b128 v[136:139], v140 offset:2048
	ds_read_b128 v[140:143], v140 offset:3072
	s_cmp_eq_u32 s56, 40
	s_cselect_b32 s51, s1, s45
	s_cselect_b32 s50, s0, s44
	s_cselect_b32 s47, s41, s53
	s_cselect_b32 s46, s40, s52
	v_lshl_add_u64 v[150:151], s[42:43], 0, v[146:147]
	s_add_i32 m0, s27, 0xc000
	ds_read_b128 v[156:159], v155
	ds_read_b128 v[160:163], v155 offset:1024
	ds_read_b128 v[164:167], v155 offset:2048
	ds_read_b128 v[168:171], v155 offset:3072
	ds_read_b128 v[172:175], v155 offset:4096
	ds_read_b128 v[176:179], v155 offset:5120
	ds_read_b128 v[180:183], v155 offset:6144
	ds_read_b128 v[184:187], v155 offset:7168
	global_load_lds_dwordx4 v[150:151], off
	v_lshl_add_u64 v[150:151], s[42:43], 0, v[148:149]
	s_add_i32 m0, s27, 0xe000
	s_nop 0
	global_load_lds_dwordx4 v[150:151], off
	s_waitcnt lgkmcnt(8)
	s_barrier
	s_waitcnt lgkmcnt(0)
	s_setprio 1
	v_mfma_f32_16x16x32_bf16 v[124:127], v[128:131], v[156:159], v[124:127]
	v_mfma_f32_16x16x32_bf16 v[120:123], v[136:139], v[156:159], v[120:123]
	v_mfma_f32_16x16x32_bf16 v[116:119], v[128:131], v[164:167], v[116:119]
	v_mfma_f32_16x16x32_bf16 v[108:111], v[136:139], v[164:167], v[108:111]
	v_mfma_f32_16x16x32_bf16 v[92:95], v[128:131], v[172:175], v[92:95]
	v_mfma_f32_16x16x32_bf16 v[88:91], v[136:139], v[172:175], v[88:91]
	v_mfma_f32_16x16x32_bf16 v[84:87], v[128:131], v[180:183], v[84:87]
	v_mfma_f32_16x16x32_bf16 v[80:83], v[136:139], v[180:183], v[80:83]
	v_mfma_f32_16x16x32_bf16 v[124:127], v[132:135], v[160:163], v[124:127]
	v_mfma_f32_16x16x32_bf16 v[120:123], v[140:143], v[160:163], v[120:123]
	v_mfma_f32_16x16x32_bf16 v[116:119], v[132:135], v[168:171], v[116:119]
	v_mfma_f32_16x16x32_bf16 v[108:111], v[140:143], v[168:171], v[108:111]
	v_mfma_f32_16x16x32_bf16 v[92:95], v[132:135], v[176:179], v[92:95]
	v_mfma_f32_16x16x32_bf16 v[88:91], v[140:143], v[176:179], v[88:91]
	v_mfma_f32_16x16x32_bf16 v[84:87], v[132:135], v[184:187], v[84:87]
	v_mfma_f32_16x16x32_bf16 v[80:83], v[140:143], v[184:187], v[80:83]
	s_setprio 0
	s_barrier
	s_add_i32 s60, 0, 0x14000
	v_add_u32_e32 v150, s60, v153
	s_add_i32 s42, s57, s15
	ds_read_b128 v[188:191], v150
	ds_read_b128 v[210:213], v150 offset:1024
	ds_read_b128 v[214:217], v150 offset:2048
	ds_read_b128 v[234:237], v150 offset:3072
	v_lshl_add_u64 v[150:151], s[46:47], 0, v[220:221]
	s_mov_b32 m0, s42
	v_lshl_add_u64 v[194:195], s[46:47], 0, v[144:145]
	global_load_lds_dwordx4 v[150:151], off
	s_add_i32 m0, s42, 0x2000
	s_nop 0
	global_load_lds_dwordx4 v[194:195], off
	s_barrier
	s_waitcnt lgkmcnt(0)
	s_setprio 1
	v_mfma_f32_16x16x32_bf16 v[112:115], v[188:191], v[156:159], v[112:115]
	v_mfma_f32_16x16x32_bf16 v[104:107], v[214:217], v[156:159], v[104:107]
	v_mfma_f32_16x16x32_bf16 v[100:103], v[188:191], v[164:167], v[100:103]
	v_mfma_f32_16x16x32_bf16 v[96:99], v[214:217], v[164:167], v[96:99]
	v_mfma_f32_16x16x32_bf16 v[76:79], v[188:191], v[172:175], v[76:79]
	v_mfma_f32_16x16x32_bf16 v[72:75], v[214:217], v[172:175], v[72:75]
	v_mfma_f32_16x16x32_bf16 v[68:71], v[188:191], v[180:183], v[68:71]
	v_mfma_f32_16x16x32_bf16 v[64:67], v[214:217], v[180:183], v[64:67]
	v_mfma_f32_16x16x32_bf16 v[112:115], v[210:213], v[160:163], v[112:115]
	v_mfma_f32_16x16x32_bf16 v[104:107], v[234:237], v[160:163], v[104:107]
	v_mfma_f32_16x16x32_bf16 v[100:103], v[210:213], v[168:171], v[100:103]
	v_mfma_f32_16x16x32_bf16 v[96:99], v[234:237], v[168:171], v[96:99]
	v_mfma_f32_16x16x32_bf16 v[76:79], v[210:213], v[176:179], v[76:79]
	v_mfma_f32_16x16x32_bf16 v[72:75], v[234:237], v[176:179], v[72:75]
	v_mfma_f32_16x16x32_bf16 v[68:71], v[210:213], v[184:187], v[68:71]
	v_mfma_f32_16x16x32_bf16 v[64:67], v[234:237], v[184:187], v[64:67]
	s_setprio 0
	s_mov_b32 m0, s27
	v_lshl_add_u64 v[200:201], s[50:51], 0, v[220:221]
	s_barrier
	ds_read_b128 v[156:159], v155 offset:16384
	ds_read_b128 v[160:163], v155 offset:17408
	ds_read_b128 v[164:167], v155 offset:18432
	ds_read_b128 v[168:171], v155 offset:19456
	ds_read_b128 v[172:175], v155 offset:20480
	ds_read_b128 v[176:179], v155 offset:21504
	ds_read_b128 v[180:183], v155 offset:22528
	ds_read_b128 v[184:187], v155 offset:23552
	global_load_lds_dwordx4 v[200:201], off
	v_lshl_add_u64 v[202:203], s[50:51], 0, v[144:145]
	s_mov_b32 m0, s29
	s_nop 0
	global_load_lds_dwordx4 v[202:203], off
	s_barrier
	s_waitcnt lgkmcnt(0)
	s_setprio 1
	v_mfma_f32_16x16x32_bf16 v[60:63], v[128:131], v[156:159], v[60:63]
	v_mfma_f32_16x16x32_bf16 v[56:59], v[136:139], v[156:159], v[56:59]
	v_mfma_f32_16x16x32_bf16 v[52:55], v[128:131], v[164:167], v[52:55]
	v_mfma_f32_16x16x32_bf16 v[48:51], v[136:139], v[164:167], v[48:51]
	v_mfma_f32_16x16x32_bf16 v[28:31], v[128:131], v[172:175], v[28:31]
	v_mfma_f32_16x16x32_bf16 v[24:27], v[136:139], v[172:175], v[24:27]
	v_mfma_f32_16x16x32_bf16 v[20:23], v[128:131], v[180:183], v[20:23]
	v_mfma_f32_16x16x32_bf16 v[16:19], v[136:139], v[180:183], v[16:19]
	v_mfma_f32_16x16x32_bf16 v[60:63], v[132:135], v[160:163], v[60:63]
	v_mfma_f32_16x16x32_bf16 v[56:59], v[140:143], v[160:163], v[56:59]
	v_mfma_f32_16x16x32_bf16 v[52:55], v[132:135], v[168:171], v[52:55]
	v_mfma_f32_16x16x32_bf16 v[48:51], v[140:143], v[168:171], v[48:51]
	v_mfma_f32_16x16x32_bf16 v[28:31], v[132:135], v[176:179], v[28:31]
	v_mfma_f32_16x16x32_bf16 v[24:27], v[140:143], v[176:179], v[24:27]
	v_mfma_f32_16x16x32_bf16 v[20:23], v[132:135], v[184:187], v[20:23]
	v_mfma_f32_16x16x32_bf16 v[16:19], v[140:143], v[184:187], v[16:19]
	s_setprio 0
	s_barrier
; #define PG8_STAGE(bufoff, gbase, voff) do { _Pragma("unroll") for (int _i = 0; _i < 2; ++_i) \
;     __builtin_amdgcn_global_load_lds((const unsigned*)((const char*)(gbase) + (voff)[_i]), (LAS unsigned*)(lds + (bufoff) + ldsw + _i * 8192), 16, 0, 0); } while (0)
; #define PG8_LDA(dst, b, h) do { _Pragma("unroll") for (int m = 0; m < 4; ++m) _Pragma("unroll") for (int k = 0; k < 2; ++k) dst[m][k] = *(const LAS bf16x8*)(lds + PG8_SA(b, h) + aoff + m * 2048 + k * 1024); } while (0)
; #define PG8_LDB(dst, b, h) do { _Pragma("unroll") for (int n = 0; n < 2; ++n) _Pragma("unroll") for (int k = 0; k < 2; ++k) dst[n][k] = *(const LAS bf16x8*)(lds + PG8_SB(b, h) + boff + n * 2048 + k * 1024); } while (0)
; #define PG8_MMA(ai, bj, At, Bt_) do { __builtin_amdgcn_s_setprio(1); _Pragma("unroll") for (int m = 0; m < 4; ++m) _Pragma("unroll") for (int n = 0; n < 2; ++n) _Pragma("unroll") for (int k = 0; k < 2; ++k) \
;     acc[ai][bj][m][n] = __builtin_amdgcn_mfma_f32_16x16x32_bf16(Bt_[n][k], At[m][k], acc[ai][bj][m][n], 0, 0, 0); __builtin_amdgcn_s_setprio(0); } while (0)
; #define PG8_WAIT_V(n) asm volatile("s_waitcnt vmcnt(" #n ")" ::: "memory")
; #define PG8_WAIT_L(n) asm volatile("s_waitcnt lgkmcnt(" #n ")" ::: "memory")
; #define PG8_BAR __builtin_amdgcn_s_barrier()
; #define PG8_SCHED __builtin_amdgcn_sched_barrier(0)
; #define PG8_LDA(dst, b, h) do { _Pragma("unroll") for (int m = 0; m < 4; ++m) _Pragma("unroll") for (int k = 0; k < 2; ++k) dst[m][k] = *(const LAS bf16x8*)(lds + PG8_SA(b, h) + aoff + m * 2048 + k * 1024); } while (0)
; #define PG8_WAIT_V(n) asm volatile("s_waitcnt vmcnt(" #n ")" ::: "memory")
; template <class Epi>
; DI void gemm_phase(char* smem, const bf16_t* A, int lda, const bf16_t* Bt, int ldb, int K, const Order& S_, const Epi& E) {
;     ...
;       PG8_STAGE(PG8_SB(0, 1), b2 + hstepB, voffB);
;       PG8_WAIT_V(6); PG8_BAR; PG8_MMA(1, 1, At, B1); PG8_BAR;
;       PG8_LDB(B0, 1, 0); PG8_SCHED; PG8_LDA(At, 1, 0); PG8_STAGE(PG8_SA(0, 1), a2 + hstepA, voffA);
;       PG8_WAIT_L(8); PG8_BAR; PG8_WAIT_L(0); PG8_MMA(0, 0, At, B0); PG8_BAR; PG8_SCHED;
;       PG8_LDB(B1, 1, 1); PG8_STAGE(PG8_SB(1, 0), b3, voffB);
;       PG8_BAR; PG8_WAIT_L(0); PG8_MMA(0, 1, At, B1); PG8_BAR;
;       PG8_LDA(At, 1, 1); PG8_STAGE(PG8_SA(1, 0), a3, voffA);
;       PG8_BAR; PG8_WAIT_L(0); PG8_MMA(1, 0, At, B0); PG8_BAR; PG8_SCHED;
	s_add_u32 s42, s46, 0xb0000
	s_addc_u32 s43, s47, 0
	s_add_i32 s57, s60, s15
	v_lshl_add_u64 v[128:129], s[42:43], 0, v[220:221]
	s_mov_b32 m0, s57
	s_nop 0
	global_load_lds_dwordx4 v[128:129], off
	v_lshl_add_u64 v[128:129], s[42:43], 0, v[144:145]
	s_add_i32 m0, s57, 0x2000
	s_nop 0
	global_load_lds_dwordx4 v[128:129], off
	s_waitcnt vmcnt(6)
	s_barrier
	s_setprio 1
	v_mfma_f32_16x16x32_bf16 v[44:47], v[188:191], v[156:159], v[44:47]
	v_mfma_f32_16x16x32_bf16 v[40:43], v[214:217], v[156:159], v[40:43]
	v_mfma_f32_16x16x32_bf16 v[36:39], v[188:191], v[164:167], v[36:39]
	v_mfma_f32_16x16x32_bf16 v[32:35], v[214:217], v[164:167], v[32:35]
	v_mfma_f32_16x16x32_bf16 v[12:15], v[188:191], v[172:175], v[12:15]
	v_mfma_f32_16x16x32_bf16 v[8:11], v[214:217], v[172:175], v[8:11]
	v_mfma_f32_16x16x32_bf16 v[4:7], v[188:191], v[180:183], v[4:7]
	v_mfma_f32_16x16x32_bf16 v[0:3], v[214:217], v[180:183], v[0:3]
	v_mfma_f32_16x16x32_bf16 v[44:47], v[210:213], v[160:163], v[44:47]
	v_mfma_f32_16x16x32_bf16 v[40:43], v[234:237], v[160:163], v[40:43]
	v_mfma_f32_16x16x32_bf16 v[36:39], v[210:213], v[168:171], v[36:39]
	v_mfma_f32_16x16x32_bf16 v[32:35], v[234:237], v[168:171], v[32:35]
	v_mfma_f32_16x16x32_bf16 v[12:15], v[210:213], v[176:179], v[12:15]
	v_mfma_f32_16x16x32_bf16 v[8:11], v[234:237], v[176:179], v[8:11]
	v_mfma_f32_16x16x32_bf16 v[4:7], v[210:213], v[184:187], v[4:7]
	v_mfma_f32_16x16x32_bf16 v[0:3], v[234:237], v[184:187], v[0:3]
	s_setprio 0
	s_add_i32 s57, 0, 0x18000
	v_add_u32_e32 v140, s57, v153
	s_barrier
	ds_read_b128 v[128:131], v140
	ds_read_b128 v[132:135], v140 offset:1024
	ds_read_b128 v[136:139], v140 offset:2048
	ds_read_b128 v[140:143], v140 offset:3072
	s_add_u32 s42, s50, 0xb0000
	s_addc_u32 s43, s51, 0
	s_mov_b32 m0, s33
	v_lshl_add_u64 v[188:189], s[42:43], 0, v[220:221]
	ds_read_b128 v[156:159], v155 offset:32768
	ds_read_b128 v[160:163], v155 offset:33792
	ds_read_b128 v[164:167], v155 offset:34816
	ds_read_b128 v[168:171], v155 offset:35840
	ds_read_b128 v[172:175], v155 offset:36864
	ds_read_b128 v[176:179], v155 offset:37888
	ds_read_b128 v[180:183], v155 offset:38912
	ds_read_b128 v[184:187], v155 offset:39936
	global_load_lds_dwordx4 v[188:189], off
	v_lshl_add_u64 v[188:189], s[42:43], 0, v[144:145]
	s_mov_b32 m0, s34
	s_nop 0
	global_load_lds_dwordx4 v[188:189], off
	s_waitcnt lgkmcnt(8)
	s_barrier
	s_waitcnt lgkmcnt(0)
	s_setprio 1
	v_mfma_f32_16x16x32_bf16 v[124:127], v[128:131], v[156:159], v[124:127]
	v_mfma_f32_16x16x32_bf16 v[120:123], v[136:139], v[156:159], v[120:123]
	v_mfma_f32_16x16x32_bf16 v[116:119], v[128:131], v[164:167], v[116:119]
	v_mfma_f32_16x16x32_bf16 v[108:111], v[136:139], v[164:167], v[108:111]
	v_mfma_f32_16x16x32_bf16 v[92:95], v[128:131], v[172:175], v[92:95]
	v_mfma_f32_16x16x32_bf16 v[88:91], v[136:139], v[172:175], v[88:91]
	v_mfma_f32_16x16x32_bf16 v[84:87], v[128:131], v[180:183], v[84:87]
	v_mfma_f32_16x16x32_bf16 v[80:83], v[136:139], v[180:183], v[80:83]
	v_mfma_f32_16x16x32_bf16 v[124:127], v[132:135], v[160:163], v[124:127]
	v_mfma_f32_16x16x32_bf16 v[120:123], v[140:143], v[160:163], v[120:123]
	v_mfma_f32_16x16x32_bf16 v[116:119], v[132:135], v[168:171], v[116:119]
	v_mfma_f32_16x16x32_bf16 v[108:111], v[140:143], v[168:171], v[108:111]
	v_mfma_f32_16x16x32_bf16 v[92:95], v[132:135], v[176:179], v[92:95]
	v_mfma_f32_16x16x32_bf16 v[88:91], v[140:143], v[176:179], v[88:91]
	v_mfma_f32_16x16x32_bf16 v[84:87], v[132:135], v[184:187], v[84:87]
	v_mfma_f32_16x16x32_bf16 v[80:83], v[140:143], v[184:187], v[80:83]
	s_setprio 0
	s_barrier
	s_add_i32 s50, 0, 0x1c000
	s_add_i32 s42, s57, s15
	v_add_u32_e32 v204, s50, v153
	v_lshl_add_u64 v[150:151], v[150:151], 0, s[58:59]
	s_mov_b32 m0, s42
	ds_read_b128 v[188:191], v204
	ds_read_b128 v[210:213], v204 offset:1024
	ds_read_b128 v[214:217], v204 offset:2048
	ds_read_b128 v[234:237], v204 offset:3072
	global_load_lds_dwordx4 v[150:151], off
	v_lshl_add_u64 v[150:151], v[194:195], 0, s[58:59]
	s_add_i32 m0, s42, 0x2000
	s_nop 0
	global_load_lds_dwordx4 v[150:151], off
	s_barrier
	s_waitcnt lgkmcnt(0)
	s_setprio 1
	v_mfma_f32_16x16x32_bf16 v[112:115], v[188:191], v[156:159], v[112:115]
	v_mfma_f32_16x16x32_bf16 v[104:107], v[214:217], v[156:159], v[104:107]
	v_mfma_f32_16x16x32_bf16 v[100:103], v[188:191], v[164:167], v[100:103]
	v_mfma_f32_16x16x32_bf16 v[96:99], v[214:217], v[164:167], v[96:99]
	v_mfma_f32_16x16x32_bf16 v[76:79], v[188:191], v[172:175], v[76:79]
	v_mfma_f32_16x16x32_bf16 v[72:75], v[214:217], v[172:175], v[72:75]
	v_mfma_f32_16x16x32_bf16 v[68:71], v[188:191], v[180:183], v[68:71]
	v_mfma_f32_16x16x32_bf16 v[64:67], v[214:217], v[180:183], v[64:67]
	v_mfma_f32_16x16x32_bf16 v[112:115], v[210:213], v[160:163], v[112:115]
	v_mfma_f32_16x16x32_bf16 v[104:107], v[234:237], v[160:163], v[104:107]
	v_mfma_f32_16x16x32_bf16 v[100:103], v[210:213], v[168:171], v[100:103]
	v_mfma_f32_16x16x32_bf16 v[96:99], v[234:237], v[168:171], v[96:99]
	v_mfma_f32_16x16x32_bf16 v[76:79], v[210:213], v[176:179], v[76:79]
	v_mfma_f32_16x16x32_bf16 v[72:75], v[234:237], v[176:179], v[72:75]
	v_mfma_f32_16x16x32_bf16 v[68:71], v[210:213], v[184:187], v[68:71]
	v_mfma_f32_16x16x32_bf16 v[64:67], v[234:237], v[184:187], v[64:67]
	s_setprio 0
	s_mov_b32 m0, s38
	v_lshl_add_u64 v[150:151], v[200:201], 0, s[58:59]
	s_barrier
	ds_read_b128 v[156:159], v155 offset:49152
	ds_read_b128 v[160:163], v155 offset:50176
	ds_read_b128 v[164:167], v155 offset:51200
	ds_read_b128 v[168:171], v155 offset:52224
	ds_read_b128 v[172:175], v155 offset:53248
	ds_read_b128 v[176:179], v155 offset:54272
	ds_read_b128 v[180:183], v155 offset:55296
	ds_read_b128 v[184:187], v155 offset:56320
	global_load_lds_dwordx4 v[150:151], off
	v_lshl_add_u64 v[150:151], v[202:203], 0, s[58:59]
	s_mov_b32 m0, s20
	s_nop 0
	global_load_lds_dwordx4 v[150:151], off
	s_barrier
; #define MEMBAR() asm volatile("" ::: "memory")
; DI float* modp(const Params& p, int layer, int g, int chunk) { return (float*)(p.ws + OFF_MOD) + ((size_t)(layer * 9 + g) * 6 + chunk) * 1024; }
; #define PG8_STAGE(bufoff, gbase, voff) do { _Pragma("unroll") for (int _i = 0; _i < 2; ++_i) \
;     __builtin_amdgcn_global_load_lds((const unsigned*)((const char*)(gbase) + (voff)[_i]), (LAS unsigned*)(lds + (bufoff) + ldsw + _i * 8192), 16, 0, 0); } while (0)
; #define PG8_MMA(ai, bj, At, Bt_) do { __builtin_amdgcn_s_setprio(1); _Pragma("unroll") for (int m = 0; m < 4; ++m) _Pragma("unroll") for (int n = 0; n < 2; ++n) _Pragma("unroll") for (int k = 0; k < 2; ++k) \
;     acc[ai][bj][m][n] = __builtin_amdgcn_mfma_f32_16x16x32_bf16(Bt_[n][k], At[m][k], acc[ai][bj][m][n], 0, 0, 0); __builtin_amdgcn_s_setprio(0); } while (0)
; #define PG8_WAIT_V(n) asm volatile("s_waitcnt vmcnt(" #n ")" ::: "memory")
; #define PG8_WAIT_L(n) asm volatile("s_waitcnt lgkmcnt(" #n ")" ::: "memory")
; #define PG8_BAR __builtin_amdgcn_s_barrier()
; template <class Epi>
; DI void gemm_phase(char* smem, const bf16_t* A, int lda, const bf16_t* Bt, int ldb, int K, const Order& S_, const Epi& E) {
;     ...
;       PG8_BAR; PG8_WAIT_L(0); PG8_MMA(1, 0, At, B0); PG8_BAR; PG8_SCHED;
;       PG8_STAGE(PG8_SB(1, 1), b3 + hstepB, voffB);
;       PG8_WAIT_V(6); PG8_BAR; PG8_MMA(1, 1, At, B1); PG8_BAR;
;   DI void operator()(const acc_t& acc, const Unit& u, int wr, int wc, int fr, int fq) const {
;     const int row0 = u.pm * BM + wr * 64 + fr, col0 = u.pn * BM + wc * 32 + 4 * fq;
;     const int b = u.pm / 17, g = (u.pm - b * 17) == 0 ? 8 : b;
;     const float* gate = modp(p, layer, g, chunk);
;     f32x4 gv[2][2];
; #pragma unroll
;     for (int bj = 0; bj < 2; ++bj)
; #pragma unroll
;       for (int n = 0; n < 2; ++n) gv[bj][n] = *(const f32x4*)(gate + col0 + bj * HALF + n * 16);
; #pragma unroll
;     for (int q = 0; q < 4; ++q) {
;       const int ai = q >> 1, mh = q & 1;
;       MEMBAR();
;       f32x4 xv[2][2][2];
; #pragma unroll
;       for (int mm = 0; mm < 2; ++mm) { const int t = row0 + ai * HALF + (2 * mh + mm) * 16;
;         const float* xi = from_input ? xrow_in(p, t) : xrow_ws(p, t);
; #pragma unroll
;         for (int bj = 0; bj < 2; ++bj)
; #pragma unroll
;           for (int n = 0; n < 2; ++n) xv[mm][bj][n] = *(const f32x4*)(xi + col0 + bj * HALF + n * 16); }
	s_waitcnt lgkmcnt(0)
	s_setprio 1
	v_mfma_f32_16x16x32_bf16 v[60:63], v[128:131], v[156:159], v[60:63]
	v_mfma_f32_16x16x32_bf16 v[56:59], v[136:139], v[156:159], v[56:59]
	v_mfma_f32_16x16x32_bf16 v[52:55], v[128:131], v[164:167], v[52:55]
	v_mfma_f32_16x16x32_bf16 v[48:51], v[136:139], v[164:167], v[48:51]
	v_mfma_f32_16x16x32_bf16 v[28:31], v[128:131], v[172:175], v[28:31]
	v_mfma_f32_16x16x32_bf16 v[24:27], v[136:139], v[172:175], v[24:27]
	v_mfma_f32_16x16x32_bf16 v[20:23], v[128:131], v[180:183], v[20:23]
	v_mfma_f32_16x16x32_bf16 v[16:19], v[136:139], v[180:183], v[16:19]
	v_mfma_f32_16x16x32_bf16 v[60:63], v[132:135], v[160:163], v[60:63]
	v_mfma_f32_16x16x32_bf16 v[56:59], v[140:143], v[160:163], v[56:59]
	v_mfma_f32_16x16x32_bf16 v[52:55], v[132:135], v[168:171], v[52:55]
	v_mfma_f32_16x16x32_bf16 v[48:51], v[140:143], v[168:171], v[48:51]
	v_mfma_f32_16x16x32_bf16 v[28:31], v[132:135], v[176:179], v[28:31]
	v_mfma_f32_16x16x32_bf16 v[24:27], v[140:143], v[176:179], v[24:27]
	v_mfma_f32_16x16x32_bf16 v[20:23], v[132:135], v[184:187], v[20:23]
	v_mfma_f32_16x16x32_bf16 v[16:19], v[140:143], v[184:187], v[16:19]
	s_setprio 0
	s_barrier
	s_add_u32 s42, s46, 0xb0080
	s_addc_u32 s43, s47, 0
	s_add_i32 s46, s50, s15
	v_lshl_add_u64 v[128:129], s[42:43], 0, v[220:221]
	s_mov_b32 m0, s46
	s_nop 0
	global_load_lds_dwordx4 v[128:129], off
	v_lshl_add_u64 v[128:129], s[42:43], 0, v[144:145]
	s_add_i32 m0, s46, 0x2000
	s_nop 0
	global_load_lds_dwordx4 v[128:129], off
	s_waitcnt vmcnt(6)
	s_barrier
	s_setprio 1
	v_mfma_f32_16x16x32_bf16 v[44:47], v[188:191], v[156:159], v[44:47]
	v_mfma_f32_16x16x32_bf16 v[40:43], v[214:217], v[156:159], v[40:43]
	v_mfma_f32_16x16x32_bf16 v[36:39], v[188:191], v[164:167], v[36:39]
	v_mfma_f32_16x16x32_bf16 v[32:35], v[214:217], v[164:167], v[32:35]
	v_mfma_f32_16x16x32_bf16 v[12:15], v[188:191], v[172:175], v[12:15]
	v_mfma_f32_16x16x32_bf16 v[8:11], v[214:217], v[172:175], v[8:11]
	v_mfma_f32_16x16x32_bf16 v[4:7], v[188:191], v[180:183], v[4:7]
	v_mfma_f32_16x16x32_bf16 v[0:3], v[214:217], v[180:183], v[0:3]
	v_mfma_f32_16x16x32_bf16 v[44:47], v[210:213], v[160:163], v[44:47]
	v_mfma_f32_16x16x32_bf16 v[40:43], v[234:237], v[160:163], v[40:43]
	v_mfma_f32_16x16x32_bf16 v[36:39], v[210:213], v[168:171], v[36:39]
	v_mfma_f32_16x16x32_bf16 v[32:35], v[234:237], v[168:171], v[32:35]
	v_mfma_f32_16x16x32_bf16 v[12:15], v[210:213], v[176:179], v[12:15]
	v_mfma_f32_16x16x32_bf16 v[8:11], v[234:237], v[176:179], v[8:11]
	v_mfma_f32_16x16x32_bf16 v[4:7], v[210:213], v[184:187], v[4:7]
	v_mfma_f32_16x16x32_bf16 v[0:3], v[234:237], v[184:187], v[0:3]
	s_setprio 0
	s_add_i32 s56, s56, 2
	s_add_u32 s52, s52, 0x100
	s_addc_u32 s53, s53, 0
	s_cmp_gt_u32 s56, 41
	s_mov_b64 s[42:43], s[44:45]
	s_barrier
	s_cbranch_scc0 .LBB0_1929
	v_lshl_add_u32 v157, s39, 8, v152
	s_mov_b32 s51, 0x78787879
	v_mul_hi_i32 v156, v157, s51
	v_lshrrev_b32_e32 v158, 31, v156
	v_ashrrev_i32_e32 v156, 11, v156
	v_add_u32_e32 v162, v156, v158
	s_mul_hi_i32 s42, s39, 0x78787879
	v_mad_i32_i24 v161, v162, s80, v157
	s_movk_i32 s50, 0x100
	s_lshr_b32 s43, s42, 31
	s_ashr_i32 s42, s42, 3
	v_ashrrev_i32_e32 v166, 31, v161
	v_add_u32_e32 v168, 0xffffff00, v161
	v_cmp_gt_i32_e32 vcc, s50, v161
	s_add_i32 s42, s42, s43
	v_ashrrev_i32_e32 v163, 31, v162
	v_cndmask_b32_e32 v167, 0, v166, vcc
	v_cndmask_b32_e32 v166, v168, v161, vcc
	v_cndmask_b32_e64 v161, 24, 20, vcc
	s_mul_i32 s43, s42, 0xffffffef
	s_sub_i32 s44, 0, s39
	v_lshlrev_b64 v[162:163], v161, v[162:163]
	v_or_b32_e32 v161, 16, v157
	s_cmp_lg_u32 s43, s44
	v_mul_hi_i32 v178, v161, s51
	s_cselect_b32 s42, s42, 8
	v_readlane_b32 s43, v254, 59
	v_lshrrev_b32_e32 v179, 31, v178
	v_ashrrev_i32_e32 v178, 11, v178
	s_add_i32 s42, s42, s43
	v_readlane_b32 s39, v254, 42
	v_add_u32_e32 v178, v178, v179
	s_mul_i32 s42, s42, 6
	v_mov_b32_e32 v156, s93
	v_mov_b32_e32 v158, s83
	v_mov_b32_e32 v159, s92
	v_mov_b32_e32 v160, s39
	v_mad_i32_i24 v161, v178, s80, v161
	s_ashr_i32 s43, s42, 31
	v_cndmask_b32_e32 v165, v156, v158, vcc
	v_cndmask_b32_e32 v164, v159, v160, vcc
	v_cmp_gt_i32_e32 vcc, s50, v161
	v_lshl_or_b32 v128, s49, 8, v154
	s_lshl_b64 s[42:43], s[42:43], 12
	v_readlane_b32 s44, v253, 29
	v_ashrrev_i32_e32 v179, 31, v178
	v_cndmask_b32_e64 v180, 24, 20, vcc
	v_ashrrev_i32_e32 v182, 31, v161
	v_add_u32_e32 v184, 0xffffff00, v161
	s_add_u32 s42, s44, s42
	v_readlane_b32 s44, v253, 30
	v_ashrrev_i32_e32 v129, 31, v128
	v_lshlrev_b64 v[178:179], v180, v[178:179]
	v_cndmask_b32_e32 v181, v156, v158, vcc
	v_cndmask_b32_e32 v180, v159, v160, vcc
	v_cndmask_b32_e32 v183, 0, v182, vcc
	v_cndmask_b32_e32 v182, v184, v161, vcc
	s_addc_u32 s43, s44, s43
	v_lshlrev_b64 v[150:151], 2, v[128:129]
	v_lshl_add_u64 v[162:163], v[164:165], 0, v[162:163]
	v_lshlrev_b64 v[164:165], 12, v[166:167]
	v_lshl_add_u64 v[178:179], v[180:181], 0, v[178:179]
	v_lshlrev_b64 v[180:181], 12, v[182:183]
	v_lshl_add_u64 v[128:129], s[42:43], 0, v[150:151]
	v_lshl_add_u64 v[162:163], v[162:163], 0, v[164:165]
	v_lshl_add_u64 v[178:179], v[178:179], 0, v[180:181]
	global_load_dwordx4 v[140:143], v[128:129], off
	global_load_dwordx4 v[136:139], v[128:129], off offset:64
	global_load_dwordx4 v[132:135], v[128:129], off offset:512
	s_nop 0
	global_load_dwordx4 v[128:131], v[128:129], off offset:576
	v_lshl_add_u64 v[190:191], v[162:163], 0, v[150:151]
	v_lshl_add_u64 v[194:195], v[178:179], 0, v[150:151]
	global_load_dwordx4 v[162:165], v[190:191], off
	global_load_dwordx4 v[166:169], v[190:191], off offset:64
	global_load_dwordx4 v[170:173], v[190:191], off offset:512
	global_load_dwordx4 v[174:177], v[190:191], off offset:576
	global_load_dwordx4 v[178:181], v[194:195], off
	global_load_dwordx4 v[182:185], v[194:195], off offset:64
	global_load_dwordx4 v[186:189], v[194:195], off offset:512
	global_load_dwordx4 v[210:213], v[194:195], off offset:576
	v_add_u32_e32 v161, 0x80, v157
	v_readlane_b32 s46, v254, 46
	s_mov_b32 s49, s4
	s_mov_b32 s39, s5
	s_mov_b64 s[44:45], s[40:41]
	s_mov_b64 s[42:43], s[0:1]
	v_readlane_b32 s47, v254, 47
	s_waitcnt vmcnt(0)
; #define MEMBAR() asm volatile("" ::: "memory")
;   DI void operator()(const acc_t& acc, const Unit& u, int wr, int wc, int fr, int fq) const {
;     ...
;     for (int q = 0; q < 4; ++q) {
;       const int ai = q >> 1, mh = q & 1;
;       MEMBAR();
;       f32x4 xv[2][2][2];
; #pragma unroll
;       for (int mm = 0; mm < 2; ++mm) { const int t = row0 + ai * HALF + (2 * mh + mm) * 16;
;         const float* xi = from_input ? xrow_in(p, t) : xrow_ws(p, t);
; #pragma unroll
;         for (int bj = 0; bj < 2; ++bj)
; #pragma unroll
;           for (int n = 0; n < 2; ++n) xv[mm][bj][n] = *(const f32x4*)(xi + col0 + bj * HALF + n * 16); }
;       MEMBAR();
; #pragma unroll
;       for (int mm = 0; mm < 2; ++mm) { const int t = row0 + ai * HALF + (2 * mh + mm) * 16;
;         float* xo = xrow_ws(p, t);
; #pragma unroll
;         for (int bj = 0; bj < 2; ++bj)
; #pragma unroll
;           for (int n = 0; n < 2; ++n) *(f32x4*)(xo + col0 + bj * HALF + n * 16) = xv[mm][bj][n] + gv[bj][n] * acc[ai][bj][2 * mh + mm][n]; }
	v_pk_fma_f32 v[126:127], v[126:127], v[142:143], v[164:165]
	v_pk_fma_f32 v[124:125], v[124:125], v[140:141], v[162:163]
	v_pk_fma_f32 v[122:123], v[122:123], v[138:139], v[168:169]
	v_pk_fma_f32 v[120:121], v[120:121], v[136:137], v[166:167]
	v_pk_fma_f32 v[98:99], v[98:99], v[130:131], v[212:213]
	v_pk_fma_f32 v[96:97], v[96:97], v[128:129], v[210:211]
	v_pk_fma_f32 v[114:115], v[114:115], v[134:135], v[172:173]
	v_pk_fma_f32 v[112:113], v[112:113], v[132:133], v[170:171]
	v_pk_fma_f32 v[106:107], v[106:107], v[130:131], v[176:177]
	v_pk_fma_f32 v[104:105], v[104:105], v[128:129], v[174:175]
	v_pk_fma_f32 v[118:119], v[118:119], v[142:143], v[180:181]
	v_pk_fma_f32 v[116:117], v[116:117], v[140:141], v[178:179]
	v_pk_fma_f32 v[110:111], v[110:111], v[138:139], v[184:185]
	v_pk_fma_f32 v[108:109], v[108:109], v[136:137], v[182:183]
	v_pk_fma_f32 v[102:103], v[102:103], v[134:135], v[188:189]
	v_pk_fma_f32 v[100:101], v[100:101], v[132:133], v[186:187]
	global_store_dwordx4 v[190:191], v[124:127], off
	global_store_dwordx4 v[190:191], v[120:123], off offset:64
	global_store_dwordx4 v[190:191], v[112:115], off offset:512
	global_store_dwordx4 v[190:191], v[104:107], off offset:576
	global_store_dwordx4 v[194:195], v[116:119], off
	global_store_dwordx4 v[194:195], v[108:111], off offset:64
	global_store_dwordx4 v[194:195], v[100:103], off offset:512
	global_store_dwordx4 v[194:195], v[96:99], off offset:576
	v_or_b32_e32 v113, 48, v157
	v_mul_hi_i32 v112, v113, s51
	v_or_b32_e32 v97, 32, v157
	v_mul_hi_i32 v96, v97, s51
	v_lshrrev_b32_e32 v98, 31, v96
	v_ashrrev_i32_e32 v96, 11, v96
	v_add_u32_e32 v96, v96, v98
	v_lshrrev_b32_e32 v114, 31, v112
	v_ashrrev_i32_e32 v112, 11, v112
	v_mad_i32_i24 v100, v96, s80, v97
	v_add_u32_e32 v112, v112, v114
	v_ashrrev_i32_e32 v101, 31, v100
	v_add_u32_e32 v102, 0xffffff00, v100
	v_cmp_gt_i32_e32 vcc, s50, v100
	v_mad_i32_i24 v116, v112, s80, v113
	v_ashrrev_i32_e32 v97, 31, v96
	v_cndmask_b32_e32 v99, v156, v158, vcc
	v_cndmask_b32_e32 v98, v159, v160, vcc
	v_cndmask_b32_e32 v101, 0, v101, vcc
	v_cndmask_b32_e32 v100, v102, v100, vcc
	v_cndmask_b32_e64 v102, 24, 20, vcc
	v_cmp_gt_i32_e32 vcc, s50, v116
	v_ashrrev_i32_e32 v113, 31, v112
	v_ashrrev_i32_e32 v117, 31, v116
	v_cndmask_b32_e64 v114, 24, 20, vcc
	v_add_u32_e32 v118, 0xffffff00, v116
	v_lshlrev_b64 v[96:97], v102, v[96:97]
	v_lshlrev_b64 v[112:113], v114, v[112:113]
	v_cndmask_b32_e32 v115, v156, v158, vcc
	v_cndmask_b32_e32 v114, v159, v160, vcc
	v_cndmask_b32_e32 v117, 0, v117, vcc
	v_cndmask_b32_e32 v116, v118, v116, vcc
	v_lshl_add_u64 v[96:97], v[98:99], 0, v[96:97]
	v_lshlrev_b64 v[98:99], 12, v[100:101]
	v_lshl_add_u64 v[112:113], v[114:115], 0, v[112:113]
	v_lshlrev_b64 v[114:115], 12, v[116:117]
	v_lshl_add_u64 v[96:97], v[96:97], 0, v[98:99]
	v_lshl_add_u64 v[112:113], v[112:113], 0, v[114:115]
	v_lshl_add_u64 v[162:163], v[96:97], 0, v[150:151]
	v_lshl_add_u64 v[164:165], v[112:113], 0, v[150:151]
	global_load_dwordx4 v[96:99], v[162:163], off
	global_load_dwordx4 v[100:103], v[162:163], off offset:64
	global_load_dwordx4 v[104:107], v[162:163], off offset:512
	global_load_dwordx4 v[108:111], v[162:163], off offset:576
	global_load_dwordx4 v[112:115], v[164:165], off
	global_load_dwordx4 v[116:119], v[164:165], off offset:64
	global_load_dwordx4 v[120:123], v[164:165], off offset:512
	global_load_dwordx4 v[124:127], v[164:165], off offset:576
	v_mul_hi_i32 v166, v161, s51
	v_lshrrev_b32_e32 v167, 31, v166
	v_ashrrev_i32_e32 v166, 11, v166
	v_add_u32_e32 v166, v166, v167
	v_ashrrev_i32_e32 v167, 31, v166
	s_waitcnt vmcnt(0)
	v_pk_fma_f32 v[94:95], v[94:95], v[142:143], v[98:99]
	v_pk_fma_f32 v[92:93], v[92:93], v[140:141], v[96:97]
	v_pk_fma_f32 v[80:81], v[80:81], v[136:137], v[116:117]
	v_pk_fma_f32 v[90:91], v[90:91], v[138:139], v[102:103]
	v_pk_fma_f32 v[88:89], v[88:89], v[136:137], v[100:101]
	v_pk_fma_f32 v[78:79], v[78:79], v[134:135], v[106:107]
	v_pk_fma_f32 v[76:77], v[76:77], v[132:133], v[104:105]
	v_pk_fma_f32 v[74:75], v[74:75], v[130:131], v[110:111]
	v_pk_fma_f32 v[72:73], v[72:73], v[128:129], v[108:109]
	v_pk_fma_f32 v[86:87], v[86:87], v[142:143], v[114:115]
	v_pk_fma_f32 v[84:85], v[84:85], v[140:141], v[112:113]
	v_pk_fma_f32 v[82:83], v[82:83], v[138:139], v[118:119]
	v_pk_fma_f32 v[70:71], v[70:71], v[134:135], v[122:123]
	v_pk_fma_f32 v[68:69], v[68:69], v[132:133], v[120:121]
	v_pk_fma_f32 v[66:67], v[66:67], v[130:131], v[126:127]
	v_pk_fma_f32 v[64:65], v[64:65], v[128:129], v[124:125]
	global_store_dwordx4 v[162:163], v[92:95], off
	global_store_dwordx4 v[162:163], v[88:91], off offset:64
	global_store_dwordx4 v[162:163], v[76:79], off offset:512
	global_store_dwordx4 v[162:163], v[72:75], off offset:576
	global_store_dwordx4 v[164:165], v[84:87], off
	global_store_dwordx4 v[164:165], v[80:83], off offset:64
	global_store_dwordx4 v[164:165], v[68:71], off offset:512
	global_store_dwordx4 v[164:165], v[64:67], off offset:576
	v_add_u32_e32 v81, 0x90, v157
	v_mul_hi_i32 v80, v81, s51
	v_lshrrev_b32_e32 v82, 31, v80
	v_ashrrev_i32_e32 v80, 11, v80
	v_mad_i32_i24 v66, v166, s80, v161
	v_add_u32_e32 v80, v80, v82
	v_ashrrev_i32_e32 v67, 31, v66
	v_add_u32_e32 v68, 0xffffff00, v66
	v_cmp_gt_i32_e32 vcc, s50, v66
	v_mad_i32_i24 v84, v80, s80, v81
	v_ashrrev_i32_e32 v81, 31, v80
	v_cndmask_b32_e32 v65, v156, v158, vcc
	v_cndmask_b32_e32 v64, v159, v160, vcc
	v_cndmask_b32_e32 v67, 0, v67, vcc
	v_cndmask_b32_e32 v66, v68, v66, vcc
	v_cndmask_b32_e64 v68, 24, 20, vcc
	v_cmp_gt_i32_e32 vcc, s50, v84
	v_ashrrev_i32_e32 v85, 31, v84
	v_add_u32_e32 v86, 0xffffff00, v84
	v_cndmask_b32_e64 v82, 24, 20, vcc
	v_lshlrev_b64 v[68:69], v68, v[166:167]
	v_lshlrev_b64 v[80:81], v82, v[80:81]
	v_cndmask_b32_e32 v83, v156, v158, vcc
	v_cndmask_b32_e32 v82, v159, v160, vcc
	v_cndmask_b32_e32 v85, 0, v85, vcc
	v_cndmask_b32_e32 v84, v86, v84, vcc
	v_lshl_add_u64 v[64:65], v[64:65], 0, v[68:69]
	v_lshlrev_b64 v[66:67], 12, v[66:67]
	v_lshl_add_u64 v[80:81], v[82:83], 0, v[80:81]
	v_lshlrev_b64 v[82:83], 12, v[84:85]
	v_lshl_add_u64 v[64:65], v[64:65], 0, v[66:67]
	v_lshl_add_u64 v[80:81], v[80:81], 0, v[82:83]
	v_lshl_add_u64 v[96:97], v[64:65], 0, v[150:151]
	v_lshl_add_u64 v[98:99], v[80:81], 0, v[150:151]
	global_load_dwordx4 v[64:67], v[96:97], off
	global_load_dwordx4 v[68:71], v[96:97], off offset:64
	global_load_dwordx4 v[72:75], v[96:97], off offset:512
	global_load_dwordx4 v[76:79], v[96:97], off offset:576
	global_load_dwordx4 v[80:83], v[98:99], off
	global_load_dwordx4 v[84:87], v[98:99], off offset:64
	global_load_dwordx4 v[88:91], v[98:99], off offset:512
	global_load_dwordx4 v[92:95], v[98:99], off offset:576
	v_add_u32_e32 v101, 0xa0, v157
	v_mul_hi_i32 v100, v101, s51
	v_lshrrev_b32_e32 v102, 31, v100
	v_ashrrev_i32_e32 v100, 11, v100
	v_add_u32_e32 v100, v100, v102
	v_mad_i32_i24 v104, v100, s80, v101
	v_ashrrev_i32_e32 v105, 31, v104
	v_add_u32_e32 v106, 0xffffff00, v104
	v_cmp_gt_i32_e32 vcc, s50, v104
	v_ashrrev_i32_e32 v101, 31, v100
	s_waitcnt vmcnt(0)
; #define MEMBAR() asm volatile("" ::: "memory")
; #define PG8_WAIT_V(n) asm volatile("s_waitcnt vmcnt(" #n ")" ::: "memory")
; #define PG8_BAR __builtin_amdgcn_s_barrier()
; #define PG8_WAIT_V(n) asm volatile("s_waitcnt vmcnt(" #n ")" ::: "memory")
; #define PG8_BAR __builtin_amdgcn_s_barrier()
; template <class Epi>
; DI void gemm_phase(char* smem, const bf16_t* A, int lda, const bf16_t* Bt, int ldb, int K, const Order& S_, const Epi& E) {
;     ...
;     if (!has_next) break;
; #pragma unroll
;     for (int a = 0; a < 2; ++a)
; #pragma unroll
;       for (int b = 0; b < 2; ++b)
; #pragma unroll
;         for (int m = 0; m < 4; ++m)
; #pragma unroll
;           for (int n = 0; n < 2; ++n) acc[a][b][m][n] = (f32x4){0.f, 0.f, 0.f, 0.f};
;     cur = nxt; cA = nA; cB = nB; ++ui;
;   }
;   PG8_WAIT_V(0);
;   if (wr == 0) PG8_BAR;
;   PG8_BAR;
;   DI void operator()(const acc_t& acc, const Unit& u, int wr, int wc, int fr, int fq) const {
;     ...
;       for (int mm = 0; mm < 2; ++mm) { const int t = row0 + ai * HALF + (2 * mh + mm) * 16;
;         const float* xi = from_input ? xrow_in(p, t) : xrow_ws(p, t);
; #pragma unroll
;         for (int bj = 0; bj < 2; ++bj)
; #pragma unroll
;           for (int n = 0; n < 2; ++n) xv[mm][bj][n] = *(const f32x4*)(xi + col0 + bj * HALF + n * 16); }
;       MEMBAR();
; #pragma unroll
;       for (int mm = 0; mm < 2; ++mm) { const int t = row0 + ai * HALF + (2 * mh + mm) * 16;
;         float* xo = xrow_ws(p, t);
; #pragma unroll
;         for (int bj = 0; bj < 2; ++bj)
; #pragma unroll
;           for (int n = 0; n < 2; ++n) *(f32x4*)(xo + col0 + bj * HALF + n * 16) = xv[mm][bj][n] + gv[bj][n] * acc[ai][bj][2 * mh + mm][n]; }
	v_pk_fma_f32 v[62:63], v[62:63], v[142:143], v[66:67]
	v_pk_fma_f32 v[60:61], v[60:61], v[140:141], v[64:65]
	v_pk_fma_f32 v[48:49], v[48:49], v[136:137], v[84:85]
	v_pk_fma_f32 v[58:59], v[58:59], v[138:139], v[70:71]
	v_pk_fma_f32 v[56:57], v[56:57], v[136:137], v[68:69]
	v_pk_fma_f32 v[46:47], v[46:47], v[134:135], v[74:75]
	v_pk_fma_f32 v[44:45], v[44:45], v[132:133], v[72:73]
	v_pk_fma_f32 v[42:43], v[42:43], v[130:131], v[78:79]
	v_pk_fma_f32 v[40:41], v[40:41], v[128:129], v[76:77]
	v_pk_fma_f32 v[54:55], v[54:55], v[142:143], v[82:83]
	v_pk_fma_f32 v[52:53], v[52:53], v[140:141], v[80:81]
	v_pk_fma_f32 v[50:51], v[50:51], v[138:139], v[86:87]
	v_pk_fma_f32 v[38:39], v[38:39], v[134:135], v[90:91]
	v_pk_fma_f32 v[36:37], v[36:37], v[132:133], v[88:89]
	v_pk_fma_f32 v[34:35], v[34:35], v[130:131], v[94:95]
	v_pk_fma_f32 v[32:33], v[32:33], v[128:129], v[92:93]
	global_store_dwordx4 v[96:97], v[60:63], off
	global_store_dwordx4 v[96:97], v[56:59], off offset:64
	global_store_dwordx4 v[96:97], v[44:47], off offset:512
	global_store_dwordx4 v[96:97], v[40:43], off offset:576
	global_store_dwordx4 v[98:99], v[52:55], off
	global_store_dwordx4 v[98:99], v[48:51], off offset:64
	global_store_dwordx4 v[98:99], v[36:39], off offset:512
	global_store_dwordx4 v[98:99], v[32:35], off offset:576
	v_add_u32_e32 v49, 0xb0, v157
	v_mul_hi_i32 v48, v49, s51
	v_lshrrev_b32_e32 v50, 31, v48
	v_ashrrev_i32_e32 v48, 11, v48
	v_add_u32_e32 v48, v48, v50
	v_mad_i32_i24 v52, v48, s80, v49
	v_cndmask_b32_e32 v103, v156, v158, vcc
	v_cndmask_b32_e32 v102, v159, v160, vcc
	v_cndmask_b32_e32 v105, 0, v105, vcc
	v_cndmask_b32_e32 v104, v106, v104, vcc
	v_cndmask_b32_e64 v32, 24, 20, vcc
	v_cmp_gt_i32_e32 vcc, s50, v52
	v_ashrrev_i32_e32 v49, 31, v48
	v_ashrrev_i32_e32 v53, 31, v52
	v_cndmask_b32_e64 v50, 24, 20, vcc
	v_add_u32_e32 v54, 0xffffff00, v52
	v_lshlrev_b64 v[32:33], v32, v[100:101]
	v_lshlrev_b64 v[48:49], v50, v[48:49]
	v_cndmask_b32_e32 v51, v156, v158, vcc
	v_cndmask_b32_e32 v50, v159, v160, vcc
	v_cndmask_b32_e32 v53, 0, v53, vcc
	v_cndmask_b32_e32 v52, v54, v52, vcc
	v_lshl_add_u64 v[32:33], v[102:103], 0, v[32:33]
	v_lshlrev_b64 v[34:35], 12, v[104:105]
	v_lshl_add_u64 v[48:49], v[50:51], 0, v[48:49]
	v_lshlrev_b64 v[50:51], 12, v[52:53]
	v_lshl_add_u64 v[32:33], v[32:33], 0, v[34:35]
	v_lshl_add_u64 v[48:49], v[48:49], 0, v[50:51]
	v_lshl_add_u64 v[64:65], v[32:33], 0, v[150:151]
	v_lshl_add_u64 v[66:67], v[48:49], 0, v[150:151]
	global_load_dwordx4 v[32:35], v[64:65], off
	global_load_dwordx4 v[36:39], v[64:65], off offset:64
	global_load_dwordx4 v[40:43], v[64:65], off offset:512
	global_load_dwordx4 v[44:47], v[64:65], off offset:576
	global_load_dwordx4 v[48:51], v[66:67], off
	global_load_dwordx4 v[52:55], v[66:67], off offset:64
	global_load_dwordx4 v[56:59], v[66:67], off offset:512
	global_load_dwordx4 v[60:63], v[66:67], off offset:576
	s_and_b64 vcc, exec, s[36:37]
	s_waitcnt vmcnt(0)
	v_pk_fma_f32 v[30:31], v[30:31], v[142:143], v[34:35]
	v_pk_fma_f32 v[28:29], v[28:29], v[140:141], v[32:33]
	v_pk_fma_f32 v[26:27], v[26:27], v[138:139], v[38:39]
	v_pk_fma_f32 v[24:25], v[24:25], v[136:137], v[36:37]
	v_pk_fma_f32 v[14:15], v[14:15], v[134:135], v[42:43]
	v_pk_fma_f32 v[12:13], v[12:13], v[132:133], v[40:41]
	v_pk_fma_f32 v[10:11], v[10:11], v[130:131], v[46:47]
	v_pk_fma_f32 v[8:9], v[8:9], v[128:129], v[44:45]
	v_pk_fma_f32 v[22:23], v[22:23], v[142:143], v[50:51]
	v_pk_fma_f32 v[20:21], v[20:21], v[140:141], v[48:49]
	v_pk_fma_f32 v[18:19], v[18:19], v[138:139], v[54:55]
	v_pk_fma_f32 v[16:17], v[16:17], v[136:137], v[52:53]
	v_pk_fma_f32 v[6:7], v[6:7], v[134:135], v[58:59]
	v_pk_fma_f32 v[4:5], v[4:5], v[132:133], v[56:57]
	v_pk_fma_f32 v[2:3], v[2:3], v[130:131], v[62:63]
	v_pk_fma_f32 v[0:1], v[0:1], v[128:129], v[60:61]
	global_store_dwordx4 v[64:65], v[28:31], off
	global_store_dwordx4 v[64:65], v[24:27], off offset:64
	global_store_dwordx4 v[64:65], v[12:15], off offset:512
	global_store_dwordx4 v[64:65], v[8:11], off offset:576
	global_store_dwordx4 v[66:67], v[20:23], off
	global_store_dwordx4 v[66:67], v[16:19], off offset:64
	global_store_dwordx4 v[66:67], v[4:7], off offset:512
	global_store_dwordx4 v[66:67], v[0:3], off offset:576
	s_cbranch_vccz .LBB0_1921
	s_waitcnt vmcnt(0)
	s_cmpk_gt_u32 s3, 0xff
	s_cbranch_scc1 .LBB0_1933
	s_barrier
